# LN gamma/beta staged in LDS for the row loops; wo/down GEMM epilogue issues its 16 residual-row loads up front with counted vmcnt waits instead of a load-wait-store ladder
# speedup vs baseline: 1.1346x; 1.0171x over previous
; #define PG8_STAGE(bufoff, gbase, voff) do { _Pragma("unroll") for (int _i = 0; _i < 2; ++_i) \
;         __builtin_amdgcn_global_load_lds((const unsigned*)((const char*)(gbase) + (voff)[_i]), (LAS unsigned*)(lds + (bufoff) + ldsw + _i * 8192), 16, 0, 0); } while (0)
; #define PG8_LDA(dst, b, h) do { _Pragma("unroll") for (int m = 0; m < 4; ++m) _Pragma("unroll") for (int k = 0; k < 2; ++k) dst[m][k] = *(const LAS h16x8*)(lds + PG8_SA(b, h) + aoff + m * 2048 + k * 1024); } while (0)
; #define PG8_LDB(dst, b, h) do { _Pragma("unroll") for (int n = 0; n < 2; ++n) _Pragma("unroll") for (int k = 0; k < 2; ++k) dst[n][k] = *(const LAS h16x8*)(lds + PG8_SB(b, h) + boff + n * 2048 + k * 1024); } while (0)
; #define PG8_MMA(ai, bj, At, Bt_) do { __builtin_amdgcn_s_setprio(1); _Pragma("unroll") for (int m = 0; m < 4; ++m) _Pragma("unroll") for (int n = 0; n < 2; ++n) _Pragma("unroll") for (int k = 0; k < 2; ++k) \
;         acc[ai][bj][m][n] = __builtin_amdgcn_mfma_f32_16x16x32_f16(Bt_[n][k], At[m][k], acc[ai][bj][m][n], 0, 0, 0); __builtin_amdgcn_s_setprio(0); } while (0)
; #define PG8_WAIT_L(n) asm volatile("s_waitcnt lgkmcnt(" #n ")" ::: "memory")
; #define PG8_BAR __builtin_amdgcn_s_barrier()
; #define PG8_SCHED __builtin_amdgcn_sched_barrier(0)
; template <class Epi, class AMap>
; __device__ __forceinline__ void gemm_phase(LAS unsigned char* lds, const AMap am, const int lda, const h16* Bt, const int ldb, const int M, const int N, const int K, const Epi& E) {
;     ...
;             PG8_LDB(B0, 0, 0); PG8_SCHED; PG8_LDA(At, 0, 0); PG8_STAGE(PG8_SA(1, 1), a1 + hstepA, voffA);
;             PG8_WAIT_L(8); PG8_BAR; PG8_WAIT_L(0); PG8_MMA(0, 0, At, B0); PG8_BAR; PG8_SCHED;
;             PG8_LDB(B1, 0, 1); PG8_STAGE(PG8_SB(0, 0), b2, voffB);
;             PG8_BAR; PG8_WAIT_L(0); PG8_MMA(0, 1, At, B1); PG8_BAR;
;             PG8_LDA(At, 0, 1); PG8_STAGE(PG8_SA(0, 0), a2, voffA);
;             PG8_BAR; PG8_WAIT_L(0); PG8_MMA(1, 0, At, B0); PG8_BAR; PG8_SCHED;
.LBB0_61:
	s_add_u32 s26, s22, 0x100
	s_addc_u32 s27, s23, 0
	s_add_i32 s51, 0, 0x10000
	v_add_u32_e32 v144, s51, v147
	ds_read_b128 v[140:143], v144
	ds_read_b128 v[150:153], v144 offset:1024
	ds_read_b128 v[154:157], v144 offset:2048
	ds_read_b128 v[158:161], v144 offset:3072
	s_cmpk_eq_i32 s29, 0x52
	s_cselect_b32 s45, s1, s27
	s_cselect_b32 s44, s0, s26
	s_cselect_b32 s43, s41, s21
	s_cselect_b32 s42, s40, s20
	v_lshl_add_u64 v[144:145], s[22:23], 0, v[136:137]
	s_add_i32 m0, s63, 0xc000
	ds_read_b128 v[162:165], v149
	ds_read_b128 v[166:169], v149 offset:1024
	ds_read_b128 v[170:173], v149 offset:2048
	ds_read_b128 v[174:177], v149 offset:3072
	ds_read_b128 v[178:181], v149 offset:4096
	ds_read_b128 v[182:185], v149 offset:5120
	ds_read_b128 v[186:189], v149 offset:6144
	ds_read_b128 v[190:193], v149 offset:7168
	global_load_lds_dwordx4 v[144:145], off
	v_lshl_add_u64 v[144:145], s[22:23], 0, v[138:139]
	s_add_i32 m0, s63, 0xe000
	s_nop 0
	global_load_lds_dwordx4 v[144:145], off
	s_waitcnt lgkmcnt(8)
	s_barrier
	s_waitcnt lgkmcnt(0)
	s_setprio 1
	s_waitcnt lgkmcnt(0)
	v_mfma_f32_16x16x32_f16 v[126:129], v[140:143], v[162:165], v[126:129]
	v_mfma_f32_16x16x32_f16 v[122:125], v[154:157], v[162:165], v[122:125]
	v_mfma_f32_16x16x32_f16 v[110:113], v[140:143], v[170:173], v[110:113]
	v_mfma_f32_16x16x32_f16 v[106:109], v[154:157], v[170:173], v[106:109]
	v_mfma_f32_16x16x32_f16 v[94:97], v[140:143], v[178:181], v[94:97]
	v_mfma_f32_16x16x32_f16 v[90:93], v[154:157], v[178:181], v[90:93]
	v_mfma_f32_16x16x32_f16 v[78:81], v[140:143], v[186:189], v[78:81]
	v_mfma_f32_16x16x32_f16 v[74:77], v[154:157], v[186:189], v[74:77]
	v_mfma_f32_16x16x32_f16 v[126:129], v[150:153], v[166:169], v[126:129]
	v_mfma_f32_16x16x32_f16 v[122:125], v[158:161], v[166:169], v[122:125]
	v_mfma_f32_16x16x32_f16 v[110:113], v[150:153], v[174:177], v[110:113]
	v_mfma_f32_16x16x32_f16 v[106:109], v[158:161], v[174:177], v[106:109]
	v_mfma_f32_16x16x32_f16 v[94:97], v[150:153], v[182:185], v[94:97]
	v_mfma_f32_16x16x32_f16 v[90:93], v[158:161], v[182:185], v[90:93]
	v_mfma_f32_16x16x32_f16 v[78:81], v[150:153], v[190:193], v[78:81]
	v_mfma_f32_16x16x32_f16 v[74:77], v[158:161], v[190:193], v[74:77]
	s_setprio 0
	s_barrier
	s_add_i32 s60, 0, 0x14000
	v_add_u32_e32 v144, s60, v147
	s_add_i32 s22, s51, s48
	ds_read_b128 v[194:197], v144
	ds_read_b128 v[198:201], v144 offset:1024
	ds_read_b128 v[202:205], v144 offset:2048
	ds_read_b128 v[220:223], v144 offset:3072
	v_lshl_add_u64 v[144:145], s[42:43], 0, v[0:1]
	s_mov_b32 m0, s22
	v_lshl_add_u64 v[206:207], s[42:43], 0, v[134:135]
	global_load_lds_dwordx4 v[144:145], off
	s_add_i32 m0, s22, 0x2000
	s_nop 0
	global_load_lds_dwordx4 v[206:207], off
	s_barrier
	s_waitcnt lgkmcnt(0)
	s_setprio 1
	s_waitcnt lgkmcnt(0)
	v_mfma_f32_16x16x32_f16 v[118:121], v[194:197], v[162:165], v[118:121]
	v_mfma_f32_16x16x32_f16 v[114:117], v[202:205], v[162:165], v[114:117]
	v_mfma_f32_16x16x32_f16 v[102:105], v[194:197], v[170:173], v[102:105]
	v_mfma_f32_16x16x32_f16 v[98:101], v[202:205], v[170:173], v[98:101]
	v_mfma_f32_16x16x32_f16 v[86:89], v[194:197], v[178:181], v[86:89]
	v_mfma_f32_16x16x32_f16 v[82:85], v[202:205], v[178:181], v[82:85]
	v_mfma_f32_16x16x32_f16 v[70:73], v[194:197], v[186:189], v[70:73]
	v_mfma_f32_16x16x32_f16 v[66:69], v[202:205], v[186:189], v[66:69]
	v_mfma_f32_16x16x32_f16 v[118:121], v[198:201], v[166:169], v[118:121]
	v_mfma_f32_16x16x32_f16 v[114:117], v[220:223], v[166:169], v[114:117]
	v_mfma_f32_16x16x32_f16 v[102:105], v[198:201], v[174:177], v[102:105]
	v_mfma_f32_16x16x32_f16 v[98:101], v[220:223], v[174:177], v[98:101]
	v_mfma_f32_16x16x32_f16 v[86:89], v[198:201], v[182:185], v[86:89]
	v_mfma_f32_16x16x32_f16 v[82:85], v[220:223], v[182:185], v[82:85]
	v_mfma_f32_16x16x32_f16 v[70:73], v[198:201], v[190:193], v[70:73]
	v_mfma_f32_16x16x32_f16 v[66:69], v[220:223], v[190:193], v[66:69]
	s_setprio 0
	s_mov_b32 m0, s63
	v_lshl_add_u64 v[212:213], s[44:45], 0, v[130:131]
	s_barrier
	ds_read_b128 v[162:165], v149 offset:16384
	ds_read_b128 v[166:169], v149 offset:17408
	ds_read_b128 v[170:173], v149 offset:18432
	ds_read_b128 v[174:177], v149 offset:19456
	ds_read_b128 v[178:181], v149 offset:20480
	ds_read_b128 v[182:185], v149 offset:21504
	ds_read_b128 v[186:189], v149 offset:22528
	ds_read_b128 v[190:193], v149 offset:23552
	global_load_lds_dwordx4 v[212:213], off
	v_lshl_add_u64 v[214:215], s[44:45], 0, v[132:133]
	s_mov_b32 m0, s64
	s_nop 0
	global_load_lds_dwordx4 v[214:215], off
	s_barrier
	s_waitcnt lgkmcnt(0)
	s_setprio 1
	s_waitcnt lgkmcnt(0)
	v_mfma_f32_16x16x32_f16 v[62:65], v[140:143], v[162:165], v[62:65]
	v_mfma_f32_16x16x32_f16 v[58:61], v[154:157], v[162:165], v[58:61]
	v_mfma_f32_16x16x32_f16 v[46:49], v[140:143], v[170:173], v[46:49]
	v_mfma_f32_16x16x32_f16 v[42:45], v[154:157], v[170:173], v[42:45]
	v_mfma_f32_16x16x32_f16 v[30:33], v[140:143], v[178:181], v[30:33]
	v_mfma_f32_16x16x32_f16 v[26:29], v[154:157], v[178:181], v[26:29]
	v_mfma_f32_16x16x32_f16 v[14:17], v[140:143], v[186:189], v[14:17]
	v_mfma_f32_16x16x32_f16 v[10:13], v[154:157], v[186:189], v[10:13]
	v_mfma_f32_16x16x32_f16 v[62:65], v[150:153], v[166:169], v[62:65]
	v_mfma_f32_16x16x32_f16 v[58:61], v[158:161], v[166:169], v[58:61]
	v_mfma_f32_16x16x32_f16 v[46:49], v[150:153], v[174:177], v[46:49]
	v_mfma_f32_16x16x32_f16 v[42:45], v[158:161], v[174:177], v[42:45]
	v_mfma_f32_16x16x32_f16 v[30:33], v[150:153], v[182:185], v[30:33]
	v_mfma_f32_16x16x32_f16 v[26:29], v[158:161], v[182:185], v[26:29]
	v_mfma_f32_16x16x32_f16 v[14:17], v[150:153], v[190:193], v[14:17]
	v_mfma_f32_16x16x32_f16 v[10:13], v[158:161], v[190:193], v[10:13]
	s_setprio 0
	s_barrier
; #define PG8_STAGE(bufoff, gbase, voff) do { _Pragma("unroll") for (int _i = 0; _i < 2; ++_i) \
;         __builtin_amdgcn_global_load_lds((const unsigned*)((const char*)(gbase) + (voff)[_i]), (LAS unsigned*)(lds + (bufoff) + ldsw + _i * 8192), 16, 0, 0); } while (0)
; #define PG8_LDA(dst, b, h) do { _Pragma("unroll") for (int m = 0; m < 4; ++m) _Pragma("unroll") for (int k = 0; k < 2; ++k) dst[m][k] = *(const LAS h16x8*)(lds + PG8_SA(b, h) + aoff + m * 2048 + k * 1024); } while (0)
; #define PG8_LDB(dst, b, h) do { _Pragma("unroll") for (int n = 0; n < 2; ++n) _Pragma("unroll") for (int k = 0; k < 2; ++k) dst[n][k] = *(const LAS h16x8*)(lds + PG8_SB(b, h) + boff + n * 2048 + k * 1024); } while (0)
; #define PG8_MMA(ai, bj, At, Bt_) do { __builtin_amdgcn_s_setprio(1); _Pragma("unroll") for (int m = 0; m < 4; ++m) _Pragma("unroll") for (int n = 0; n < 2; ++n) _Pragma("unroll") for (int k = 0; k < 2; ++k) \
;         acc[ai][bj][m][n] = __builtin_amdgcn_mfma_f32_16x16x32_f16(Bt_[n][k], At[m][k], acc[ai][bj][m][n], 0, 0, 0); __builtin_amdgcn_s_setprio(0); } while (0)
; #define PG8_WAIT_V(n) asm volatile("s_waitcnt vmcnt(" #n ")" ::: "memory")
; #define PG8_WAIT_L(n) asm volatile("s_waitcnt lgkmcnt(" #n ")" ::: "memory")
; #define PG8_BAR __builtin_amdgcn_s_barrier()
; #define PG8_SCHED __builtin_amdgcn_sched_barrier(0)
; template <class Epi, class AMap>
; __device__ __forceinline__ void gemm_phase(LAS unsigned char* lds, const AMap am, const int lda, const h16* Bt, const int ldb, const int M, const int N, const int K, const Epi& E) {
;     ...
;             PG8_STAGE(PG8_SB(0, 1), b2 + hstepB, voffB);
;             PG8_WAIT_V(6); PG8_BAR; PG8_MMA(1, 1, At, B1); PG8_BAR;
;             PG8_LDB(B0, 1, 0); PG8_SCHED; PG8_LDA(At, 1, 0); PG8_STAGE(PG8_SA(0, 1), a2 + hstepA, voffA);
;             PG8_WAIT_L(8); PG8_BAR; PG8_WAIT_L(0); PG8_MMA(0, 0, At, B0); PG8_BAR; PG8_SCHED;
;             PG8_LDB(B1, 1, 1); PG8_STAGE(PG8_SB(1, 0), b3, voffB);
;             PG8_BAR; PG8_WAIT_L(0); PG8_MMA(0, 1, At, B1); PG8_BAR;
;             PG8_LDA(At, 1, 1); PG8_STAGE(PG8_SA(1, 0), a3, voffA);
;             PG8_BAR; PG8_WAIT_L(0); PG8_MMA(1, 0, At, B0); PG8_BAR; PG8_SCHED;
	s_add_u32 s22, s42, 0x158000
	s_addc_u32 s23, s43, 0
	s_add_i32 s51, s60, s48
	v_lshl_add_u64 v[140:141], s[22:23], 0, v[0:1]
	s_mov_b32 m0, s51
	s_nop 0
	global_load_lds_dwordx4 v[140:141], off
	v_lshl_add_u64 v[140:141], s[22:23], 0, v[134:135]
	s_add_i32 m0, s51, 0x2000
	s_nop 0
	global_load_lds_dwordx4 v[140:141], off
	s_waitcnt vmcnt(6)
	s_barrier
	s_setprio 1
	v_mfma_f32_16x16x32_f16 v[54:57], v[194:197], v[162:165], v[54:57]
	v_mfma_f32_16x16x32_f16 v[50:53], v[202:205], v[162:165], v[50:53]
	v_mfma_f32_16x16x32_f16 v[38:41], v[194:197], v[170:173], v[38:41]
	v_mfma_f32_16x16x32_f16 v[34:37], v[202:205], v[170:173], v[34:37]
	v_mfma_f32_16x16x32_f16 v[22:25], v[194:197], v[178:181], v[22:25]
	v_mfma_f32_16x16x32_f16 v[18:21], v[202:205], v[178:181], v[18:21]
	v_mfma_f32_16x16x32_f16 v[6:9], v[194:197], v[186:189], v[6:9]
	v_mfma_f32_16x16x32_f16 v[2:5], v[202:205], v[186:189], v[2:5]
	v_mfma_f32_16x16x32_f16 v[54:57], v[198:201], v[166:169], v[54:57]
	v_mfma_f32_16x16x32_f16 v[50:53], v[220:223], v[166:169], v[50:53]
	v_mfma_f32_16x16x32_f16 v[38:41], v[198:201], v[174:177], v[38:41]
	v_mfma_f32_16x16x32_f16 v[34:37], v[220:223], v[174:177], v[34:37]
	v_mfma_f32_16x16x32_f16 v[22:25], v[198:201], v[182:185], v[22:25]
	v_mfma_f32_16x16x32_f16 v[18:21], v[220:223], v[182:185], v[18:21]
	v_mfma_f32_16x16x32_f16 v[6:9], v[198:201], v[190:193], v[6:9]
	v_mfma_f32_16x16x32_f16 v[2:5], v[220:223], v[190:193], v[2:5]
	s_setprio 0
	s_add_i32 s51, 0, 0x18000
	v_add_u32_e32 v158, s51, v147
	s_barrier
	ds_read_b128 v[140:143], v158
	ds_read_b128 v[150:153], v158 offset:1024
	ds_read_b128 v[154:157], v158 offset:2048
	ds_read_b128 v[158:161], v158 offset:3072
	s_add_u32 s22, s44, 0x158000
	s_addc_u32 s23, s45, 0
	s_mov_b32 m0, s65
	v_lshl_add_u64 v[194:195], s[22:23], 0, v[130:131]
	ds_read_b128 v[162:165], v149 offset:32768
	ds_read_b128 v[166:169], v149 offset:33792
	ds_read_b128 v[170:173], v149 offset:34816
	ds_read_b128 v[174:177], v149 offset:35840
	ds_read_b128 v[178:181], v149 offset:36864
	ds_read_b128 v[182:185], v149 offset:37888
	ds_read_b128 v[186:189], v149 offset:38912
	ds_read_b128 v[190:193], v149 offset:39936
	global_load_lds_dwordx4 v[194:195], off
	v_lshl_add_u64 v[194:195], s[22:23], 0, v[132:133]
	s_mov_b32 m0, s68
	s_nop 0
	global_load_lds_dwordx4 v[194:195], off
	s_waitcnt lgkmcnt(8)
	s_barrier
	s_waitcnt lgkmcnt(0)
	s_setprio 1
	s_waitcnt lgkmcnt(0)
	v_mfma_f32_16x16x32_f16 v[126:129], v[140:143], v[162:165], v[126:129]
	v_mfma_f32_16x16x32_f16 v[122:125], v[154:157], v[162:165], v[122:125]
	v_mfma_f32_16x16x32_f16 v[110:113], v[140:143], v[170:173], v[110:113]
	v_mfma_f32_16x16x32_f16 v[106:109], v[154:157], v[170:173], v[106:109]
	v_mfma_f32_16x16x32_f16 v[94:97], v[140:143], v[178:181], v[94:97]
	v_mfma_f32_16x16x32_f16 v[90:93], v[154:157], v[178:181], v[90:93]
	v_mfma_f32_16x16x32_f16 v[78:81], v[140:143], v[186:189], v[78:81]
	v_mfma_f32_16x16x32_f16 v[74:77], v[154:157], v[186:189], v[74:77]
	v_mfma_f32_16x16x32_f16 v[126:129], v[150:153], v[166:169], v[126:129]
	v_mfma_f32_16x16x32_f16 v[122:125], v[158:161], v[166:169], v[122:125]
	v_mfma_f32_16x16x32_f16 v[110:113], v[150:153], v[174:177], v[110:113]
	v_mfma_f32_16x16x32_f16 v[106:109], v[158:161], v[174:177], v[106:109]
	v_mfma_f32_16x16x32_f16 v[94:97], v[150:153], v[182:185], v[94:97]
	v_mfma_f32_16x16x32_f16 v[90:93], v[158:161], v[182:185], v[90:93]
	v_mfma_f32_16x16x32_f16 v[78:81], v[150:153], v[190:193], v[78:81]
	v_mfma_f32_16x16x32_f16 v[74:77], v[158:161], v[190:193], v[74:77]
	s_setprio 0
	s_barrier
	s_add_i32 s44, 0, 0x1c000
	s_add_i32 s22, s51, s48
	v_add_u32_e32 v216, s44, v147
	v_lshl_add_u64 v[144:145], v[144:145], 0, s[92:93]
	s_mov_b32 m0, s22
	ds_read_b128 v[194:197], v216
	ds_read_b128 v[198:201], v216 offset:1024
	ds_read_b128 v[202:205], v216 offset:2048
	ds_read_b128 v[220:223], v216 offset:3072
	global_load_lds_dwordx4 v[144:145], off
	v_lshl_add_u64 v[144:145], v[206:207], 0, s[92:93]
	s_add_i32 m0, s22, 0x2000
	s_nop 0
	global_load_lds_dwordx4 v[144:145], off
	s_barrier
	s_waitcnt lgkmcnt(0)
	s_setprio 1
	s_waitcnt lgkmcnt(0)
	v_mfma_f32_16x16x32_f16 v[118:121], v[194:197], v[162:165], v[118:121]
	v_mfma_f32_16x16x32_f16 v[114:117], v[202:205], v[162:165], v[114:117]
	v_mfma_f32_16x16x32_f16 v[102:105], v[194:197], v[170:173], v[102:105]
	v_mfma_f32_16x16x32_f16 v[98:101], v[202:205], v[170:173], v[98:101]
	v_mfma_f32_16x16x32_f16 v[86:89], v[194:197], v[178:181], v[86:89]
	v_mfma_f32_16x16x32_f16 v[82:85], v[202:205], v[178:181], v[82:85]
	v_mfma_f32_16x16x32_f16 v[70:73], v[194:197], v[186:189], v[70:73]
	v_mfma_f32_16x16x32_f16 v[66:69], v[202:205], v[186:189], v[66:69]
	v_mfma_f32_16x16x32_f16 v[118:121], v[198:201], v[166:169], v[118:121]
	v_mfma_f32_16x16x32_f16 v[114:117], v[220:223], v[166:169], v[114:117]
	v_mfma_f32_16x16x32_f16 v[102:105], v[198:201], v[174:177], v[102:105]
	v_mfma_f32_16x16x32_f16 v[98:101], v[220:223], v[174:177], v[98:101]
	v_mfma_f32_16x16x32_f16 v[86:89], v[198:201], v[182:185], v[86:89]
	v_mfma_f32_16x16x32_f16 v[82:85], v[220:223], v[182:185], v[82:85]
	v_mfma_f32_16x16x32_f16 v[70:73], v[198:201], v[190:193], v[70:73]
	v_mfma_f32_16x16x32_f16 v[66:69], v[220:223], v[190:193], v[66:69]
	s_setprio 0
	s_mov_b32 m0, s69
	v_lshl_add_u64 v[144:145], v[212:213], 0, s[92:93]
	s_barrier
	ds_read_b128 v[162:165], v149 offset:49152
	ds_read_b128 v[166:169], v149 offset:50176
	ds_read_b128 v[170:173], v149 offset:51200
	ds_read_b128 v[174:177], v149 offset:52224
	ds_read_b128 v[178:181], v149 offset:53248
	ds_read_b128 v[182:185], v149 offset:54272
	ds_read_b128 v[186:189], v149 offset:55296
	ds_read_b128 v[190:193], v149 offset:56320
	global_load_lds_dwordx4 v[144:145], off
	v_lshl_add_u64 v[144:145], v[214:215], 0, s[92:93]
	s_mov_b32 m0, s70
	s_nop 0
	global_load_lds_dwordx4 v[144:145], off
	s_barrier
; #define PG8_STAGE(bufoff, gbase, voff) do { _Pragma("unroll") for (int _i = 0; _i < 2; ++_i) \
;         __builtin_amdgcn_global_load_lds((const unsigned*)((const char*)(gbase) + (voff)[_i]), (LAS unsigned*)(lds + (bufoff) + ldsw + _i * 8192), 16, 0, 0); } while (0)
; #define PG8_MMA(ai, bj, At, Bt_) do { __builtin_amdgcn_s_setprio(1); _Pragma("unroll") for (int m = 0; m < 4; ++m) _Pragma("unroll") for (int n = 0; n < 2; ++n) _Pragma("unroll") for (int k = 0; k < 2; ++k) \
;         acc[ai][bj][m][n] = __builtin_amdgcn_mfma_f32_16x16x32_f16(Bt_[n][k], At[m][k], acc[ai][bj][m][n], 0, 0, 0); __builtin_amdgcn_s_setprio(0); } while (0)
; #define PG8_WAIT_V(n) asm volatile("s_waitcnt vmcnt(" #n ")" ::: "memory")
; #define PG8_WAIT_L(n) asm volatile("s_waitcnt lgkmcnt(" #n ")" ::: "memory")
; #define PG8_BAR __builtin_amdgcn_s_barrier()
; #define PG8_SCHED __builtin_amdgcn_sched_barrier(0)
; template <class Epi, class AMap>
; __device__ __forceinline__ void gemm_phase(LAS unsigned char* lds, const AMap am, const int lda, const h16* Bt, const int ldb, const int M, const int N, const int K, const Epi& E) {
;     ...
;             PG8_BAR; PG8_WAIT_L(0); PG8_MMA(1, 0, At, B0); PG8_BAR; PG8_SCHED;
;             PG8_STAGE(PG8_SB(1, 1), b3 + hstepB, voffB);
;             PG8_WAIT_V(6); PG8_BAR; PG8_MMA(1, 1, At, B1); PG8_BAR;
;     __device__ __forceinline__ void operator()(const f32x4 (&acc)[2][2][4][2], const Unit& u, int wr, int wc, int fr, int fq) const {
;         EPI_ROWS_PERM
; #pragma unroll
;         for (int ai = 0; ai < 2; ++ai)
; #pragma unroll
;             for (int m = 0; m < 4; ++m) { const size_t off = (size_t)(row0 + ai * 128 + m * 16) * DM + colt;
; #pragma unroll
;                 for (int bj = 0; bj < 2; ++bj) {
;                     const h16x8 x = *(const h16x8*)(X + off + bj * 128);
;                     f32x4 o0, o1;
; #pragma unroll
;                     for (int e = 0; e < 4; ++e) { o0[e] = (float)x[e] * ALPHA + acc[ai][bj][m][0][e]; o1[e] = (float)x[4 + e] * ALPHA + acc[ai][bj][m][1][e]; }
;                     *(u32x4*)(PRE + off + bj * 128) = pack8(o0, o1); } }
	s_waitcnt lgkmcnt(0)
	s_setprio 1
	s_waitcnt lgkmcnt(0)
	v_mfma_f32_16x16x32_f16 v[62:65], v[140:143], v[162:165], v[62:65]
	v_mfma_f32_16x16x32_f16 v[58:61], v[154:157], v[162:165], v[58:61]
	v_mfma_f32_16x16x32_f16 v[46:49], v[140:143], v[170:173], v[46:49]
	v_mfma_f32_16x16x32_f16 v[42:45], v[154:157], v[170:173], v[42:45]
	v_mfma_f32_16x16x32_f16 v[30:33], v[140:143], v[178:181], v[30:33]
	v_mfma_f32_16x16x32_f16 v[26:29], v[154:157], v[178:181], v[26:29]
	v_mfma_f32_16x16x32_f16 v[14:17], v[140:143], v[186:189], v[14:17]
	v_mfma_f32_16x16x32_f16 v[10:13], v[154:157], v[186:189], v[10:13]
	v_mfma_f32_16x16x32_f16 v[62:65], v[150:153], v[166:169], v[62:65]
	v_mfma_f32_16x16x32_f16 v[58:61], v[158:161], v[166:169], v[58:61]
	v_mfma_f32_16x16x32_f16 v[46:49], v[150:153], v[174:177], v[46:49]
	v_mfma_f32_16x16x32_f16 v[42:45], v[158:161], v[174:177], v[42:45]
	v_mfma_f32_16x16x32_f16 v[30:33], v[150:153], v[182:185], v[30:33]
	v_mfma_f32_16x16x32_f16 v[26:29], v[158:161], v[182:185], v[26:29]
	v_mfma_f32_16x16x32_f16 v[14:17], v[150:153], v[190:193], v[14:17]
	v_mfma_f32_16x16x32_f16 v[10:13], v[158:161], v[190:193], v[10:13]
	s_setprio 0
	s_barrier
	s_add_u32 s22, s42, 0x158080
	s_addc_u32 s23, s43, 0
	s_add_i32 s42, s44, s48
	v_lshl_add_u64 v[140:141], s[22:23], 0, v[0:1]
	s_mov_b32 m0, s42
	s_nop 0
	global_load_lds_dwordx4 v[140:141], off
	v_lshl_add_u64 v[140:141], s[22:23], 0, v[134:135]
	s_add_i32 m0, s42, 0x2000
	s_nop 0
	global_load_lds_dwordx4 v[140:141], off
	s_waitcnt vmcnt(6)
	s_barrier
	s_setprio 1
	v_mfma_f32_16x16x32_f16 v[54:57], v[194:197], v[162:165], v[54:57]
	v_mfma_f32_16x16x32_f16 v[50:53], v[202:205], v[162:165], v[50:53]
	v_mfma_f32_16x16x32_f16 v[38:41], v[194:197], v[170:173], v[38:41]
	v_mfma_f32_16x16x32_f16 v[34:37], v[202:205], v[170:173], v[34:37]
	v_mfma_f32_16x16x32_f16 v[22:25], v[194:197], v[178:181], v[22:25]
	v_mfma_f32_16x16x32_f16 v[18:21], v[202:205], v[178:181], v[18:21]
	v_mfma_f32_16x16x32_f16 v[6:9], v[194:197], v[186:189], v[6:9]
	v_mfma_f32_16x16x32_f16 v[2:5], v[202:205], v[186:189], v[2:5]
	v_mfma_f32_16x16x32_f16 v[54:57], v[198:201], v[166:169], v[54:57]
	v_mfma_f32_16x16x32_f16 v[50:53], v[220:223], v[166:169], v[50:53]
	v_mfma_f32_16x16x32_f16 v[38:41], v[198:201], v[174:177], v[38:41]
	v_mfma_f32_16x16x32_f16 v[34:37], v[220:223], v[174:177], v[34:37]
	v_mfma_f32_16x16x32_f16 v[22:25], v[198:201], v[182:185], v[22:25]
	v_mfma_f32_16x16x32_f16 v[18:21], v[220:223], v[182:185], v[18:21]
	v_mfma_f32_16x16x32_f16 v[6:9], v[198:201], v[190:193], v[6:9]
	v_mfma_f32_16x16x32_f16 v[2:5], v[220:223], v[190:193], v[2:5]
	s_setprio 0
	s_add_i32 s29, s29, 2
	s_add_u32 s20, s20, 0x100
	s_addc_u32 s21, s21, 0
	s_cmpk_gt_u32 s29, 0x53
	s_mov_b64 s[22:23], s[26:27]
	s_barrier
	s_cbranch_scc0 .LBB0_61
	v_lshl_add_u32 v144, s35, 8, v146
	v_lshl_or_b32 v142, s50, 8, v148
	v_ashrrev_i32_e32 v145, 31, v144
	v_ashrrev_i32_e32 v143, 31, v142
	v_lshlrev_b64 v[140:141], 11, v[144:145]
	v_lshl_add_u64 v[140:141], v[140:141], 0, v[142:143]
	v_lshlrev_b64 v[140:141], 1, v[140:141]
	v_lshl_add_u64 v[154:155], s[94:95], 0, v[140:141]
	s_mov_b32 s101, 0
	global_load_dwordx4 v[158:161], v[154:155], off
	global_load_dwordx4 v[162:165], v[154:155], off offset:256
	s_mov_b32 s100, 0x10000
	v_lshl_add_u64 v[232:233], v[154:155], 0, s[100:101]
	global_load_dwordx4 v[166:169], v[232:233], off
	global_load_dwordx4 v[170:173], v[232:233], off offset:256
	s_mov_b32 s100, 0x20000
	v_lshl_add_u64 v[232:233], v[154:155], 0, s[100:101]
	global_load_dwordx4 v[174:177], v[232:233], off
	global_load_dwordx4 v[178:181], v[232:233], off offset:256
	s_mov_b32 s100, 0x30000
	v_lshl_add_u64 v[232:233], v[154:155], 0, s[100:101]
	global_load_dwordx4 v[182:185], v[232:233], off
	global_load_dwordx4 v[186:189], v[232:233], off offset:256
	s_mov_b32 s100, 0x80000
	v_lshl_add_u64 v[232:233], v[154:155], 0, s[100:101]
	global_load_dwordx4 v[190:193], v[232:233], off
	global_load_dwordx4 v[194:197], v[232:233], off offset:256
	s_mov_b32 s100, 0x90000
	v_lshl_add_u64 v[232:233], v[154:155], 0, s[100:101]
	global_load_dwordx4 v[198:201], v[232:233], off
	global_load_dwordx4 v[202:205], v[232:233], off offset:256
	s_mov_b32 s100, 0xa0000
	v_lshl_add_u64 v[232:233], v[154:155], 0, s[100:101]
	global_load_dwordx4 v[212:215], v[232:233], off
	global_load_dwordx4 v[220:223], v[232:233], off offset:256
	s_mov_b32 s100, 0xb0000
	v_lshl_add_u64 v[232:233], v[154:155], 0, s[100:101]
	global_load_dwordx4 v[224:227], v[232:233], off
	global_load_dwordx4 v[228:231], v[232:233], off offset:256
	s_mov_b64 s[4:5], 0xb0000
	s_and_b64 vcc, exec, s[38:39]
	s_mov_b32 s50, s72
	s_mov_b64 s[26:27], s[40:41]
	s_mov_b64 s[22:23], s[0:1]
	s_waitcnt vmcnt(15)
	v_mov_b64_e32 v[150:151], v[158:159]
	v_mov_b64_e32 v[152:153], v[160:161]
	v_cvt_f32_f16_e32 v156, v150
	v_cvt_f32_f16_sdwa v157, v150 dst_sel:DWORD dst_unused:UNUSED_PAD src0_sel:WORD_1
	v_cvt_f32_f16_e32 v150, v151
	v_cvt_f32_f16_sdwa v151, v151 dst_sel:DWORD dst_unused:UNUSED_PAD src0_sel:WORD_1
	v_pk_fma_f32 v[126:127], v[156:157], s[34:35], v[126:127] op_sel_hi:[1,0,1]
	s_nop 0
	v_cvt_pk_f16_f32 v126, v126, v127
	v_pk_fma_f32 v[128:129], v[150:151], s[34:35], v[128:129] op_sel_hi:[1,0,1]
	v_lshl_add_u64 v[150:151], s[8:9], 0, v[140:141]
	v_cvt_pk_f16_f32 v127, v128, v129
	v_cvt_f32_f16_e32 v128, v152
	v_cvt_f32_f16_sdwa v129, v152 dst_sel:DWORD dst_unused:UNUSED_PAD src0_sel:WORD_1
	v_pk_fma_f32 v[122:123], v[128:129], s[34:35], v[122:123] op_sel_hi:[1,0,1]
	s_nop 0
	v_cvt_pk_f16_f32 v128, v122, v123
	v_cvt_f32_f16_e32 v122, v153
	v_cvt_f32_f16_sdwa v123, v153 dst_sel:DWORD dst_unused:UNUSED_PAD src0_sel:WORD_1
	v_pk_fma_f32 v[122:123], v[122:123], s[34:35], v[124:125] op_sel_hi:[1,0,1]
	s_nop 0
	v_cvt_pk_f16_f32 v129, v122, v123
	s_nop 0
	global_store_dwordx4 v[150:151], v[126:129], off
	s_waitcnt vmcnt(15)
;     __device__ __forceinline__ void operator()(const f32x4 (&acc)[2][2][4][2], const Unit& u, int wr, int wc, int fr, int fq) const {
;     ...
;             for (int m = 0; m < 4; ++m) { const size_t off = (size_t)(row0 + ai * 128 + m * 16) * DM + colt;
; #pragma unroll
;                 for (int bj = 0; bj < 2; ++bj) {
;                     const h16x8 x = *(const h16x8*)(X + off + bj * 128);
;                     f32x4 o0, o1;
; #pragma unroll
;                     for (int e = 0; e < 4; ++e) { o0[e] = (float)x[e] * ALPHA + acc[ai][bj][m][0][e]; o1[e] = (float)x[4 + e] * ALPHA + acc[ai][bj][m][1][e]; }
;                     *(u32x4*)(PRE + off + bj * 128) = pack8(o0, o1); } }
	v_mov_b64_e32 v[122:123], v[162:163]
	v_mov_b64_e32 v[124:125], v[164:165]
	s_nop 0
	v_cvt_f32_f16_e32 v126, v122
	v_cvt_f32_f16_sdwa v127, v122 dst_sel:DWORD dst_unused:UNUSED_PAD src0_sel:WORD_1
	v_cvt_f32_f16_e32 v122, v123
	v_cvt_f32_f16_sdwa v123, v123 dst_sel:DWORD dst_unused:UNUSED_PAD src0_sel:WORD_1
	v_pk_fma_f32 v[118:119], v[126:127], s[34:35], v[118:119] op_sel_hi:[1,0,1]
	s_nop 0
	v_cvt_pk_f16_f32 v118, v118, v119
	v_pk_fma_f32 v[120:121], v[122:123], s[34:35], v[120:121] op_sel_hi:[1,0,1]
	s_nop 0
	v_cvt_pk_f16_f32 v119, v120, v121
	v_cvt_f32_f16_e32 v120, v124
	v_cvt_f32_f16_sdwa v121, v124 dst_sel:DWORD dst_unused:UNUSED_PAD src0_sel:WORD_1
	v_pk_fma_f32 v[114:115], v[120:121], s[34:35], v[114:115] op_sel_hi:[1,0,1]
	s_nop 0
	v_cvt_pk_f16_f32 v120, v114, v115
	v_cvt_f32_f16_e32 v114, v125
	v_cvt_f32_f16_sdwa v115, v125 dst_sel:DWORD dst_unused:UNUSED_PAD src0_sel:WORD_1
	v_pk_fma_f32 v[114:115], v[114:115], s[34:35], v[116:117] op_sel_hi:[1,0,1]
	s_nop 0
	v_cvt_pk_f16_f32 v121, v114, v115
	v_or_b32_e32 v114, 16, v144
	v_ashrrev_i32_e32 v115, 31, v114
	v_lshlrev_b64 v[114:115], 11, v[114:115]
	v_lshl_add_u64 v[114:115], v[114:115], 0, v[142:143]
	global_store_dwordx4 v[150:151], v[118:121], off offset:256
	s_nop 1
	v_lshlrev_b64 v[118:119], 1, v[114:115]
	v_lshl_add_u64 v[120:121], s[94:95], 0, v[118:119]
	s_waitcnt vmcnt(15)
	v_mov_b64_e32 v[114:115], v[166:167]
	v_mov_b64_e32 v[116:117], v[168:169]
	v_cvt_f32_f16_e32 v122, v114
	v_cvt_f32_f16_sdwa v123, v114 dst_sel:DWORD dst_unused:UNUSED_PAD src0_sel:WORD_1
	v_cvt_f32_f16_e32 v114, v115
	v_cvt_f32_f16_sdwa v115, v115 dst_sel:DWORD dst_unused:UNUSED_PAD src0_sel:WORD_1
	v_pk_fma_f32 v[110:111], v[122:123], s[34:35], v[110:111] op_sel_hi:[1,0,1]
	s_nop 0
	v_cvt_pk_f16_f32 v110, v110, v111
	v_pk_fma_f32 v[112:113], v[114:115], s[34:35], v[112:113] op_sel_hi:[1,0,1]
	v_lshl_add_u64 v[114:115], s[8:9], 0, v[118:119]
	v_cvt_pk_f16_f32 v111, v112, v113
	v_cvt_f32_f16_e32 v112, v116
	v_cvt_f32_f16_sdwa v113, v116 dst_sel:DWORD dst_unused:UNUSED_PAD src0_sel:WORD_1
	v_pk_fma_f32 v[106:107], v[112:113], s[34:35], v[106:107] op_sel_hi:[1,0,1]
	s_nop 0
	v_cvt_pk_f16_f32 v112, v106, v107
	v_cvt_f32_f16_e32 v106, v117
	v_cvt_f32_f16_sdwa v107, v117 dst_sel:DWORD dst_unused:UNUSED_PAD src0_sel:WORD_1
	v_pk_fma_f32 v[106:107], v[106:107], s[34:35], v[108:109] op_sel_hi:[1,0,1]
	s_nop 0
	v_cvt_pk_f16_f32 v113, v106, v107
	s_nop 0
	global_store_dwordx4 v[114:115], v[110:113], off
	s_waitcnt vmcnt(15)
	v_mov_b64_e32 v[106:107], v[170:171]
	v_mov_b64_e32 v[108:109], v[172:173]
	s_nop 0
	v_cvt_f32_f16_e32 v110, v106
	v_cvt_f32_f16_sdwa v111, v106 dst_sel:DWORD dst_unused:UNUSED_PAD src0_sel:WORD_1
	v_cvt_f32_f16_e32 v106, v107
	v_cvt_f32_f16_sdwa v107, v107 dst_sel:DWORD dst_unused:UNUSED_PAD src0_sel:WORD_1
	v_pk_fma_f32 v[102:103], v[110:111], s[34:35], v[102:103] op_sel_hi:[1,0,1]
	s_nop 0
	v_cvt_pk_f16_f32 v102, v102, v103
	v_pk_fma_f32 v[104:105], v[106:107], s[34:35], v[104:105] op_sel_hi:[1,0,1]
	s_nop 0
	v_cvt_pk_f16_f32 v103, v104, v105
	v_cvt_f32_f16_e32 v104, v108
	v_cvt_f32_f16_sdwa v105, v108 dst_sel:DWORD dst_unused:UNUSED_PAD src0_sel:WORD_1
	v_pk_fma_f32 v[98:99], v[104:105], s[34:35], v[98:99] op_sel_hi:[1,0,1]
	s_nop 0
	v_cvt_pk_f16_f32 v104, v98, v99
	v_cvt_f32_f16_e32 v98, v109
	v_cvt_f32_f16_sdwa v99, v109 dst_sel:DWORD dst_unused:UNUSED_PAD src0_sel:WORD_1
	v_pk_fma_f32 v[98:99], v[98:99], s[34:35], v[100:101] op_sel_hi:[1,0,1]
	s_nop 0
	v_cvt_pk_f16_f32 v105, v98, v99
	v_or_b32_e32 v98, 32, v144
	v_ashrrev_i32_e32 v99, 31, v98
	v_lshlrev_b64 v[98:99], 11, v[98:99]
	v_lshl_add_u64 v[98:99], v[98:99], 0, v[142:143]
	global_store_dwordx4 v[114:115], v[102:105], off offset:256
	s_nop 1
	v_lshlrev_b64 v[102:103], 1, v[98:99]
	v_lshl_add_u64 v[104:105], s[94:95], 0, v[102:103]
	s_waitcnt vmcnt(15)
	v_mov_b64_e32 v[98:99], v[174:175]
	v_mov_b64_e32 v[100:101], v[176:177]
	v_cvt_f32_f16_e32 v106, v98
	v_cvt_f32_f16_sdwa v107, v98 dst_sel:DWORD dst_unused:UNUSED_PAD src0_sel:WORD_1
	v_cvt_f32_f16_e32 v98, v99
	v_cvt_f32_f16_sdwa v99, v99 dst_sel:DWORD dst_unused:UNUSED_PAD src0_sel:WORD_1
	v_pk_fma_f32 v[94:95], v[106:107], s[34:35], v[94:95] op_sel_hi:[1,0,1]
	s_nop 0
	v_cvt_pk_f16_f32 v94, v94, v95
	v_pk_fma_f32 v[96:97], v[98:99], s[34:35], v[96:97] op_sel_hi:[1,0,1]
	v_lshl_add_u64 v[98:99], s[8:9], 0, v[102:103]
	v_cvt_pk_f16_f32 v95, v96, v97
	v_cvt_f32_f16_e32 v96, v100
	v_cvt_f32_f16_sdwa v97, v100 dst_sel:DWORD dst_unused:UNUSED_PAD src0_sel:WORD_1
	v_pk_fma_f32 v[90:91], v[96:97], s[34:35], v[90:91] op_sel_hi:[1,0,1]
	s_nop 0
	v_cvt_pk_f16_f32 v96, v90, v91
	v_cvt_f32_f16_e32 v90, v101
	v_cvt_f32_f16_sdwa v91, v101 dst_sel:DWORD dst_unused:UNUSED_PAD src0_sel:WORD_1
	v_pk_fma_f32 v[90:91], v[90:91], s[34:35], v[92:93] op_sel_hi:[1,0,1]
	s_nop 0
	v_cvt_pk_f16_f32 v97, v90, v91
	s_nop 0
	global_store_dwordx4 v[98:99], v[94:97], off
	s_waitcnt vmcnt(15)
	v_mov_b64_e32 v[90:91], v[178:179]
	v_mov_b64_e32 v[92:93], v[180:181]
	s_nop 0
	v_cvt_f32_f16_e32 v94, v90
	v_cvt_f32_f16_sdwa v95, v90 dst_sel:DWORD dst_unused:UNUSED_PAD src0_sel:WORD_1
	v_cvt_f32_f16_e32 v90, v91
	v_cvt_f32_f16_sdwa v91, v91 dst_sel:DWORD dst_unused:UNUSED_PAD src0_sel:WORD_1
	v_pk_fma_f32 v[86:87], v[94:95], s[34:35], v[86:87] op_sel_hi:[1,0,1]
	s_nop 0
	v_cvt_pk_f16_f32 v86, v86, v87
	v_pk_fma_f32 v[88:89], v[90:91], s[34:35], v[88:89] op_sel_hi:[1,0,1]
	s_nop 0
	v_cvt_pk_f16_f32 v87, v88, v89
	v_cvt_f32_f16_e32 v88, v92
	v_cvt_f32_f16_sdwa v89, v92 dst_sel:DWORD dst_unused:UNUSED_PAD src0_sel:WORD_1
	v_pk_fma_f32 v[82:83], v[88:89], s[34:35], v[82:83] op_sel_hi:[1,0,1]
	s_nop 0
	v_cvt_pk_f16_f32 v88, v82, v83
	v_cvt_f32_f16_e32 v82, v93
	v_cvt_f32_f16_sdwa v83, v93 dst_sel:DWORD dst_unused:UNUSED_PAD src0_sel:WORD_1
	v_pk_fma_f32 v[82:83], v[82:83], s[34:35], v[84:85] op_sel_hi:[1,0,1]
	s_nop 0
	v_cvt_pk_f16_f32 v89, v82, v83
	v_or_b32_e32 v82, 48, v144
	v_ashrrev_i32_e32 v83, 31, v82
	v_lshlrev_b64 v[82:83], 11, v[82:83]
	v_lshl_add_u64 v[82:83], v[82:83], 0, v[142:143]
	global_store_dwordx4 v[98:99], v[86:89], off offset:256
	s_nop 1
	v_lshlrev_b64 v[86:87], 1, v[82:83]
	v_lshl_add_u64 v[88:89], s[94:95], 0, v[86:87]
	s_waitcnt vmcnt(15)
;     __device__ __forceinline__ void operator()(const f32x4 (&acc)[2][2][4][2], const Unit& u, int wr, int wc, int fr, int fq) const {
;     ...
;             for (int m = 0; m < 4; ++m) { const size_t off = (size_t)(row0 + ai * 128 + m * 16) * DM + colt;
; #pragma unroll
;                 for (int bj = 0; bj < 2; ++bj) {
;                     const h16x8 x = *(const h16x8*)(X + off + bj * 128);
;                     f32x4 o0, o1;
; #pragma unroll
;                     for (int e = 0; e < 4; ++e) { o0[e] = (float)x[e] * ALPHA + acc[ai][bj][m][0][e]; o1[e] = (float)x[4 + e] * ALPHA + acc[ai][bj][m][1][e]; }
;                     *(u32x4*)(PRE + off + bj * 128) = pack8(o0, o1); } }
	v_mov_b64_e32 v[82:83], v[182:183]
	v_mov_b64_e32 v[84:85], v[184:185]
	v_cvt_f32_f16_e32 v90, v82
	v_cvt_f32_f16_sdwa v91, v82 dst_sel:DWORD dst_unused:UNUSED_PAD src0_sel:WORD_1
	v_cvt_f32_f16_e32 v82, v83
	v_cvt_f32_f16_sdwa v83, v83 dst_sel:DWORD dst_unused:UNUSED_PAD src0_sel:WORD_1
	v_pk_fma_f32 v[78:79], v[90:91], s[34:35], v[78:79] op_sel_hi:[1,0,1]
	s_nop 0
	v_cvt_pk_f16_f32 v78, v78, v79
	v_pk_fma_f32 v[80:81], v[82:83], s[34:35], v[80:81] op_sel_hi:[1,0,1]
	v_lshl_add_u64 v[82:83], s[8:9], 0, v[86:87]
	v_cvt_pk_f16_f32 v79, v80, v81
	v_cvt_f32_f16_e32 v80, v84
	v_cvt_f32_f16_sdwa v81, v84 dst_sel:DWORD dst_unused:UNUSED_PAD src0_sel:WORD_1
	v_pk_fma_f32 v[74:75], v[80:81], s[34:35], v[74:75] op_sel_hi:[1,0,1]
	s_nop 0
	v_cvt_pk_f16_f32 v80, v74, v75
	v_cvt_f32_f16_e32 v74, v85
	v_cvt_f32_f16_sdwa v75, v85 dst_sel:DWORD dst_unused:UNUSED_PAD src0_sel:WORD_1
	v_pk_fma_f32 v[74:75], v[74:75], s[34:35], v[76:77] op_sel_hi:[1,0,1]
	s_nop 0
	v_cvt_pk_f16_f32 v81, v74, v75
	s_nop 0
	global_store_dwordx4 v[82:83], v[78:81], off
	s_waitcnt vmcnt(15)
	v_mov_b64_e32 v[74:75], v[186:187]
	v_mov_b64_e32 v[76:77], v[188:189]
	s_nop 0
	v_cvt_f32_f16_e32 v78, v74
	v_cvt_f32_f16_sdwa v79, v74 dst_sel:DWORD dst_unused:UNUSED_PAD src0_sel:WORD_1
	v_cvt_f32_f16_e32 v74, v75
	v_cvt_f32_f16_sdwa v75, v75 dst_sel:DWORD dst_unused:UNUSED_PAD src0_sel:WORD_1
	v_pk_fma_f32 v[70:71], v[78:79], s[34:35], v[70:71] op_sel_hi:[1,0,1]
	s_nop 0
	v_cvt_pk_f16_f32 v70, v70, v71
	v_pk_fma_f32 v[72:73], v[74:75], s[34:35], v[72:73] op_sel_hi:[1,0,1]
	s_nop 0
	v_cvt_pk_f16_f32 v71, v72, v73
	v_cvt_f32_f16_e32 v72, v76
	v_cvt_f32_f16_sdwa v73, v76 dst_sel:DWORD dst_unused:UNUSED_PAD src0_sel:WORD_1
	v_pk_fma_f32 v[66:67], v[72:73], s[34:35], v[66:67] op_sel_hi:[1,0,1]
	s_nop 0
	v_cvt_pk_f16_f32 v72, v66, v67
	v_cvt_f32_f16_e32 v66, v77
	v_cvt_f32_f16_sdwa v67, v77 dst_sel:DWORD dst_unused:UNUSED_PAD src0_sel:WORD_1
	v_pk_fma_f32 v[66:67], v[66:67], s[34:35], v[68:69] op_sel_hi:[1,0,1]
	s_nop 0
	v_cvt_pk_f16_f32 v73, v66, v67
	global_store_dwordx4 v[82:83], v[70:73], off offset:256
	s_nop 1
	v_lshl_add_u64 v[70:71], v[140:141], 0, s[16:17]
	v_lshl_add_u64 v[72:73], s[94:95], 0, v[70:71]
	s_waitcnt vmcnt(15)
	v_mov_b64_e32 v[66:67], v[190:191]
	v_mov_b64_e32 v[68:69], v[192:193]
	v_cvt_f32_f16_e32 v74, v66
	v_cvt_f32_f16_sdwa v75, v66 dst_sel:DWORD dst_unused:UNUSED_PAD src0_sel:WORD_1
	v_cvt_f32_f16_e32 v66, v67
	v_cvt_f32_f16_sdwa v67, v67 dst_sel:DWORD dst_unused:UNUSED_PAD src0_sel:WORD_1
	v_pk_fma_f32 v[62:63], v[74:75], s[34:35], v[62:63] op_sel_hi:[1,0,1]
	s_nop 0
	v_cvt_pk_f16_f32 v62, v62, v63
	v_pk_fma_f32 v[64:65], v[66:67], s[34:35], v[64:65] op_sel_hi:[1,0,1]
	v_lshl_add_u64 v[66:67], s[8:9], 0, v[70:71]
	v_cvt_pk_f16_f32 v63, v64, v65
	v_cvt_f32_f16_e32 v64, v68
	v_cvt_f32_f16_sdwa v65, v68 dst_sel:DWORD dst_unused:UNUSED_PAD src0_sel:WORD_1
	v_pk_fma_f32 v[58:59], v[64:65], s[34:35], v[58:59] op_sel_hi:[1,0,1]
	s_nop 0
	v_cvt_pk_f16_f32 v64, v58, v59
	v_cvt_f32_f16_e32 v58, v69
	v_cvt_f32_f16_sdwa v59, v69 dst_sel:DWORD dst_unused:UNUSED_PAD src0_sel:WORD_1
	v_pk_fma_f32 v[58:59], v[58:59], s[34:35], v[60:61] op_sel_hi:[1,0,1]
	s_nop 0
	v_cvt_pk_f16_f32 v65, v58, v59
	s_nop 0
	global_store_dwordx4 v[66:67], v[62:65], off
	s_waitcnt vmcnt(15)
	v_mov_b64_e32 v[58:59], v[194:195]
	v_mov_b64_e32 v[60:61], v[196:197]
	s_nop 0
	v_cvt_f32_f16_e32 v62, v58
	v_cvt_f32_f16_sdwa v63, v58 dst_sel:DWORD dst_unused:UNUSED_PAD src0_sel:WORD_1
	v_cvt_f32_f16_e32 v58, v59
	v_cvt_f32_f16_sdwa v59, v59 dst_sel:DWORD dst_unused:UNUSED_PAD src0_sel:WORD_1
	v_pk_fma_f32 v[54:55], v[62:63], s[34:35], v[54:55] op_sel_hi:[1,0,1]
	s_nop 0
	v_cvt_pk_f16_f32 v54, v54, v55
	v_pk_fma_f32 v[56:57], v[58:59], s[34:35], v[56:57] op_sel_hi:[1,0,1]
	s_nop 0
	v_cvt_pk_f16_f32 v55, v56, v57
	v_cvt_f32_f16_e32 v56, v60
	v_cvt_f32_f16_sdwa v57, v60 dst_sel:DWORD dst_unused:UNUSED_PAD src0_sel:WORD_1
	v_pk_fma_f32 v[50:51], v[56:57], s[34:35], v[50:51] op_sel_hi:[1,0,1]
	s_nop 0
	v_cvt_pk_f16_f32 v56, v50, v51
	v_cvt_f32_f16_e32 v50, v61
	v_cvt_f32_f16_sdwa v51, v61 dst_sel:DWORD dst_unused:UNUSED_PAD src0_sel:WORD_1
	v_pk_fma_f32 v[50:51], v[50:51], s[34:35], v[52:53] op_sel_hi:[1,0,1]
	s_nop 0
	v_cvt_pk_f16_f32 v57, v50, v51
	global_store_dwordx4 v[66:67], v[54:57], off offset:256
	s_nop 1
	v_lshl_add_u64 v[54:55], v[140:141], 0, s[18:19]
	v_lshl_add_u64 v[56:57], s[94:95], 0, v[54:55]
	s_waitcnt vmcnt(15)
	v_mov_b64_e32 v[50:51], v[198:199]
	v_mov_b64_e32 v[52:53], v[200:201]
	v_cvt_f32_f16_e32 v58, v50
	v_cvt_f32_f16_sdwa v59, v50 dst_sel:DWORD dst_unused:UNUSED_PAD src0_sel:WORD_1
	v_cvt_f32_f16_e32 v50, v51
	v_cvt_f32_f16_sdwa v51, v51 dst_sel:DWORD dst_unused:UNUSED_PAD src0_sel:WORD_1
	v_pk_fma_f32 v[46:47], v[58:59], s[34:35], v[46:47] op_sel_hi:[1,0,1]
	s_nop 0
	v_cvt_pk_f16_f32 v46, v46, v47
	v_pk_fma_f32 v[48:49], v[50:51], s[34:35], v[48:49] op_sel_hi:[1,0,1]
	v_lshl_add_u64 v[50:51], s[8:9], 0, v[54:55]
	v_cvt_pk_f16_f32 v47, v48, v49
	v_cvt_f32_f16_e32 v48, v52
	v_cvt_f32_f16_sdwa v49, v52 dst_sel:DWORD dst_unused:UNUSED_PAD src0_sel:WORD_1
	v_pk_fma_f32 v[42:43], v[48:49], s[34:35], v[42:43] op_sel_hi:[1,0,1]
	s_nop 0
	v_cvt_pk_f16_f32 v48, v42, v43
	v_cvt_f32_f16_e32 v42, v53
	v_cvt_f32_f16_sdwa v43, v53 dst_sel:DWORD dst_unused:UNUSED_PAD src0_sel:WORD_1
	v_pk_fma_f32 v[42:43], v[42:43], s[34:35], v[44:45] op_sel_hi:[1,0,1]
	s_nop 0
	v_cvt_pk_f16_f32 v49, v42, v43
	s_nop 0
	global_store_dwordx4 v[50:51], v[46:49], off
	s_waitcnt vmcnt(15)
; #define PG8_WAIT_V(n) asm volatile("s_waitcnt vmcnt(" #n ")" ::: "memory")
; #define PG8_BAR __builtin_amdgcn_s_barrier()
; template <class Epi, class AMap>
; __device__ __forceinline__ void gemm_phase(LAS unsigned char* lds, const AMap am, const int lda, const h16* Bt, const int ldb, const int M, const int N, const int K, const Epi& E) {
;     ...
;         if (!has_next) break;
; #pragma unroll
;         for (int a = 0; a < 2; ++a)
; #pragma unroll
;             for (int b = 0; b < 2; ++b)
; #pragma unroll
;                 for (int m = 0; m < 4; ++m)
; #pragma unroll
;                     for (int n = 0; n < 2; ++n) acc[a][b][m][n] = (f32x4){0.f, 0.f, 0.f, 0.f};
;         cur = nxt; cA = nA; cB = nB; ++ui;
;     }
;     PG8_WAIT_V(0);
;     if (wr == 0) PG8_BAR;
;     PG8_BAR;
;     __device__ __forceinline__ void operator()(const f32x4 (&acc)[2][2][4][2], const Unit& u, int wr, int wc, int fr, int fq) const {
;     ...
;             for (int m = 0; m < 4; ++m) { const size_t off = (size_t)(row0 + ai * 128 + m * 16) * DM + colt;
; #pragma unroll
;                 for (int bj = 0; bj < 2; ++bj) {
;                     const h16x8 x = *(const h16x8*)(X + off + bj * 128);
;                     f32x4 o0, o1;
; #pragma unroll
;                     for (int e = 0; e < 4; ++e) { o0[e] = (float)x[e] * ALPHA + acc[ai][bj][m][0][e]; o1[e] = (float)x[4 + e] * ALPHA + acc[ai][bj][m][1][e]; }
;                     *(u32x4*)(PRE + off + bj * 128) = pack8(o0, o1); } }
	v_mov_b64_e32 v[42:43], v[202:203]
	v_mov_b64_e32 v[44:45], v[204:205]
	s_nop 0
	v_cvt_f32_f16_e32 v46, v42
	v_cvt_f32_f16_sdwa v47, v42 dst_sel:DWORD dst_unused:UNUSED_PAD src0_sel:WORD_1
	v_cvt_f32_f16_e32 v42, v43
	v_cvt_f32_f16_sdwa v43, v43 dst_sel:DWORD dst_unused:UNUSED_PAD src0_sel:WORD_1
	v_pk_fma_f32 v[38:39], v[46:47], s[34:35], v[38:39] op_sel_hi:[1,0,1]
	s_nop 0
	v_cvt_pk_f16_f32 v38, v38, v39
	v_pk_fma_f32 v[40:41], v[42:43], s[34:35], v[40:41] op_sel_hi:[1,0,1]
	s_nop 0
	v_cvt_pk_f16_f32 v39, v40, v41
	v_cvt_f32_f16_e32 v40, v44
	v_cvt_f32_f16_sdwa v41, v44 dst_sel:DWORD dst_unused:UNUSED_PAD src0_sel:WORD_1
	v_pk_fma_f32 v[34:35], v[40:41], s[34:35], v[34:35] op_sel_hi:[1,0,1]
	s_nop 0
	v_cvt_pk_f16_f32 v40, v34, v35
	v_cvt_f32_f16_e32 v34, v45
	v_cvt_f32_f16_sdwa v35, v45 dst_sel:DWORD dst_unused:UNUSED_PAD src0_sel:WORD_1
	v_pk_fma_f32 v[34:35], v[34:35], s[34:35], v[36:37] op_sel_hi:[1,0,1]
	s_nop 0
	v_cvt_pk_f16_f32 v41, v34, v35
	global_store_dwordx4 v[50:51], v[38:41], off offset:256
	s_nop 1
	v_lshl_add_u64 v[38:39], v[140:141], 0, s[14:15]
	v_lshl_add_u64 v[40:41], s[94:95], 0, v[38:39]
	s_waitcnt vmcnt(15)
	v_mov_b64_e32 v[34:35], v[212:213]
	v_mov_b64_e32 v[36:37], v[214:215]
	v_cvt_f32_f16_e32 v42, v34
	v_cvt_f32_f16_sdwa v43, v34 dst_sel:DWORD dst_unused:UNUSED_PAD src0_sel:WORD_1
	v_cvt_f32_f16_e32 v34, v35
	v_cvt_f32_f16_sdwa v35, v35 dst_sel:DWORD dst_unused:UNUSED_PAD src0_sel:WORD_1
	v_pk_fma_f32 v[30:31], v[42:43], s[34:35], v[30:31] op_sel_hi:[1,0,1]
	s_nop 0
	v_cvt_pk_f16_f32 v30, v30, v31
	v_pk_fma_f32 v[32:33], v[34:35], s[34:35], v[32:33] op_sel_hi:[1,0,1]
	v_lshl_add_u64 v[34:35], s[8:9], 0, v[38:39]
	v_cvt_pk_f16_f32 v31, v32, v33
	v_cvt_f32_f16_e32 v32, v36
	v_cvt_f32_f16_sdwa v33, v36 dst_sel:DWORD dst_unused:UNUSED_PAD src0_sel:WORD_1
	v_pk_fma_f32 v[26:27], v[32:33], s[34:35], v[26:27] op_sel_hi:[1,0,1]
	s_nop 0
	v_cvt_pk_f16_f32 v32, v26, v27
	v_cvt_f32_f16_e32 v26, v37
	v_cvt_f32_f16_sdwa v27, v37 dst_sel:DWORD dst_unused:UNUSED_PAD src0_sel:WORD_1
	v_pk_fma_f32 v[26:27], v[26:27], s[34:35], v[28:29] op_sel_hi:[1,0,1]
	s_nop 0
	v_cvt_pk_f16_f32 v33, v26, v27
	s_nop 0
	global_store_dwordx4 v[34:35], v[30:33], off
	s_waitcnt vmcnt(15)
	v_mov_b64_e32 v[26:27], v[220:221]
	v_mov_b64_e32 v[28:29], v[222:223]
	s_nop 0
	v_cvt_f32_f16_e32 v30, v26
	v_cvt_f32_f16_sdwa v31, v26 dst_sel:DWORD dst_unused:UNUSED_PAD src0_sel:WORD_1
	v_cvt_f32_f16_e32 v26, v27
	v_cvt_f32_f16_sdwa v27, v27 dst_sel:DWORD dst_unused:UNUSED_PAD src0_sel:WORD_1
	v_pk_fma_f32 v[22:23], v[30:31], s[34:35], v[22:23] op_sel_hi:[1,0,1]
	s_nop 0
	v_cvt_pk_f16_f32 v22, v22, v23
	v_pk_fma_f32 v[24:25], v[26:27], s[34:35], v[24:25] op_sel_hi:[1,0,1]
	s_nop 0
	v_cvt_pk_f16_f32 v23, v24, v25
	v_cvt_f32_f16_e32 v24, v28
	v_cvt_f32_f16_sdwa v25, v28 dst_sel:DWORD dst_unused:UNUSED_PAD src0_sel:WORD_1
	v_pk_fma_f32 v[18:19], v[24:25], s[34:35], v[18:19] op_sel_hi:[1,0,1]
	s_nop 0
	v_cvt_pk_f16_f32 v24, v18, v19
	v_cvt_f32_f16_e32 v18, v29
	v_cvt_f32_f16_sdwa v19, v29 dst_sel:DWORD dst_unused:UNUSED_PAD src0_sel:WORD_1
	v_pk_fma_f32 v[18:19], v[18:19], s[34:35], v[20:21] op_sel_hi:[1,0,1]
	s_nop 0
	v_cvt_pk_f16_f32 v25, v18, v19
	global_store_dwordx4 v[34:35], v[22:25], off offset:256
	s_nop 1
	v_lshl_add_u64 v[22:23], v[140:141], 0, s[4:5]
	v_lshl_add_u64 v[24:25], s[94:95], 0, v[22:23]
	s_waitcnt vmcnt(15)
	v_mov_b64_e32 v[18:19], v[224:225]
	v_mov_b64_e32 v[20:21], v[226:227]
	v_cvt_f32_f16_e32 v26, v18
	v_cvt_f32_f16_sdwa v27, v18 dst_sel:DWORD dst_unused:UNUSED_PAD src0_sel:WORD_1
	v_cvt_f32_f16_e32 v18, v19
	v_cvt_f32_f16_sdwa v19, v19 dst_sel:DWORD dst_unused:UNUSED_PAD src0_sel:WORD_1
	v_pk_fma_f32 v[14:15], v[26:27], s[34:35], v[14:15] op_sel_hi:[1,0,1]
	s_nop 0
	v_cvt_pk_f16_f32 v14, v14, v15
	v_pk_fma_f32 v[16:17], v[18:19], s[34:35], v[16:17] op_sel_hi:[1,0,1]
	v_lshl_add_u64 v[18:19], s[8:9], 0, v[22:23]
	v_cvt_pk_f16_f32 v15, v16, v17
	v_cvt_f32_f16_e32 v16, v20
	v_cvt_f32_f16_sdwa v17, v20 dst_sel:DWORD dst_unused:UNUSED_PAD src0_sel:WORD_1
	v_pk_fma_f32 v[10:11], v[16:17], s[34:35], v[10:11] op_sel_hi:[1,0,1]
	s_nop 0
	v_cvt_pk_f16_f32 v16, v10, v11
	v_cvt_f32_f16_e32 v10, v21
	v_cvt_f32_f16_sdwa v11, v21 dst_sel:DWORD dst_unused:UNUSED_PAD src0_sel:WORD_1
	v_pk_fma_f32 v[10:11], v[10:11], s[34:35], v[12:13] op_sel_hi:[1,0,1]
	s_nop 0
	v_cvt_pk_f16_f32 v17, v10, v11
	s_nop 0
	global_store_dwordx4 v[18:19], v[14:17], off
	s_waitcnt vmcnt(15)
	v_mov_b64_e32 v[10:11], v[228:229]
	v_mov_b64_e32 v[12:13], v[230:231]
	s_nop 0
	v_cvt_f32_f16_e32 v14, v10
	v_cvt_f32_f16_sdwa v15, v10 dst_sel:DWORD dst_unused:UNUSED_PAD src0_sel:WORD_1
	v_cvt_f32_f16_e32 v10, v11
	v_cvt_f32_f16_sdwa v11, v11 dst_sel:DWORD dst_unused:UNUSED_PAD src0_sel:WORD_1
	v_pk_fma_f32 v[6:7], v[14:15], s[34:35], v[6:7] op_sel_hi:[1,0,1]
	s_nop 0
	v_cvt_pk_f16_f32 v6, v6, v7
	v_pk_fma_f32 v[8:9], v[10:11], s[34:35], v[8:9] op_sel_hi:[1,0,1]
	s_nop 0
	v_cvt_pk_f16_f32 v7, v8, v9
	v_cvt_f32_f16_e32 v8, v12
	v_cvt_f32_f16_sdwa v9, v12 dst_sel:DWORD dst_unused:UNUSED_PAD src0_sel:WORD_1
	v_pk_fma_f32 v[2:3], v[8:9], s[34:35], v[2:3] op_sel_hi:[1,0,1]
	s_nop 0
	v_cvt_pk_f16_f32 v8, v2, v3
	v_cvt_f32_f16_e32 v2, v13
	v_cvt_f32_f16_sdwa v3, v13 dst_sel:DWORD dst_unused:UNUSED_PAD src0_sel:WORD_1
	v_pk_fma_f32 v[2:3], v[2:3], s[34:35], v[4:5] op_sel_hi:[1,0,1]
	s_nop 0
	v_cvt_pk_f16_f32 v9, v2, v3
	s_mov_b32 s35, s73
	global_store_dwordx4 v[18:19], v[6:9], off offset:256
	s_cbranch_vccz .LBB0_50
	s_waitcnt vmcnt(0)
	s_cmpk_gt_u32 s46, 0xff
	s_cbranch_scc1 .LBB0_65
	s_barrier

; __device__ __forceinline__ int otid() { int t = (int)threadIdx.x; asm volatile("" : "+v"(t)); return t; }
; __device__ __forceinline__ int obid() { int t = (int)blockIdx.x; asm volatile("" : "+s"(t)); return t; }
; template <bool LN>
; __device__ __forceinline__ void ln_phase(const void* src, const float* g, const float* bt, float* xout, h16* xh, const float* mu, h16* mix) {
;     const int lane = otid() & 63, gw = obid() * 8 + (otid() >> 6), GW = gridDim.x * 8;
;     for (int ch = gw; ch < MTOK / 8; ch += GW) {
;         const size_t t0 = (size_t)ch * 8;
;         f32x4 prev[8], cur[8];
;         if (mix) {
;             if ((t0 & (SEQ - 1)) == 0) {
; #pragma unroll
;                 for (int i = 0; i < 8; ++i) prev[i] = (f32x4){0.f, 0.f, 0.f, 0.f};
;             } else ln_row<LN>(src, t0 - 1, lane, g, bt, prev);
;         }
;         h16x4 raw[8], rawn[8];
;         if (LN) ln_load16(src, t0, lane, raw);
; #pragma unroll 1
;         for (int r = 0; r < 8; ++r) {
;             const size_t row = t0 + r;
;             asm volatile("" ::: "memory");
;             if (LN) {
;                 ln_load16(src, t0 + (r < 7 ? r + 1 : 7), lane, rawn);
.LBB0_114:
	v_mov_b32_e32 v0, v240
	s_mov_b32 s0, s29
	s_waitcnt vmcnt(0)
	v_mov_b32_e32 v2, v240
	s_lshl_b32 s22, s0, 3
	v_ashrrev_i32_e32 v2, 6, v2
	v_add_u32_e32 v70, s22, v2
	v_cmp_gt_i32_e32 vcc, s2, v70
	s_and_saveexec_b64 s[0:1], vcc
	s_movk_i32 s2, 0x7ff
	s_cbranch_execz .LBB0_130
	v_readlane_b32 s3, v255, 9
	v_and_b32_e32 v3, 63, v0
	v_readlane_b32 s4, v254, 54
	v_readlane_b32 s16, v255, 25
	s_lshl_b32 s20, s3, 12
	v_readlane_b32 s3, v255, 12
	v_lshlrev_b32_e32 v0, 4, v3
	v_lshlrev_b32_e32 v12, 3, v3
	v_mov_b32_e32 v13, v1
	v_readlane_b32 s5, v254, 55
	v_readlane_b32 s17, v255, 26
	s_cmp_eq_u32 s3, 9
	v_lshl_add_u64 v[92:93], s[4:5], 0, v[12:13]
	v_lshl_add_u64 v[94:95], s[16:17], 0, v[0:1]
	s_mov_b64 s[4:5], 0x2400
	s_cselect_b32 s21, 0, 0x800
	v_lshl_add_u64 v[106:107], v[94:95], 0, s[4:5]
	s_mov_b64 s[4:5], 0x4400
	s_or_b32 s24, s20, s21
	v_lshl_add_u64 v[108:109], v[94:95], 0, s[4:5]
	s_mov_b64 s[4:5], 0x6400
	s_lshl_b64 s[20:21], s[24:25], 2
	v_lshl_add_u64 v[110:111], v[94:95], 0, s[4:5]
	s_mov_b64 s[4:5], 0x8400
	s_add_u32 s26, s70, s20
	v_lshl_add_u64 v[112:113], v[94:95], 0, s[4:5]
	s_mov_b64 s[4:5], 0xa400
	s_addc_u32 s27, s71, s21
	v_lshl_add_u64 v[114:115], v[94:95], 0, s[4:5]
	s_mov_b64 s[4:5], 0x2800
	s_add_u32 s20, s72, s20
	v_readlane_b32 s10, v255, 23
	v_lshl_add_u64 v[116:117], v[94:95], 0, s[4:5]
	s_mov_b64 s[4:5], 0x4800
	s_addc_u32 s21, s73, s21
	v_readlane_b32 s11, v255, 24
	v_lshl_add_u64 v[118:119], v[94:95], 0, s[4:5]
	s_mov_b64 s[4:5], 0x6800
	s_cmp_lg_u64 s[10:11], 0
	v_lshl_add_u64 v[120:121], v[94:95], 0, s[4:5]
	s_mov_b64 s[4:5], 0x8800
	s_cselect_b64 s[42:43], -1, 0
	s_cmp_lg_u64 s[8:9], 0
	v_lshl_add_u64 v[122:123], v[94:95], 0, s[4:5]
	s_mov_b64 s[4:5], 0xa800
	s_cselect_b64 s[44:45], -1, 0
	s_cmp_lg_u64 s[38:39], 0
	v_lshl_add_u64 v[124:125], v[94:95], 0, s[4:5]
	s_mov_b64 s[4:5], 0x2c00
	s_cselect_b64 s[46:47], -1, 0
	v_lshl_add_u64 v[126:127], v[94:95], 0, s[4:5]
	s_mov_b64 s[4:5], 0x4c00
	v_ashrrev_i32_e32 v3, 31, v2
	s_ashr_i32 s23, s22, 31
	v_or_b32_e32 v4, 0x1000, v0
	v_mov_b32_e32 v5, v1
	v_lshl_add_u64 v[128:129], v[94:95], 0, s[4:5]
	s_mov_b64 s[4:5], 0x6c00
	v_lshl_add_u64 v[2:3], v[2:3], 0, s[22:23]
	v_lshl_add_u64 v[76:77], s[26:27], 0, v[4:5]
	v_lshl_add_u64 v[78:79], s[20:21], 0, v[4:5]
	v_lshl_add_u64 v[130:131], v[94:95], 0, s[4:5]
	s_mov_b64 s[4:5], 0x8c00
	v_lshl_add_u64 v[136:137], s[16:17], 0, v[4:5]
	v_lshlrev_b64 v[4:5], 15, v[2:3]
	v_lshlrev_b64 v[2:3], 16, v[2:3]
	v_or_b32_e32 v6, 0x1400, v0
	v_mov_b32_e32 v7, v1
	v_or_b32_e32 v8, 0x1800, v0
	v_mov_b32_e32 v9, v1
	v_or_b32_e32 v10, 0x1c00, v0
	v_mov_b32_e32 v11, v1
	v_lshl_add_u64 v[132:133], v[94:95], 0, s[4:5]
	s_mov_b64 s[4:5], 0xac00
	v_or_b32_e32 v2, v2, v0
	v_lshl_add_u64 v[72:73], s[26:27], 0, v[0:1]
	v_lshl_add_u64 v[74:75], s[20:21], 0, v[0:1]
	v_lshl_add_u64 v[80:81], s[26:27], 0, v[6:7]
	v_lshl_add_u64 v[82:83], s[20:21], 0, v[6:7]
	v_lshl_add_u64 v[84:85], s[26:27], 0, v[8:9]
	v_lshl_add_u64 v[86:87], s[20:21], 0, v[8:9]
	v_lshl_add_u64 v[88:89], s[26:27], 0, v[10:11]
	v_lshl_add_u64 v[90:91], s[20:21], 0, v[10:11]
	s_mov_b64 s[6:7], 0x4000
	s_mov_b64 s[18:19], 0x6000
	s_mov_b64 s[20:21], 0x8000
	s_mov_b64 s[26:27], 0xa000
	v_lshl_add_u64 v[134:135], v[94:95], 0, s[4:5]
	v_lshl_add_u64 v[148:149], s[16:17], 0, v[6:7]
	v_lshl_add_u64 v[160:161], s[16:17], 0, v[8:9]
	v_lshl_add_u64 v[172:173], s[16:17], 0, v[10:11]
	v_or_b32_e32 v4, v4, v12
	v_lshl_add_u64 v[2:3], s[8:9], 0, v[2:3]
	s_mov_b64 s[4:5], 0x1000
	s_mov_b64 s[40:41], 0
	v_lshl_add_u64 v[96:97], v[94:95], 0, s[90:91]
	v_lshl_add_u64 v[98:99], v[94:95], 0, s[6:7]
	v_lshl_add_u64 v[100:101], v[94:95], 0, s[18:19]
	v_lshl_add_u64 v[102:103], v[94:95], 0, s[20:21]
	v_lshl_add_u64 v[104:105], v[94:95], 0, s[26:27]
	v_lshl_add_u64 v[138:139], v[136:137], 0, s[90:91]
	v_lshl_add_u64 v[140:141], v[136:137], 0, s[6:7]
	v_lshl_add_u64 v[142:143], v[136:137], 0, s[18:19]
	v_lshl_add_u64 v[144:145], v[136:137], 0, s[20:21]
	v_lshl_add_u64 v[146:147], v[136:137], 0, s[26:27]
	v_lshl_add_u64 v[150:151], v[148:149], 0, s[90:91]
	v_lshl_add_u64 v[152:153], v[148:149], 0, s[6:7]
	v_lshl_add_u64 v[154:155], v[148:149], 0, s[18:19]
	v_lshl_add_u64 v[156:157], v[148:149], 0, s[20:21]
	v_lshl_add_u64 v[158:159], v[148:149], 0, s[26:27]
	v_lshl_add_u64 v[162:163], v[160:161], 0, s[90:91]
	v_lshl_add_u64 v[164:165], v[160:161], 0, s[6:7]
	v_lshl_add_u64 v[166:167], v[160:161], 0, s[18:19]
	v_lshl_add_u64 v[168:169], v[160:161], 0, s[20:21]
	v_lshl_add_u64 v[170:171], v[160:161], 0, s[26:27]
	v_lshl_add_u64 v[174:175], v[172:173], 0, s[90:91]
	v_lshl_add_u64 v[176:177], v[172:173], 0, s[6:7]
	v_lshl_add_u64 v[178:179], v[172:173], 0, s[18:19]
	s_mov_b64 s[18:19], 0x90000
	s_mov_b64 s[16:17], 0x80000
	v_lshl_add_u64 v[180:181], v[172:173], 0, s[20:21]
	v_lshl_add_u64 v[182:183], v[172:173], 0, s[26:27]
	v_lshl_add_u64 v[184:185], s[10:11], 0, v[4:5]
	v_lshl_add_u64 v[186:187], v[2:3], 0, s[4:5]
	v_lshl_add_u64 v[188:189], s[38:39], 0, v[4:5]
	v_and_b32_e32 v230, 63, v240
	v_lshrrev_b32_e32 v232, 6, v240
	v_lshlrev_b32_e32 v230, 4, v230
	v_readfirstlane_b32 s100, v232
	s_mov_b32 s101, 0
	s_nop 3
	s_lshl_b32 s100, s100, 10
	v_lshl_add_u64 v[232:233], v[72:73], 0, s[100:101]
	s_add_i32 m0, s100, 0xc000
	s_nop 0
	global_load_lds_dwordx4 v[232:233], off
	v_lshl_add_u64 v[232:233], v[74:75], 0, s[100:101]
	s_add_i32 m0, s100, 0xe000
	s_nop 0
	global_load_lds_dwordx4 v[232:233], off
	v_or_b32_e32 v232, v94, v95
	s_nop 0
	v_readfirstlane_b32 s101, v232
	s_nop 3
	s_cmp_eq_u32 s101, 0
	s_mov_b32 s101, 0
	s_cbranch_scc1 .Lmix_nostage_a
	s_mul_i32 s100, s100, 6
	v_lshl_add_u64 v[232:233], v[94:95], 0, s[100:101]
	s_mov_b32 m0, s100
	s_nop 0
	global_load_lds_dwordx4 v[232:233], off
	global_load_lds_dwordx4 v[232:233], off offset:1024
	global_load_lds_dwordx4 v[232:233], off offset:2048
	global_load_lds_dwordx4 v[232:233], off offset:3072
	s_add_i32 s100, s100, 0x1000
	v_lshl_add_u64 v[232:233], v[94:95], 0, s[100:101]
	s_mov_b32 m0, s100
	s_nop 0
	global_load_lds_dwordx4 v[232:233], off
	global_load_lds_dwordx4 v[232:233], off offset:1024
.Lmix_nostage_a:
	s_waitcnt vmcnt(0)
	s_barrier
	s_branch .LBB0_117

; __device__ __forceinline__ float wave_sum(float x) { x = row16_sum(x); x += __shfl_xor(x, 16); x += __shfl_xor(x, 32); return x; }
; template <bool LN>
; __device__ __forceinline__ void ln_row(const void* src, size_t row, int lane, const float* g, const float* bt, f32x4 (&v)[8]) {
;     if (LN) {
;         const h16x4* sp = (const h16x4*)((const h16*)src + row * DM);
; #pragma unroll
;         for (int i = 0; i < 8; ++i) { const h16x4 t = sp[i * 64 + lane]; v[i] = (f32x4){(float)t[0], (float)t[1], (float)t[2], (float)t[3]}; }
;         float s = 0.f;
; #pragma unroll
;         for (int i = 0; i < 8; ++i) s += (v[i][0] + v[i][1]) + (v[i][2] + v[i][3]);
;         const float mean = wave_sum(s) * (1.0f / DM);
.LBB0_117:
	v_cndmask_b32_e64 v0, 0, 1, s[42:43]
	v_cmp_ne_u32_e64 s[38:39], 1, v0
	s_andn2_b64 vcc, exec, s[42:43]
	v_ashrrev_i32_e32 v71, 31, v70
	s_cbranch_vccnz .LBB0_121
	v_and_b32_e32 v0, 0x3ff, v70
	v_mov_b32_e32 v2, v1
	v_mov_b32_e32 v3, v1
	v_cmp_ne_u32_e32 vcc, 0, v0
	v_mov_b32_e32 v0, v1
	v_mov_b64_e32 v[60:61], v[2:3]
	v_mov_b64_e32 v[36:37], v[2:3]
	v_mov_b64_e32 v[32:33], v[2:3]
	v_mov_b64_e32 v[24:25], v[2:3]
	v_mov_b64_e32 v[16:17], v[2:3]
	v_mov_b64_e32 v[12:13], v[2:3]
	v_mov_b64_e32 v[8:9], v[2:3]
	v_mov_b64_e32 v[58:59], v[0:1]
	v_mov_b64_e32 v[34:35], v[0:1]
	v_mov_b64_e32 v[30:31], v[0:1]
	v_mov_b64_e32 v[22:23], v[0:1]
	v_mov_b64_e32 v[14:15], v[0:1]
	v_mov_b64_e32 v[10:11], v[0:1]
	v_mov_b64_e32 v[6:7], v[0:1]
	v_mov_b64_e32 v[4:5], v[2:3]
	v_mov_b64_e32 v[2:3], v[0:1]
	s_and_saveexec_b64 s[22:23], vcc
	s_cbranch_execz .LBB0_120
	v_lshlrev_b64 v[2:3], 15, v[70:71]
	v_lshl_add_u64 v[10:11], v[92:93], 0, v[2:3]
	global_load_dwordx2 v[14:15], v[10:11], off offset:-4096
	global_load_dwordx2 v[16:17], v[10:11], off offset:-3584
	global_load_dwordx2 v[12:13], v[10:11], off offset:-3072
	global_load_dwordx2 v[2:3], v[10:11], off offset:-2560
	global_load_dwordx2 v[4:5], v[10:11], off offset:-2048
	global_load_dwordx2 v[6:7], v[10:11], off offset:-1536
	global_load_dwordx2 v[8:9], v[10:11], off offset:-1024
	s_waitcnt vmcnt(0)
	v_cvt_f32_f16_e32 v18, v14
	global_load_dwordx2 v[10:11], v[10:11], off offset:-512
	v_cvt_f32_f16_sdwa v20, v14 dst_sel:DWORD dst_unused:UNUSED_PAD src0_sel:WORD_1
	v_cvt_f32_f16_e32 v22, v15
	v_cvt_f32_f16_sdwa v24, v15 dst_sel:DWORD dst_unused:UNUSED_PAD src0_sel:WORD_1
	v_cvt_f32_f16_e32 v19, v16
	v_cvt_f32_f16_sdwa v21, v16 dst_sel:DWORD dst_unused:UNUSED_PAD src0_sel:WORD_1
	v_cvt_f32_f16_e32 v23, v17
	v_cvt_f32_f16_sdwa v25, v17 dst_sel:DWORD dst_unused:UNUSED_PAD src0_sel:WORD_1
	v_cvt_f32_f16_e32 v26, v12
	v_cvt_f32_f16_sdwa v28, v12 dst_sel:DWORD dst_unused:UNUSED_PAD src0_sel:WORD_1
	v_cvt_f32_f16_e32 v27, v13
	v_cvt_f32_f16_sdwa v29, v13 dst_sel:DWORD dst_unused:UNUSED_PAD src0_sel:WORD_1
	v_pk_add_f32 v[18:19], v[18:19], v[20:21]
	v_pk_add_f32 v[20:21], v[22:23], v[24:25]
	v_cvt_f32_f16_e32 v0, v2
	v_cvt_f32_f16_sdwa v32, v2 dst_sel:DWORD dst_unused:UNUSED_PAD src0_sel:WORD_1
	v_cvt_f32_f16_e32 v34, v3
	v_cvt_f32_f16_sdwa v40, v3 dst_sel:DWORD dst_unused:UNUSED_PAD src0_sel:WORD_1
	v_cvt_f32_f16_sdwa v42, v4 dst_sel:DWORD dst_unused:UNUSED_PAD src0_sel:WORD_1
	v_pk_add_f32 v[18:19], v[18:19], v[20:21]
	v_cvt_f32_f16_e32 v31, v4
	v_cvt_f32_f16_e32 v33, v5
	v_cvt_f32_f16_sdwa v35, v5 dst_sel:DWORD dst_unused:UNUSED_PAD src0_sel:WORD_1
	v_add_f32_e32 v18, 0, v18
	v_cvt_f32_f16_e32 v36, v6
	v_cvt_f32_f16_sdwa v38, v6 dst_sel:DWORD dst_unused:UNUSED_PAD src0_sel:WORD_1
	v_cvt_f32_f16_e32 v37, v7
	v_cvt_f32_f16_sdwa v39, v7 dst_sel:DWORD dst_unused:UNUSED_PAD src0_sel:WORD_1
	v_add_f32_e32 v30, v18, v19
	v_pk_add_f32 v[18:19], v[26:27], v[28:29]
	v_cvt_f32_f16_e32 v44, v8
	v_pk_add_f32 v[18:19], v[18:19], v[18:19] op_sel:[0,1] op_sel_hi:[1,0]
	v_cvt_f32_f16_sdwa v45, v8 dst_sel:DWORD dst_unused:UNUSED_PAD src0_sel:WORD_1
	v_cvt_f32_f16_e32 v46, v9
	v_cvt_f32_f16_sdwa v47, v9 dst_sel:DWORD dst_unused:UNUSED_PAD src0_sel:WORD_1
	v_add_f32_e32 v32, v32, v0
	v_add_f32_e32 v34, v40, v34
	v_mov_b32_e32 v19, v42
	v_pk_add_f32 v[18:19], v[30:31], v[18:19]
	v_pk_add_f32 v[20:21], v[32:33], v[34:35]
	v_add_f32_e32 v40, v45, v44
	v_pk_add_f32 v[18:19], v[18:19], v[20:21]
	v_pk_add_f32 v[20:21], v[36:37], v[38:39]
	v_pk_add_f32 v[18:19], v[18:19], v[18:19] op_sel:[0,1] op_sel_hi:[1,0]
	v_pk_add_f32 v[20:21], v[20:21], v[20:21] op_sel:[0,1] op_sel_hi:[1,0]
	v_add_f32_e32 v42, v47, v46
	s_waitcnt vmcnt(0)
	v_cvt_f32_f16_e32 v48, v10
	v_cvt_f32_f16_sdwa v49, v10 dst_sel:DWORD dst_unused:UNUSED_PAD src0_sel:WORD_1
	v_cvt_f32_f16_e32 v41, v11
	v_cvt_f32_f16_sdwa v43, v11 dst_sel:DWORD dst_unused:UNUSED_PAD src0_sel:WORD_1
	v_mov_b32_e32 v19, v48
	v_mov_b32_e32 v21, v49
	v_pk_add_f32 v[18:19], v[18:19], v[20:21]
	v_pk_add_f32 v[20:21], v[40:41], v[42:43]
	s_nop 0
	v_pk_add_f32 v[18:19], v[18:19], v[20:21]
	s_nop 0
	v_add_f32_e32 v0, v18, v19
	v_and_b32_e32 v19, 64, v246
	v_add_u32_e32 v19, 64, v19
	v_add_f32_dpp v0, v0, v0 quad_perm:[1,0,3,2] row_mask:0xf bank_mask:0xf bound_ctrl:1
	s_nop 1
	v_add_f32_dpp v0, v0, v0 quad_perm:[2,3,0,1] row_mask:0xf bank_mask:0xf bound_ctrl:1
	s_nop 1
	v_add_f32_dpp v0, v0, v0 row_half_mirror row_mask:0xf bank_mask:0xf bound_ctrl:1
	s_nop 1
	v_add_f32_dpp v18, v0, v0 row_mirror row_mask:0xf bank_mask:0xf bound_ctrl:1
	v_xor_b32_e32 v0, 16, v246
	v_cmp_lt_i32_e32 vcc, v0, v19
	s_nop 1
	v_cndmask_b32_e32 v0, v246, v0, vcc
	v_lshlrev_b32_e32 v0, 2, v0
	ds_bpermute_b32 v20, v0, v18
	s_waitcnt lgkmcnt(0)
	v_add_f32_e32 v18, v18, v20
	v_xor_b32_e32 v20, 32, v246
	v_cmp_lt_i32_e32 vcc, v20, v19
	s_nop 1
	v_cndmask_b32_e32 v19, v246, v20, vcc
	v_lshlrev_b32_e32 v46, 2, v19
	ds_bpermute_b32 v19, v46, v18
	s_waitcnt lgkmcnt(0)
; __device__ __forceinline__ float wave_sum(float x) { x = row16_sum(x); x += __shfl_xor(x, 16); x += __shfl_xor(x, 32); return x; }
; template <bool LN>
; __device__ __forceinline__ void ln_row(const void* src, size_t row, int lane, const float* g, const float* bt, f32x4 (&v)[8]) {
;     ...
;         float q = 0.f;
; #pragma unroll
;         for (int i = 0; i < 8; ++i) { v[i] = v[i] - mean; q += (v[i][0] * v[i][0] + v[i][1] * v[i][1]) + (v[i][2] * v[i][2] + v[i][3] * v[i][3]); }
;         const float rstd = rsqrtf(wave_sum(q) * (1.0f / DM) + 1e-5f);
	v_add_f32_e32 v40, v18, v19
	v_fma_mix_f32 v19, v40, s59, v15 op_sel:[0,0,1] op_sel_hi:[0,0,1]
	v_fma_mix_f32 v18, v40, s59, v15 op_sel_hi:[0,0,1]
	v_fma_mix_f32 v23, v40, s59, v14 op_sel:[0,0,1] op_sel_hi:[0,0,1]
	v_fma_mix_f32 v22, v40, s59, v14 op_sel_hi:[0,0,1]
	v_fma_mix_f32 v15, v40, s59, v17 op_sel:[0,0,1] op_sel_hi:[0,0,1]
	v_fma_mix_f32 v14, v40, s59, v17 op_sel_hi:[0,0,1]
	v_fma_mix_f32 v17, v40, s59, v16 op_sel:[0,0,1] op_sel_hi:[0,0,1]
	v_fma_mix_f32 v16, v40, s59, v16 op_sel_hi:[0,0,1]
	v_mov_b32_e32 v24, v23
	v_mov_b32_e32 v25, v17
	v_mov_b32_e32 v20, v22
	v_mov_b32_e32 v21, v16
	v_pk_mul_f32 v[24:25], v[24:25], v[24:25]
	v_mov_b32_e32 v26, v19
	v_mov_b32_e32 v27, v15
	v_pk_fma_f32 v[20:21], v[20:21], v[20:21], v[24:25]
	v_mov_b32_e32 v24, v18
	v_mov_b32_e32 v25, v14
	v_pk_mul_f32 v[26:27], v[26:27], v[26:27]
	v_fma_mix_f32 v29, v40, s59, v12 op_sel:[0,0,1] op_sel_hi:[0,0,1]
	v_pk_fma_f32 v[24:25], v[24:25], v[24:25], v[26:27]
	v_fma_mix_f32 v28, v40, s59, v12 op_sel_hi:[0,0,1]
	v_fma_mix_f32 v33, v40, s59, v13 op_sel:[0,0,1] op_sel_hi:[0,0,1]
	v_fma_mix_f32 v32, v40, s59, v13 op_sel_hi:[0,0,1]
	v_pk_add_f32 v[20:21], v[20:21], v[24:25]
	v_pk_mul_f32 v[12:13], v[32:33], v[32:33]
	v_pk_mul_f32 v[24:25], v[28:29], v[28:29]
	v_fma_mix_f32 v31, v40, s59, v3 op_sel:[0,0,1] op_sel_hi:[0,0,1]
	v_pk_mov_b32 v[26:27], v[24:25], v[12:13] op_sel:[1,0]
	v_mov_b32_e32 v25, v13
	v_pk_add_f32 v[12:13], v[26:27], v[24:25]
	v_fma_mix_f32 v24, v40, s59, v2 op_sel_hi:[0,0,1]
	v_fma_mix_f32 v25, v40, s59, v2 op_sel:[0,0,1] op_sel_hi:[0,0,1]
	v_mul_f32_e32 v2, v24, v24
	v_fma_mix_f32 v30, v40, s59, v3 op_sel_hi:[0,0,1]
	v_pk_fma_f32 v[2:3], v[24:25], v[24:25], v[2:3] op_sel_hi:[1,1,0]
	v_pk_add_f32 v[20:21], v[20:21], v[20:21] op_sel_hi:[0,1]
	v_mul_f32_e32 v2, v30, v30
	v_pk_add_f32 v[12:13], v[12:13], v[12:13] op_sel_hi:[0,1]
	v_pk_fma_f32 v[26:27], v[30:31], v[30:31], v[2:3] op_sel_hi:[1,1,0]
	v_fma_mix_f32 v43, v40, s59, v5 op_sel:[0,0,1] op_sel_hi:[0,0,1]
	v_fma_mix_f32 v42, v40, s59, v5 op_sel_hi:[0,0,1]
	v_fma_mix_f32 v45, v40, s59, v4 op_sel:[0,0,1] op_sel_hi:[0,0,1]
	v_fma_mix_f32 v44, v40, s59, v4 op_sel_hi:[0,0,1]
	v_mul_f32_e32 v2, v44, v44
	v_mul_f32_e32 v26, v45, v45
	v_mul_f32_e32 v12, v42, v42
	v_mul_f32_e32 v20, v43, v43
	v_pk_add_f32 v[2:3], v[2:3], v[26:27]
	v_pk_add_f32 v[4:5], v[12:13], v[20:21]
	v_fma_mix_f32 v35, v40, s59, v6 op_sel:[0,0,1] op_sel_hi:[0,0,1]
	v_pk_add_f32 v[2:3], v[2:3], v[4:5]
	v_fma_mix_f32 v34, v40, s59, v6 op_sel_hi:[0,0,1]
	v_fma_mix_f32 v37, v40, s59, v7 op_sel:[0,0,1] op_sel_hi:[0,0,1]
	v_fma_mix_f32 v36, v40, s59, v7 op_sel_hi:[0,0,1]
	v_pk_add_f32 v[2:3], v[2:3], v[2:3] op_sel_hi:[0,1]
	v_pk_mul_f32 v[4:5], v[36:37], v[36:37]
	v_pk_mul_f32 v[6:7], v[34:35], v[34:35]
	v_fma_mix_f32 v20, v40, s59, v8 op_sel_hi:[0,0,1]
	v_pk_mov_b32 v[12:13], v[6:7], v[4:5] op_sel:[1,0]
	v_mov_b32_e32 v7, v5
	v_fma_mix_f32 v21, v40, s59, v8 op_sel:[0,0,1] op_sel_hi:[0,0,1]
	v_fma_mix_f32 v26, v40, s59, v9 op_sel_hi:[0,0,1]
	v_mul_f32_e32 v2, v20, v20
	v_pk_add_f32 v[4:5], v[12:13], v[6:7]
	v_fma_mix_f32 v27, v40, s59, v9 op_sel:[0,0,1] op_sel_hi:[0,0,1]
	v_pk_fma_f32 v[6:7], v[20:21], v[20:21], v[2:3] op_sel_hi:[1,1,0]
	v_mul_f32_e32 v2, v26, v26
	v_pk_add_f32 v[4:5], v[4:5], v[4:5] op_sel_hi:[0,1]
	v_pk_fma_f32 v[8:9], v[26:27], v[26:27], v[2:3] op_sel_hi:[1,1,0]
	v_fma_mix_f32 v39, v40, s59, v11 op_sel:[0,0,1] op_sel_hi:[0,0,1]
	v_fma_mix_f32 v38, v40, s59, v11 op_sel_hi:[0,0,1]
	v_fma_mix_f32 v41, v40, s59, v10 op_sel:[0,0,1] op_sel_hi:[0,0,1]
	v_fma_mix_f32 v40, v40, s59, v10 op_sel_hi:[0,0,1]
	v_mul_f32_e32 v6, v40, v40
	v_mul_f32_e32 v8, v41, v41
	v_mul_f32_e32 v4, v38, v38
	v_mul_f32_e32 v2, v39, v39
	v_pk_add_f32 v[6:7], v[6:7], v[8:9]
	v_pk_add_f32 v[2:3], v[4:5], v[2:3]
	s_nop 0
	v_pk_add_f32 v[2:3], v[6:7], v[2:3]
	s_nop 0
	v_add_f32_e32 v2, v2, v3
	s_nop 1
	v_add_f32_dpp v2, v2, v2 quad_perm:[1,0,3,2] row_mask:0xf bank_mask:0xf bound_ctrl:1
	s_nop 1
	v_add_f32_dpp v2, v2, v2 quad_perm:[2,3,0,1] row_mask:0xf bank_mask:0xf bound_ctrl:1
	s_nop 1
	v_add_f32_dpp v2, v2, v2 row_half_mirror row_mask:0xf bank_mask:0xf bound_ctrl:1
	s_nop 1
	v_add_f32_dpp v2, v2, v2 row_mirror row_mask:0xf bank_mask:0xf bound_ctrl:1
	ds_bpermute_b32 v0, v0, v2
	s_waitcnt lgkmcnt(0)
; __device__ __forceinline__ float wave_sum(float x) { x = row16_sum(x); x += __shfl_xor(x, 16); x += __shfl_xor(x, 32); return x; }
; template <bool LN>
; __device__ __forceinline__ void ln_row(const void* src, size_t row, int lane, const float* g, const float* bt, f32x4 (&v)[8]) {
;     ...
;         const float rstd = rsqrtf(wave_sum(q) * (1.0f / DM) + 1e-5f);
; #pragma unroll
;         for (int i = 0; i < 8; ++i) { const f32x4 gg = ((const f32x4*)g)[i * 64 + lane], bb = ((const f32x4*)bt)[i * 64 + lane]; v[i] = v[i] * rstd * gg + bb; }
	v_add_f32_e32 v0, v2, v0
	ds_bpermute_b32 v2, v46, v0
	s_waitcnt lgkmcnt(0)
	v_add_f32_e32 v0, v0, v2
	v_fmamk_f32 v0, v0, 0x3a000000, v242
	v_cmp_gt_f32_e32 vcc, s28, v0
	v_mul_f32_e32 v2, 0x4b800000, v0
	s_nop 0
	v_cndmask_b32_e32 v0, v0, v2, vcc
	v_rsq_f32_e32 v0, v0
	s_nop 0
	v_mul_f32_e32 v2, 0x45800000, v0
	v_cndmask_b32_e32 v0, v0, v2, vcc
	ds_read_b128 v[2:5], v230 offset:49152
	ds_read_b128 v[6:9], v230 offset:57344
	v_pk_mul_f32 v[10:11], v[22:23], v[0:1] op_sel_hi:[1,0]
	v_pk_mul_f32 v[12:13], v[18:19], v[0:1] op_sel_hi:[1,0]
	v_pk_mul_f32 v[16:17], v[16:17], v[0:1] op_sel_hi:[1,0]
	v_pk_mul_f32 v[14:15], v[14:15], v[0:1] op_sel_hi:[1,0]
	v_pk_mul_f32 v[18:19], v[28:29], v[0:1] op_sel_hi:[1,0]
	v_pk_mul_f32 v[22:23], v[32:33], v[0:1] op_sel_hi:[1,0]
	v_pk_mul_f32 v[32:33], v[42:43], v[0:1] op_sel_hi:[1,0]
	v_pk_mul_f32 v[40:41], v[40:41], v[0:1] op_sel_hi:[1,0]
	v_pk_mul_f32 v[38:39], v[38:39], v[0:1] op_sel_hi:[1,0]
	s_waitcnt lgkmcnt(0)
	v_pk_fma_f32 v[4:5], v[4:5], v[12:13], v[8:9]
	v_pk_fma_f32 v[2:3], v[2:3], v[10:11], v[6:7]
	ds_read_b128 v[6:9], v230 offset:50176
	ds_read_b128 v[10:13], v230 offset:58368
	s_waitcnt lgkmcnt(0)
	v_pk_fma_f32 v[8:9], v[8:9], v[14:15], v[12:13]
	v_pk_fma_f32 v[6:7], v[6:7], v[16:17], v[10:11]
	ds_read_b128 v[10:13], v230 offset:51200
	ds_read_b128 v[14:17], v230 offset:59392
	s_waitcnt lgkmcnt(0)
	v_pk_fma_f32 v[12:13], v[12:13], v[22:23], v[16:17]
	v_pk_fma_f32 v[10:11], v[10:11], v[18:19], v[14:15]
	ds_read_b128 v[14:17], v230 offset:52224
	ds_read_b128 v[46:49], v230 offset:60416
	v_pk_mul_f32 v[22:23], v[30:31], v[0:1] op_sel_hi:[1,0]
	v_pk_mul_f32 v[18:19], v[24:25], v[0:1] op_sel_hi:[1,0]
	s_waitcnt lgkmcnt(0)
	v_pk_fma_f32 v[16:17], v[16:17], v[22:23], v[48:49]
	ds_read_b128 v[22:25], v230 offset:53248
	ds_read_b128 v[28:31], v230 offset:61440
	v_pk_fma_f32 v[14:15], v[14:15], v[18:19], v[46:47]
	v_pk_mul_f32 v[18:19], v[44:45], v[0:1] op_sel_hi:[1,0]
	s_waitcnt lgkmcnt(0)
	v_pk_fma_f32 v[24:25], v[24:25], v[32:33], v[30:31]
	v_pk_fma_f32 v[22:23], v[22:23], v[18:19], v[28:29]
	ds_read_b128 v[28:31], v230 offset:54272
	ds_read_b128 v[42:45], v230 offset:62464
	v_pk_mul_f32 v[18:19], v[34:35], v[0:1] op_sel_hi:[1,0]
	v_pk_mul_f32 v[32:33], v[36:37], v[0:1] op_sel_hi:[1,0]
	s_waitcnt lgkmcnt(0)
	v_pk_fma_f32 v[32:33], v[30:31], v[32:33], v[44:45]
	v_pk_fma_f32 v[30:31], v[28:29], v[18:19], v[42:43]
	ds_read_b128 v[34:37], v230 offset:55296
	ds_read_b128 v[42:45], v230 offset:63488
	v_pk_mul_f32 v[18:19], v[20:21], v[0:1] op_sel_hi:[1,0]
	v_pk_mul_f32 v[20:21], v[26:27], v[0:1] op_sel_hi:[1,0]
	s_waitcnt lgkmcnt(0)
	v_pk_fma_f32 v[34:35], v[34:35], v[18:19], v[42:43]
	v_pk_fma_f32 v[36:37], v[36:37], v[20:21], v[44:45]
	ds_read_b128 v[18:21], v230 offset:56320
	ds_read_b128 v[26:29], v230 offset:64512
	s_waitcnt lgkmcnt(0)
	v_pk_fma_f32 v[60:61], v[20:21], v[38:39], v[28:29]
	v_pk_fma_f32 v[58:59], v[18:19], v[40:41], v[26:27]

; __device__ __forceinline__ float wave_sum(float x) { x = row16_sum(x); x += __shfl_xor(x, 16); x += __shfl_xor(x, 32); return x; }
; __device__ __forceinline__ void ln_apply16(const h16x4 (&t)[8], int lane, const float* g, const float* bt, f32x4 (&v)[8]) {
; #pragma unroll
;     for (int i = 0; i < 8; ++i) v[i] = (f32x4){(float)t[i][0], (float)t[i][1], (float)t[i][2], (float)t[i][3]};
;     float s = 0.f;
; #pragma unroll
;     for (int i = 0; i < 8; ++i) s += (v[i][0] + v[i][1]) + (v[i][2] + v[i][3]);
;     const float mean = wave_sum(s) * (1.0f / DM);
; template <bool LN>
; __device__ __forceinline__ void ln_phase(const void* src, const float* g, const float* bt, float* xout, h16* xh, const float* mu, h16* mix) {
;     ...
;         for (int r = 0; r < 8; ++r) {
;             const size_t row = t0 + r;
;             asm volatile("" ::: "memory");
;             if (LN) {
;                 ln_load16(src, t0 + (r < 7 ? r + 1 : 7), lane, rawn);
;                 ln_apply16(raw, lane, g, bt, cur);
; #pragma unroll
;                 for (int i = 0; i < 8; ++i) raw[i] = rawn[i];
.LBB0_124:
	v_mov_b64_e32 v[64:65], v[4:5]
	v_mov_b64_e32 v[56:57], v[8:9]
	v_mov_b64_e32 v[52:53], v[12:13]
	v_mov_b64_e32 v[48:49], v[16:17]
	v_mov_b64_e32 v[44:45], v[24:25]
	v_mov_b64_e32 v[40:41], v[32:33]
	v_mov_b64_e32 v[26:27], v[34:35]
	v_mov_b64_e32 v[18:19], v[58:59]
	v_mov_b64_e32 v[62:63], v[2:3]
	v_mov_b64_e32 v[54:55], v[6:7]
	v_mov_b64_e32 v[50:51], v[10:11]
	v_mov_b64_e32 v[46:47], v[14:15]
	v_mov_b64_e32 v[42:43], v[22:23]
	v_mov_b64_e32 v[38:39], v[30:31]
	v_mov_b64_e32 v[28:29], v[36:37]
	v_mov_b64_e32 v[20:21], v[60:61]
	s_cmpk_lg_i32 s22, 0x7000
	s_cselect_b32 s24, s26, 7
	v_lshl_add_u64 v[2:3], v[190:191], 0, s[24:25]
	v_lshlrev_b64 v[2:3], 12, v[2:3]
	s_waitcnt vmcnt(0)
	v_mov_b64_e32 v[4:5], v[194:195]
	v_mov_b64_e32 v[8:9], v[196:197]
	v_lshl_add_u64 v[2:3], v[92:93], 0, v[2:3]
	v_mov_b64_e32 v[14:15], v[198:199]
	v_mov_b64_e32 v[22:23], v[200:201]
	v_mov_b64_e32 v[24:25], v[202:203]
	v_mov_b64_e32 v[34:35], v[204:205]
	v_mov_b64_e32 v[60:61], v[206:207]
	v_mov_b64_e32 v[58:59], v[220:221]
	global_load_dwordx2 v[194:195], v[2:3], off
	global_load_dwordx2 v[196:197], v[2:3], off offset:512
	global_load_dwordx2 v[198:199], v[2:3], off offset:1024
	global_load_dwordx2 v[200:201], v[2:3], off offset:1536
	global_load_dwordx2 v[202:203], v[2:3], off offset:2048
	global_load_dwordx2 v[204:205], v[2:3], off offset:2560
	global_load_dwordx2 v[206:207], v[2:3], off offset:3072
	global_load_dwordx2 v[220:221], v[2:3], off offset:3584
	v_cvt_f32_f16_sdwa v3, v4 dst_sel:DWORD dst_unused:UNUSED_PAD src0_sel:WORD_1
	v_cvt_f32_f16_e32 v7, v4
	v_cvt_f32_f16_sdwa v11, v5 dst_sel:DWORD dst_unused:UNUSED_PAD src0_sel:WORD_1
	v_cvt_f32_f16_e32 v13, v5
	v_cvt_f32_f16_sdwa v2, v8 dst_sel:DWORD dst_unused:UNUSED_PAD src0_sel:WORD_1
	v_cvt_f32_f16_e32 v6, v8
	v_cvt_f32_f16_sdwa v10, v9 dst_sel:DWORD dst_unused:UNUSED_PAD src0_sel:WORD_1
	v_cvt_f32_f16_e32 v12, v9
	v_cvt_f32_f16_sdwa v16, v14 dst_sel:DWORD dst_unused:UNUSED_PAD src0_sel:WORD_1
	v_cvt_f32_f16_e32 v30, v14
	v_cvt_f32_f16_sdwa v17, v15 dst_sel:DWORD dst_unused:UNUSED_PAD src0_sel:WORD_1
	v_cvt_f32_f16_e32 v31, v15
	v_pk_add_f32 v[2:3], v[6:7], v[2:3]
	v_pk_add_f32 v[6:7], v[12:13], v[10:11]
	v_cvt_f32_f16_sdwa v0, v22 dst_sel:DWORD dst_unused:UNUSED_PAD src0_sel:WORD_1
	v_cvt_f32_f16_e32 v33, v22
	v_cvt_f32_f16_sdwa v69, v23 dst_sel:DWORD dst_unused:UNUSED_PAD src0_sel:WORD_1
	v_cvt_f32_f16_e32 v71, v23
	v_pk_add_f32 v[2:3], v[2:3], v[6:7]
	v_cvt_f32_f16_sdwa v32, v24 dst_sel:DWORD dst_unused:UNUSED_PAD src0_sel:WORD_1
	v_cvt_f32_f16_e32 v36, v24
	v_cvt_f32_f16_sdwa v66, v25 dst_sel:DWORD dst_unused:UNUSED_PAD src0_sel:WORD_1
	v_cvt_f32_f16_e32 v68, v25
	v_add_f32_e32 v3, 0, v3
	v_cvt_f32_f16_sdwa v212, v34 dst_sel:DWORD dst_unused:UNUSED_PAD src0_sel:WORD_1
	v_cvt_f32_f16_e32 v214, v34
	v_cvt_f32_f16_sdwa v213, v35 dst_sel:DWORD dst_unused:UNUSED_PAD src0_sel:WORD_1
	v_cvt_f32_f16_e32 v215, v35
	v_add_f32_e32 v67, v2, v3
	v_pk_add_f32 v[2:3], v[30:31], v[16:17]
	v_cvt_f32_f16_sdwa v217, v60 dst_sel:DWORD dst_unused:UNUSED_PAD src0_sel:WORD_1
	v_pk_add_f32 v[2:3], v[2:3], v[2:3] op_sel_hi:[0,1]
	v_cvt_f32_f16_e32 v223, v60
	v_cvt_f32_f16_sdwa v225, v61 dst_sel:DWORD dst_unused:UNUSED_PAD src0_sel:WORD_1
	v_cvt_f32_f16_e32 v227, v61
	v_add_f32_e32 v37, v33, v0
	v_add_f32_e32 v33, v71, v69
	v_mov_b32_e32 v69, v3
	v_cvt_f32_f16_sdwa v216, v58 dst_sel:DWORD dst_unused:UNUSED_PAD src0_sel:WORD_1
	v_cvt_f32_f16_e32 v222, v58
	v_cvt_f32_f16_sdwa v224, v59 dst_sel:DWORD dst_unused:UNUSED_PAD src0_sel:WORD_1
	v_cvt_f32_f16_e32 v226, v59
	v_pk_add_f32 v[6:7], v[36:37], v[32:33]
	v_pk_add_f32 v[2:3], v[68:69], v[66:67]
	v_add_f32_e32 v223, v223, v217
	v_pk_add_f32 v[2:3], v[6:7], v[2:3]
	v_pk_add_f32 v[6:7], v[214:215], v[212:213]
	v_pk_add_f32 v[2:3], v[2:3], v[2:3] op_sel_hi:[0,1]
	v_pk_add_f32 v[6:7], v[6:7], v[6:7] op_sel_hi:[0,1]
	v_add_f32_e32 v217, v227, v225
	v_mov_b32_e32 v227, v7
	v_mov_b32_e32 v225, v3
	v_pk_add_f32 v[10:11], v[222:223], v[216:217]
	v_pk_add_f32 v[2:3], v[226:227], v[224:225]
	s_nop 0
	v_pk_add_f32 v[2:3], v[10:11], v[2:3]
	s_nop 0
	v_add_f32_e32 v0, v2, v3
	v_and_b32_e32 v3, 64, v246
	v_xor_b32_e32 v2, 16, v246
	v_add_f32_dpp v0, v0, v0 quad_perm:[1,0,3,2] row_mask:0xf bank_mask:0xf bound_ctrl:1
	v_add_u32_e32 v3, 64, v3
	v_cmp_lt_i32_e32 vcc, v2, v3
	v_add_f32_dpp v0, v0, v0 quad_perm:[2,3,0,1] row_mask:0xf bank_mask:0xf bound_ctrl:1
	s_nop 0
	v_cndmask_b32_e32 v2, v246, v2, vcc
	v_add_f32_dpp v0, v0, v0 row_half_mirror row_mask:0xf bank_mask:0xf bound_ctrl:1
	v_lshlrev_b32_e32 v71, 2, v2
	s_nop 0
	v_add_f32_dpp v0, v0, v0 row_mirror row_mask:0xf bank_mask:0xf bound_ctrl:1
	ds_bpermute_b32 v2, v71, v0
	s_waitcnt lgkmcnt(0)
	v_add_f32_e32 v0, v0, v2
	v_xor_b32_e32 v2, 32, v246
	v_cmp_lt_i32_e32 vcc, v2, v3
	s_nop 1
	v_cndmask_b32_e32 v2, v246, v2, vcc
	v_lshlrev_b32_e32 v214, 2, v2
	ds_bpermute_b32 v2, v214, v0
	s_waitcnt lgkmcnt(0)
; __device__ __forceinline__ float wave_sum(float x) { x = row16_sum(x); x += __shfl_xor(x, 16); x += __shfl_xor(x, 32); return x; }
; __device__ __forceinline__ void ln_apply16(const h16x4 (&t)[8], int lane, const float* g, const float* bt, f32x4 (&v)[8]) {
;     ...
;     float q = 0.f;
; #pragma unroll
;     for (int i = 0; i < 8; ++i) { v[i] = v[i] - mean; q += (v[i][0] * v[i][0] + v[i][1] * v[i][1]) + (v[i][2] * v[i][2] + v[i][3] * v[i][3]); }
;     const float rstd = rsqrtf(wave_sum(q) * (1.0f / DM) + 1e-5f);
	v_add_f32_e32 v215, v0, v2
	v_fma_mix_f32 v3, v215, s59, v5 op_sel:[0,0,1] op_sel_hi:[0,0,1]
	v_fma_mix_f32 v2, v215, s59, v5 op_sel_hi:[0,0,1]
	v_fma_mix_f32 v5, v215, s59, v4 op_sel:[0,0,1] op_sel_hi:[0,0,1]
	v_fma_mix_f32 v7, v215, s59, v9 op_sel:[0,0,1] op_sel_hi:[0,0,1]
	v_fma_mix_f32 v6, v215, s59, v9 op_sel_hi:[0,0,1]
	v_fma_mix_f32 v9, v215, s59, v8 op_sel:[0,0,1] op_sel_hi:[0,0,1]
	v_fma_mix_f32 v4, v215, s59, v4 op_sel_hi:[0,0,1]
	v_fma_mix_f32 v8, v215, s59, v8 op_sel_hi:[0,0,1]
	v_mov_b32_e32 v12, v5
	v_mov_b32_e32 v13, v9
	v_mov_b32_e32 v10, v4
	v_mov_b32_e32 v11, v8
	v_pk_mul_f32 v[12:13], v[12:13], v[12:13]
	v_mov_b32_e32 v16, v3
	v_mov_b32_e32 v17, v7
	v_pk_fma_f32 v[10:11], v[10:11], v[10:11], v[12:13]
	v_mov_b32_e32 v12, v2
	v_mov_b32_e32 v13, v6
	v_pk_mul_f32 v[16:17], v[16:17], v[16:17]
	v_fma_mix_f32 v223, v215, s59, v59 op_sel:[0,0,1] op_sel_hi:[0,0,1]
	v_pk_fma_f32 v[12:13], v[12:13], v[12:13], v[16:17]
	v_fma_mix_f32 v222, v215, s59, v59 op_sel_hi:[0,0,1]
	v_pk_add_f32 v[10:11], v[10:11], v[12:13]
	v_fma_mix_f32 v13, v215, s59, v15 op_sel:[0,0,1] op_sel_hi:[0,0,1]
	v_pk_add_f32 v[30:31], v[10:11], v[10:11] op_sel_hi:[0,1]
	v_fma_mix_f32 v11, v215, s59, v14 op_sel:[0,0,1] op_sel_hi:[0,0,1]
	v_fma_mix_f32 v10, v215, s59, v14 op_sel_hi:[0,0,1]
	v_fma_mix_f32 v12, v215, s59, v15 op_sel_hi:[0,0,1]
	v_pk_mul_f32 v[14:15], v[12:13], v[12:13]
	v_pk_mul_f32 v[16:17], v[10:11], v[10:11]
	v_fma_mix_f32 v225, v215, s59, v58 op_sel:[0,0,1] op_sel_hi:[0,0,1]
	v_pk_mov_b32 v[32:33], v[16:17], v[14:15] op_sel:[1,0]
	v_mov_b32_e32 v17, v15
	v_pk_add_f32 v[14:15], v[32:33], v[16:17]
	v_fma_mix_f32 v16, v215, s59, v23 op_sel_hi:[0,0,1]
	v_pk_add_f32 v[32:33], v[14:15], v[14:15] op_sel_hi:[0,1]
	v_fma_mix_f32 v14, v215, s59, v22 op_sel_hi:[0,0,1]
	v_fma_mix_f32 v15, v215, s59, v22 op_sel:[0,0,1] op_sel_hi:[0,0,1]
	v_mul_f32_e32 v0, v14, v14
	v_fma_mix_f32 v17, v215, s59, v23 op_sel:[0,0,1] op_sel_hi:[0,0,1]
	v_pk_fma_f32 v[36:37], v[14:15], v[14:15], v[0:1] op_sel_hi:[1,1,0]
	v_mul_f32_e32 v0, v16, v16
	v_pk_fma_f32 v[66:67], v[16:17], v[16:17], v[0:1] op_sel_hi:[1,1,0]
	v_fma_mix_f32 v23, v215, s59, v25 op_sel:[0,0,1] op_sel_hi:[0,0,1]
	v_fma_mix_f32 v22, v215, s59, v25 op_sel_hi:[0,0,1]
	v_fma_mix_f32 v25, v215, s59, v24 op_sel:[0,0,1] op_sel_hi:[0,0,1]
	v_fma_mix_f32 v24, v215, s59, v24 op_sel_hi:[0,0,1]
	v_mul_f32_e32 v36, v24, v24
	v_mul_f32_e32 v66, v25, v25
	v_mul_f32_e32 v32, v22, v22
	v_mul_f32_e32 v30, v23, v23
	v_pk_add_f32 v[36:37], v[36:37], v[66:67]
	v_pk_add_f32 v[30:31], v[32:33], v[30:31]
	v_fma_mix_f32 v33, v215, s59, v35 op_sel:[0,0,1] op_sel_hi:[0,0,1]
	v_pk_add_f32 v[30:31], v[36:37], v[30:31]
	v_fma_mix_f32 v32, v215, s59, v35 op_sel_hi:[0,0,1]
	v_pk_add_f32 v[66:67], v[30:31], v[30:31] op_sel_hi:[0,1]
	v_fma_mix_f32 v31, v215, s59, v34 op_sel:[0,0,1] op_sel_hi:[0,0,1]
	v_fma_mix_f32 v30, v215, s59, v34 op_sel_hi:[0,0,1]
	v_pk_mul_f32 v[34:35], v[32:33], v[32:33]
	v_pk_mul_f32 v[36:37], v[30:31], v[30:31]
	v_fma_mix_f32 v224, v215, s59, v58 op_sel_hi:[0,0,1]
	v_pk_mov_b32 v[68:69], v[36:37], v[34:35] op_sel:[1,0]
	v_mov_b32_e32 v37, v35
	v_pk_add_f32 v[34:35], v[68:69], v[36:37]
	v_fma_mix_f32 v36, v215, s59, v61 op_sel_hi:[0,0,1]
	v_pk_add_f32 v[68:69], v[34:35], v[34:35] op_sel_hi:[0,1]
	v_fma_mix_f32 v34, v215, s59, v60 op_sel_hi:[0,0,1]
	v_fma_mix_f32 v35, v215, s59, v60 op_sel:[0,0,1] op_sel_hi:[0,0,1]
	v_mul_f32_e32 v0, v34, v34
	v_fma_mix_f32 v37, v215, s59, v61 op_sel:[0,0,1] op_sel_hi:[0,0,1]
	v_pk_fma_f32 v[60:61], v[34:35], v[34:35], v[0:1] op_sel_hi:[1,1,0]
	v_mul_f32_e32 v0, v36, v36
	v_pk_fma_f32 v[212:213], v[36:37], v[36:37], v[0:1] op_sel_hi:[1,1,0]
	v_mul_f32_e32 v60, v224, v224
	v_mul_f32_e32 v212, v225, v225
	v_mul_f32_e32 v68, v222, v222
	v_mul_f32_e32 v66, v223, v223
	v_pk_add_f32 v[58:59], v[60:61], v[212:213]
	v_pk_add_f32 v[60:61], v[68:69], v[66:67]
	s_nop 0
	v_pk_add_f32 v[58:59], v[58:59], v[60:61]
	s_nop 0
	v_add_f32_e32 v0, v58, v59
	s_nop 1
	v_add_f32_dpp v0, v0, v0 quad_perm:[1,0,3,2] row_mask:0xf bank_mask:0xf bound_ctrl:1
	s_nop 1
	v_add_f32_dpp v0, v0, v0 quad_perm:[2,3,0,1] row_mask:0xf bank_mask:0xf bound_ctrl:1
	s_nop 1
	v_add_f32_dpp v0, v0, v0 row_half_mirror row_mask:0xf bank_mask:0xf bound_ctrl:1
	s_nop 1
	v_add_f32_dpp v0, v0, v0 row_mirror row_mask:0xf bank_mask:0xf bound_ctrl:1
	ds_bpermute_b32 v58, v71, v0
	s_waitcnt lgkmcnt(0)
; __device__ __forceinline__ float wave_sum(float x) { x = row16_sum(x); x += __shfl_xor(x, 16); x += __shfl_xor(x, 32); return x; }
; __device__ __forceinline__ void ln_apply16(const h16x4 (&t)[8], int lane, const float* g, const float* bt, f32x4 (&v)[8]) {
;     ...
;     const float rstd = rsqrtf(wave_sum(q) * (1.0f / DM) + 1e-5f);
; #pragma unroll
;     for (int i = 0; i < 8; ++i) { const f32x4 gg = ((const f32x4*)g)[i * 64 + lane], bb = ((const f32x4*)bt)[i * 64 + lane]; v[i] = v[i] * rstd * gg + bb; }
; template <bool LN>
; __device__ __forceinline__ void ln_phase(const void* src, const float* g, const float* bt, float* xout, h16* xh, const float* mu, h16* mix) {
;     ...
;             if (xout) {
; #pragma unroll
;                 for (int i = 0; i < 8; ++i) ((f32x4*)(xout + row * DM))[i * 64 + lane] = cur[i];
;             }
	v_add_f32_e32 v0, v0, v58
	ds_bpermute_b32 v58, v214, v0
	s_waitcnt lgkmcnt(0)
	v_add_f32_e32 v0, v0, v58
	v_fmamk_f32 v0, v0, 0x3a000000, v242
	v_cmp_gt_f32_e32 vcc, s28, v0
	v_mul_f32_e32 v58, 0x4b800000, v0
	s_nop 0
	v_cndmask_b32_e32 v0, v0, v58, vcc
	v_rsq_f32_e32 v0, v0
	s_nop 0
	v_mul_f32_e32 v58, 0x45800000, v0
	v_cndmask_b32_e32 v0, v0, v58, vcc
	ds_read_b128 v[58:61], v230 offset:49152
	ds_read_b128 v[66:69], v230 offset:57344
	v_pk_mul_f32 v[212:213], v[4:5], v[0:1] op_sel_hi:[1,0]
	v_pk_mul_f32 v[2:3], v[2:3], v[0:1] op_sel_hi:[1,0]
	v_pk_mul_f32 v[6:7], v[6:7], v[0:1] op_sel_hi:[1,0]
	v_pk_mul_f32 v[10:11], v[10:11], v[0:1] op_sel_hi:[1,0]
	v_pk_mul_f32 v[12:13], v[12:13], v[0:1] op_sel_hi:[1,0]
	v_pk_mul_f32 v[14:15], v[14:15], v[0:1] op_sel_hi:[1,0]
	v_pk_mul_f32 v[16:17], v[16:17], v[0:1] op_sel_hi:[1,0]
	v_pk_mul_f32 v[22:23], v[22:23], v[0:1] op_sel_hi:[1,0]
	v_pk_mul_f32 v[30:31], v[30:31], v[0:1] op_sel_hi:[1,0]
	v_pk_mul_f32 v[32:33], v[32:33], v[0:1] op_sel_hi:[1,0]
	v_pk_mul_f32 v[34:35], v[34:35], v[0:1] op_sel_hi:[1,0]
	v_pk_mul_f32 v[36:37], v[36:37], v[0:1] op_sel_hi:[1,0]
	v_pk_mul_f32 v[214:215], v[222:223], v[0:1] op_sel_hi:[1,0]
	s_andn2_b64 vcc, exec, s[44:45]
	s_waitcnt lgkmcnt(0)
	v_pk_fma_f32 v[4:5], v[60:61], v[2:3], v[68:69]
	v_pk_fma_f32 v[2:3], v[58:59], v[212:213], v[66:67]
	ds_read_b128 v[58:61], v230 offset:50176
	ds_read_b128 v[66:69], v230 offset:58368
	v_pk_mul_f32 v[212:213], v[8:9], v[0:1] op_sel_hi:[1,0]
	s_waitcnt lgkmcnt(0)
	v_pk_fma_f32 v[8:9], v[60:61], v[6:7], v[68:69]
	v_pk_fma_f32 v[6:7], v[58:59], v[212:213], v[66:67]
	ds_read_b128 v[58:61], v230 offset:51200
	ds_read_b128 v[66:69], v230 offset:59392
	v_pk_mul_f32 v[212:213], v[24:25], v[0:1] op_sel_hi:[1,0]
	s_waitcnt lgkmcnt(0)
	v_pk_fma_f32 v[12:13], v[60:61], v[12:13], v[68:69]
	v_pk_fma_f32 v[10:11], v[58:59], v[10:11], v[66:67]
	ds_read_b128 v[58:61], v230 offset:52224
	ds_read_b128 v[66:69], v230 offset:60416
	s_waitcnt lgkmcnt(0)
	v_pk_fma_f32 v[16:17], v[60:61], v[16:17], v[68:69]
	v_pk_fma_f32 v[14:15], v[58:59], v[14:15], v[66:67]
	ds_read_b128 v[58:61], v230 offset:53248
	ds_read_b128 v[66:69], v230 offset:61440
	s_waitcnt lgkmcnt(0)
	v_pk_fma_f32 v[24:25], v[60:61], v[22:23], v[68:69]
	v_pk_fma_f32 v[22:23], v[58:59], v[212:213], v[66:67]
	ds_read_b128 v[58:61], v230 offset:54272
	ds_read_b128 v[66:69], v230 offset:62464
	v_pk_mul_f32 v[212:213], v[224:225], v[0:1] op_sel_hi:[1,0]
	s_waitcnt lgkmcnt(0)
	v_pk_fma_f32 v[32:33], v[60:61], v[32:33], v[68:69]
	v_pk_fma_f32 v[30:31], v[58:59], v[30:31], v[66:67]
	ds_read_b128 v[58:61], v230 offset:55296
	ds_read_b128 v[66:69], v230 offset:63488
	s_waitcnt lgkmcnt(0)
	v_pk_fma_f32 v[36:37], v[60:61], v[36:37], v[68:69]
	v_pk_fma_f32 v[34:35], v[58:59], v[34:35], v[66:67]
	ds_read_b128 v[58:61], v230 offset:56320
	ds_read_b128 v[66:69], v230 offset:64512
	s_waitcnt lgkmcnt(0)
	v_pk_fma_f32 v[60:61], v[60:61], v[214:215], v[68:69]
	v_pk_fma_f32 v[58:59], v[58:59], v[212:213], v[66:67]
	s_cbranch_vccnz .LBB0_126
	global_store_dwordx4 v[192:193], v[2:5], off offset:-4096
	global_store_dwordx4 v[192:193], v[6:9], off offset:-3072
	global_store_dwordx4 v[192:193], v[10:13], off offset:-2048
	global_store_dwordx4 v[192:193], v[14:17], off offset:-1024
	global_store_dwordx4 v[192:193], v[22:25], off
	global_store_dwordx4 v[192:193], v[30:33], off offset:1024
	global_store_dwordx4 v[192:193], v[34:37], off offset:2048
	global_store_dwordx4 v[192:193], v[58:61], off offset:3072

; #define PG8_STAGE(bufoff, gbase, voff) do { _Pragma("unroll") for (int _i = 0; _i < 2; ++_i) \
;         __builtin_amdgcn_global_load_lds((const unsigned*)((const char*)(gbase) + (voff)[_i]), (LAS unsigned*)(lds + (bufoff) + ldsw + _i * 8192), 16, 0, 0); } while (0)
; #define PG8_LDA(dst, b, h) do { _Pragma("unroll") for (int m = 0; m < 4; ++m) _Pragma("unroll") for (int k = 0; k < 2; ++k) dst[m][k] = *(const LAS h16x8*)(lds + PG8_SA(b, h) + aoff + m * 2048 + k * 1024); } while (0)
; #define PG8_LDB(dst, b, h) do { _Pragma("unroll") for (int n = 0; n < 2; ++n) _Pragma("unroll") for (int k = 0; k < 2; ++k) dst[n][k] = *(const LAS h16x8*)(lds + PG8_SB(b, h) + boff + n * 2048 + k * 1024); } while (0)
; #define PG8_MMA(ai, bj, At, Bt_) do { __builtin_amdgcn_s_setprio(1); _Pragma("unroll") for (int m = 0; m < 4; ++m) _Pragma("unroll") for (int n = 0; n < 2; ++n) _Pragma("unroll") for (int k = 0; k < 2; ++k) \
;         acc[ai][bj][m][n] = __builtin_amdgcn_mfma_f32_16x16x32_f16(Bt_[n][k], At[m][k], acc[ai][bj][m][n], 0, 0, 0); __builtin_amdgcn_s_setprio(0); } while (0)
; #define PG8_WAIT_L(n) asm volatile("s_waitcnt lgkmcnt(" #n ")" ::: "memory")
; #define PG8_BAR __builtin_amdgcn_s_barrier()
; #define PG8_SCHED __builtin_amdgcn_sched_barrier(0)
; template <class Epi, class AMap>
; __device__ __forceinline__ void gemm_phase(LAS unsigned char* lds, const AMap am, const int lda, const h16* Bt, const int ldb, const int M, const int N, const int K, const Epi& E) {
;     ...
;             PG8_LDB(B0, 0, 0); PG8_SCHED; PG8_LDA(At, 0, 0); PG8_STAGE(PG8_SA(1, 1), a1 + hstepA, voffA);
;             PG8_WAIT_L(8); PG8_BAR; PG8_WAIT_L(0); PG8_MMA(0, 0, At, B0); PG8_BAR; PG8_SCHED;
;             PG8_LDB(B1, 0, 1); PG8_STAGE(PG8_SB(0, 0), b2, voffB);
;             PG8_BAR; PG8_WAIT_L(0); PG8_MMA(0, 1, At, B1); PG8_BAR;
;             PG8_LDA(At, 0, 1); PG8_STAGE(PG8_SA(0, 0), a2, voffA);
;             PG8_BAR; PG8_WAIT_L(0); PG8_MMA(1, 0, At, B0); PG8_BAR; PG8_SCHED;
.LBB0_147:
	s_add_u32 s46, s26, 0xfff80080
	s_addc_u32 s47, s27, -1
	s_add_i32 s60, 0, 0x10000
	v_add_u32_e32 v144, s60, v147
	ds_read_b128 v[140:143], v144
	ds_read_b128 v[150:153], v144 offset:1024
	ds_read_b128 v[154:157], v144 offset:2048
	ds_read_b128 v[158:161], v144 offset:3072
	s_cmp_eq_u32 s51, 28
	s_cselect_b32 s49, s41, s47
	s_cselect_b32 s48, s29, s46
	s_cselect_b32 s47, s1, s50
	s_cselect_b32 s46, s20, s21
	v_lshl_add_u64 v[144:145], s[26:27], 0, v[136:137]
	s_add_i32 m0, s23, 0xc000
	ds_read_b128 v[162:165], v149
	ds_read_b128 v[166:169], v149 offset:1024
	ds_read_b128 v[170:173], v149 offset:2048
	ds_read_b128 v[174:177], v149 offset:3072
	ds_read_b128 v[178:181], v149 offset:4096
	ds_read_b128 v[182:185], v149 offset:5120
	ds_read_b128 v[186:189], v149 offset:6144
	ds_read_b128 v[190:193], v149 offset:7168
	global_load_lds_dwordx4 v[144:145], off
	v_lshl_add_u64 v[144:145], s[26:27], 0, v[138:139]
	s_add_i32 m0, s23, 0xe000
	s_nop 0
	global_load_lds_dwordx4 v[144:145], off
	s_waitcnt lgkmcnt(8)
	s_barrier
	s_waitcnt lgkmcnt(0)
	s_setprio 1
	s_waitcnt lgkmcnt(0)
	v_mfma_f32_16x16x32_f16 v[126:129], v[140:143], v[162:165], v[126:129]
	v_mfma_f32_16x16x32_f16 v[122:125], v[154:157], v[162:165], v[122:125]
	v_mfma_f32_16x16x32_f16 v[110:113], v[140:143], v[170:173], v[110:113]
	v_mfma_f32_16x16x32_f16 v[106:109], v[154:157], v[170:173], v[106:109]
	v_mfma_f32_16x16x32_f16 v[94:97], v[140:143], v[178:181], v[94:97]
	v_mfma_f32_16x16x32_f16 v[90:93], v[154:157], v[178:181], v[90:93]
	v_mfma_f32_16x16x32_f16 v[78:81], v[140:143], v[186:189], v[78:81]
	v_mfma_f32_16x16x32_f16 v[74:77], v[154:157], v[186:189], v[74:77]
	v_mfma_f32_16x16x32_f16 v[126:129], v[150:153], v[166:169], v[126:129]
	v_mfma_f32_16x16x32_f16 v[122:125], v[158:161], v[166:169], v[122:125]
	v_mfma_f32_16x16x32_f16 v[110:113], v[150:153], v[174:177], v[110:113]
	v_mfma_f32_16x16x32_f16 v[106:109], v[158:161], v[174:177], v[106:109]
	v_mfma_f32_16x16x32_f16 v[94:97], v[150:153], v[182:185], v[94:97]
	v_mfma_f32_16x16x32_f16 v[90:93], v[158:161], v[182:185], v[90:93]
	v_mfma_f32_16x16x32_f16 v[78:81], v[150:153], v[190:193], v[78:81]
	v_mfma_f32_16x16x32_f16 v[74:77], v[158:161], v[190:193], v[74:77]
	s_setprio 0
	s_barrier
	s_add_i32 s66, 0, 0x14000
	v_add_u32_e32 v144, s66, v147
	s_add_i32 s60, s60, s64
	ds_read_b128 v[194:197], v144
	ds_read_b128 v[198:201], v144 offset:1024
	ds_read_b128 v[202:205], v144 offset:2048
	ds_read_b128 v[220:223], v144 offset:3072
	v_lshl_add_u64 v[144:145], s[46:47], 0, v[0:1]
	s_mov_b32 m0, s60
	v_lshl_add_u64 v[206:207], s[46:47], 0, v[134:135]
	global_load_lds_dwordx4 v[144:145], off
	s_add_i32 m0, s60, 0x2000
	s_nop 0
	global_load_lds_dwordx4 v[206:207], off
	s_barrier
	s_waitcnt lgkmcnt(0)
	s_setprio 1
	s_waitcnt lgkmcnt(0)
	v_mfma_f32_16x16x32_f16 v[118:121], v[194:197], v[162:165], v[118:121]
	v_mfma_f32_16x16x32_f16 v[114:117], v[202:205], v[162:165], v[114:117]
	v_mfma_f32_16x16x32_f16 v[102:105], v[194:197], v[170:173], v[102:105]
	v_mfma_f32_16x16x32_f16 v[98:101], v[202:205], v[170:173], v[98:101]
	v_mfma_f32_16x16x32_f16 v[86:89], v[194:197], v[178:181], v[86:89]
	v_mfma_f32_16x16x32_f16 v[82:85], v[202:205], v[178:181], v[82:85]
	v_mfma_f32_16x16x32_f16 v[70:73], v[194:197], v[186:189], v[70:73]
	v_mfma_f32_16x16x32_f16 v[66:69], v[202:205], v[186:189], v[66:69]
	v_mfma_f32_16x16x32_f16 v[118:121], v[198:201], v[166:169], v[118:121]
	v_mfma_f32_16x16x32_f16 v[114:117], v[220:223], v[166:169], v[114:117]
	v_mfma_f32_16x16x32_f16 v[102:105], v[198:201], v[174:177], v[102:105]
	v_mfma_f32_16x16x32_f16 v[98:101], v[220:223], v[174:177], v[98:101]
	v_mfma_f32_16x16x32_f16 v[86:89], v[198:201], v[182:185], v[86:89]
	v_mfma_f32_16x16x32_f16 v[82:85], v[220:223], v[182:185], v[82:85]
	v_mfma_f32_16x16x32_f16 v[70:73], v[198:201], v[190:193], v[70:73]
	v_mfma_f32_16x16x32_f16 v[66:69], v[220:223], v[190:193], v[66:69]
	s_setprio 0
	s_mov_b32 m0, s23
	v_lshl_add_u64 v[212:213], s[48:49], 0, v[130:131]
	s_barrier
	ds_read_b128 v[162:165], v149 offset:16384
	ds_read_b128 v[166:169], v149 offset:17408
	ds_read_b128 v[170:173], v149 offset:18432
	ds_read_b128 v[174:177], v149 offset:19456
	ds_read_b128 v[178:181], v149 offset:20480
	ds_read_b128 v[182:185], v149 offset:21504
	ds_read_b128 v[186:189], v149 offset:22528
	ds_read_b128 v[190:193], v149 offset:23552
	global_load_lds_dwordx4 v[212:213], off
	v_lshl_add_u64 v[214:215], s[48:49], 0, v[132:133]
	s_mov_b32 m0, s71
	s_nop 0
	global_load_lds_dwordx4 v[214:215], off
	s_barrier
	s_waitcnt lgkmcnt(0)
	s_setprio 1
	s_waitcnt lgkmcnt(0)
	v_mfma_f32_16x16x32_f16 v[62:65], v[140:143], v[162:165], v[62:65]
	v_mfma_f32_16x16x32_f16 v[58:61], v[154:157], v[162:165], v[58:61]
	v_mfma_f32_16x16x32_f16 v[46:49], v[140:143], v[170:173], v[46:49]
	v_mfma_f32_16x16x32_f16 v[42:45], v[154:157], v[170:173], v[42:45]
	v_mfma_f32_16x16x32_f16 v[30:33], v[140:143], v[178:181], v[30:33]
	v_mfma_f32_16x16x32_f16 v[26:29], v[154:157], v[178:181], v[26:29]
	v_mfma_f32_16x16x32_f16 v[14:17], v[140:143], v[186:189], v[14:17]
	v_mfma_f32_16x16x32_f16 v[10:13], v[154:157], v[186:189], v[10:13]
	v_mfma_f32_16x16x32_f16 v[62:65], v[150:153], v[166:169], v[62:65]
	v_mfma_f32_16x16x32_f16 v[58:61], v[158:161], v[166:169], v[58:61]
	v_mfma_f32_16x16x32_f16 v[46:49], v[150:153], v[174:177], v[46:49]
	v_mfma_f32_16x16x32_f16 v[42:45], v[158:161], v[174:177], v[42:45]
	v_mfma_f32_16x16x32_f16 v[30:33], v[150:153], v[182:185], v[30:33]
	v_mfma_f32_16x16x32_f16 v[26:29], v[158:161], v[182:185], v[26:29]
	v_mfma_f32_16x16x32_f16 v[14:17], v[150:153], v[190:193], v[14:17]
	v_mfma_f32_16x16x32_f16 v[10:13], v[158:161], v[190:193], v[10:13]
	s_setprio 0
	s_barrier
; #define PG8_STAGE(bufoff, gbase, voff) do { _Pragma("unroll") for (int _i = 0; _i < 2; ++_i) \
;         __builtin_amdgcn_global_load_lds((const unsigned*)((const char*)(gbase) + (voff)[_i]), (LAS unsigned*)(lds + (bufoff) + ldsw + _i * 8192), 16, 0, 0); } while (0)
; #define PG8_LDA(dst, b, h) do { _Pragma("unroll") for (int m = 0; m < 4; ++m) _Pragma("unroll") for (int k = 0; k < 2; ++k) dst[m][k] = *(const LAS h16x8*)(lds + PG8_SA(b, h) + aoff + m * 2048 + k * 1024); } while (0)
; #define PG8_LDB(dst, b, h) do { _Pragma("unroll") for (int n = 0; n < 2; ++n) _Pragma("unroll") for (int k = 0; k < 2; ++k) dst[n][k] = *(const LAS h16x8*)(lds + PG8_SB(b, h) + boff + n * 2048 + k * 1024); } while (0)
; #define PG8_MMA(ai, bj, At, Bt_) do { __builtin_amdgcn_s_setprio(1); _Pragma("unroll") for (int m = 0; m < 4; ++m) _Pragma("unroll") for (int n = 0; n < 2; ++n) _Pragma("unroll") for (int k = 0; k < 2; ++k) \
;         acc[ai][bj][m][n] = __builtin_amdgcn_mfma_f32_16x16x32_f16(Bt_[n][k], At[m][k], acc[ai][bj][m][n], 0, 0, 0); __builtin_amdgcn_s_setprio(0); } while (0)
; #define PG8_WAIT_V(n) asm volatile("s_waitcnt vmcnt(" #n ")" ::: "memory")
; #define PG8_WAIT_L(n) asm volatile("s_waitcnt lgkmcnt(" #n ")" ::: "memory")
; #define PG8_BAR __builtin_amdgcn_s_barrier()
; #define PG8_SCHED __builtin_amdgcn_sched_barrier(0)
; template <class Epi, class AMap>
; __device__ __forceinline__ void gemm_phase(LAS unsigned char* lds, const AMap am, const int lda, const h16* Bt, const int ldb, const int M, const int N, const int K, const Epi& E) {
;     ...
;             PG8_STAGE(PG8_SB(0, 1), b2 + hstepB, voffB);
;             PG8_WAIT_V(6); PG8_BAR; PG8_MMA(1, 1, At, B1); PG8_BAR;
;             PG8_LDB(B0, 1, 0); PG8_SCHED; PG8_LDA(At, 1, 0); PG8_STAGE(PG8_SA(0, 1), a2 + hstepA, voffA);
;             PG8_WAIT_L(8); PG8_BAR; PG8_WAIT_L(0); PG8_MMA(0, 0, At, B0); PG8_BAR; PG8_SCHED;
;             PG8_LDB(B1, 1, 1); PG8_STAGE(PG8_SB(1, 0), b3, voffB);
;             PG8_BAR; PG8_WAIT_L(0); PG8_MMA(0, 1, At, B1); PG8_BAR;
;             PG8_LDA(At, 1, 1); PG8_STAGE(PG8_SA(1, 0), a3, voffA);
;             PG8_BAR; PG8_WAIT_L(0); PG8_MMA(1, 0, At, B0); PG8_BAR; PG8_SCHED;
	s_add_u32 s78, s46, 0x80000
	s_addc_u32 s79, s47, 0
	s_add_i32 s60, s66, s64
	v_lshl_add_u64 v[140:141], s[78:79], 0, v[0:1]
	s_mov_b32 m0, s60
	s_nop 0
	global_load_lds_dwordx4 v[140:141], off
	v_lshl_add_u64 v[140:141], s[78:79], 0, v[134:135]
	s_add_i32 m0, s60, 0x2000
	s_nop 0
	global_load_lds_dwordx4 v[140:141], off
	s_waitcnt vmcnt(6)
	s_barrier
	s_setprio 1
	v_mfma_f32_16x16x32_f16 v[54:57], v[194:197], v[162:165], v[54:57]
	v_mfma_f32_16x16x32_f16 v[50:53], v[202:205], v[162:165], v[50:53]
	v_mfma_f32_16x16x32_f16 v[38:41], v[194:197], v[170:173], v[38:41]
	v_mfma_f32_16x16x32_f16 v[34:37], v[202:205], v[170:173], v[34:37]
	v_mfma_f32_16x16x32_f16 v[22:25], v[194:197], v[178:181], v[22:25]
	v_mfma_f32_16x16x32_f16 v[18:21], v[202:205], v[178:181], v[18:21]
	v_mfma_f32_16x16x32_f16 v[6:9], v[194:197], v[186:189], v[6:9]
	v_mfma_f32_16x16x32_f16 v[2:5], v[202:205], v[186:189], v[2:5]
	v_mfma_f32_16x16x32_f16 v[54:57], v[198:201], v[166:169], v[54:57]
	v_mfma_f32_16x16x32_f16 v[50:53], v[220:223], v[166:169], v[50:53]
	v_mfma_f32_16x16x32_f16 v[38:41], v[198:201], v[174:177], v[38:41]
	v_mfma_f32_16x16x32_f16 v[34:37], v[220:223], v[174:177], v[34:37]
	v_mfma_f32_16x16x32_f16 v[22:25], v[198:201], v[182:185], v[22:25]
	v_mfma_f32_16x16x32_f16 v[18:21], v[220:223], v[182:185], v[18:21]
	v_mfma_f32_16x16x32_f16 v[6:9], v[198:201], v[190:193], v[6:9]
	v_mfma_f32_16x16x32_f16 v[2:5], v[220:223], v[190:193], v[2:5]
	s_setprio 0
	s_add_i32 s60, 0, 0x18000
	v_add_u32_e32 v158, s60, v147
	s_barrier
	ds_read_b128 v[140:143], v158
	ds_read_b128 v[150:153], v158 offset:1024
	ds_read_b128 v[154:157], v158 offset:2048
	ds_read_b128 v[158:161], v158 offset:3072
	s_add_u32 s48, s48, 0x80000
	s_addc_u32 s49, s49, 0
	s_mov_b32 m0, s72
	v_lshl_add_u64 v[194:195], s[48:49], 0, v[130:131]
	ds_read_b128 v[162:165], v149 offset:32768
	ds_read_b128 v[166:169], v149 offset:33792
	ds_read_b128 v[170:173], v149 offset:34816
	ds_read_b128 v[174:177], v149 offset:35840
	ds_read_b128 v[178:181], v149 offset:36864
	ds_read_b128 v[182:185], v149 offset:37888
	ds_read_b128 v[186:189], v149 offset:38912
	ds_read_b128 v[190:193], v149 offset:39936
	global_load_lds_dwordx4 v[194:195], off
	v_lshl_add_u64 v[194:195], s[48:49], 0, v[132:133]
	s_mov_b32 m0, s73
	s_nop 0
	global_load_lds_dwordx4 v[194:195], off
	s_waitcnt lgkmcnt(8)
	s_barrier
	s_waitcnt lgkmcnt(0)
	s_setprio 1
	s_waitcnt lgkmcnt(0)
	v_mfma_f32_16x16x32_f16 v[126:129], v[140:143], v[162:165], v[126:129]
	v_mfma_f32_16x16x32_f16 v[122:125], v[154:157], v[162:165], v[122:125]
	v_mfma_f32_16x16x32_f16 v[110:113], v[140:143], v[170:173], v[110:113]
	v_mfma_f32_16x16x32_f16 v[106:109], v[154:157], v[170:173], v[106:109]
	v_mfma_f32_16x16x32_f16 v[94:97], v[140:143], v[178:181], v[94:97]
	v_mfma_f32_16x16x32_f16 v[90:93], v[154:157], v[178:181], v[90:93]
	v_mfma_f32_16x16x32_f16 v[78:81], v[140:143], v[186:189], v[78:81]
	v_mfma_f32_16x16x32_f16 v[74:77], v[154:157], v[186:189], v[74:77]
	v_mfma_f32_16x16x32_f16 v[126:129], v[150:153], v[166:169], v[126:129]
	v_mfma_f32_16x16x32_f16 v[122:125], v[158:161], v[166:169], v[122:125]
	v_mfma_f32_16x16x32_f16 v[110:113], v[150:153], v[174:177], v[110:113]
	v_mfma_f32_16x16x32_f16 v[106:109], v[158:161], v[174:177], v[106:109]
	v_mfma_f32_16x16x32_f16 v[94:97], v[150:153], v[182:185], v[94:97]
	v_mfma_f32_16x16x32_f16 v[90:93], v[158:161], v[182:185], v[90:93]
	v_mfma_f32_16x16x32_f16 v[78:81], v[150:153], v[190:193], v[78:81]
	v_mfma_f32_16x16x32_f16 v[74:77], v[158:161], v[190:193], v[74:77]
	s_setprio 0
	s_barrier
	s_add_i32 s48, 0, 0x1c000
	s_add_i32 s49, s60, s64
	v_add_u32_e32 v216, s48, v147
	v_lshl_add_u64 v[144:145], v[144:145], 0, s[92:93]
	s_mov_b32 m0, s49
	ds_read_b128 v[194:197], v216
	ds_read_b128 v[198:201], v216 offset:1024
	ds_read_b128 v[202:205], v216 offset:2048
	ds_read_b128 v[220:223], v216 offset:3072
	global_load_lds_dwordx4 v[144:145], off
	v_lshl_add_u64 v[144:145], v[206:207], 0, s[92:93]
	s_add_i32 m0, s49, 0x2000
	s_nop 0
	global_load_lds_dwordx4 v[144:145], off
	s_barrier
	s_waitcnt lgkmcnt(0)
	s_setprio 1
	s_waitcnt lgkmcnt(0)
	v_mfma_f32_16x16x32_f16 v[118:121], v[194:197], v[162:165], v[118:121]
	v_mfma_f32_16x16x32_f16 v[114:117], v[202:205], v[162:165], v[114:117]
	v_mfma_f32_16x16x32_f16 v[102:105], v[194:197], v[170:173], v[102:105]
	v_mfma_f32_16x16x32_f16 v[98:101], v[202:205], v[170:173], v[98:101]
	v_mfma_f32_16x16x32_f16 v[86:89], v[194:197], v[178:181], v[86:89]
	v_mfma_f32_16x16x32_f16 v[82:85], v[202:205], v[178:181], v[82:85]
	v_mfma_f32_16x16x32_f16 v[70:73], v[194:197], v[186:189], v[70:73]
	v_mfma_f32_16x16x32_f16 v[66:69], v[202:205], v[186:189], v[66:69]
	v_mfma_f32_16x16x32_f16 v[118:121], v[198:201], v[166:169], v[118:121]
	v_mfma_f32_16x16x32_f16 v[114:117], v[220:223], v[166:169], v[114:117]
	v_mfma_f32_16x16x32_f16 v[102:105], v[198:201], v[174:177], v[102:105]
	v_mfma_f32_16x16x32_f16 v[98:101], v[220:223], v[174:177], v[98:101]
	v_mfma_f32_16x16x32_f16 v[86:89], v[198:201], v[182:185], v[86:89]
	v_mfma_f32_16x16x32_f16 v[82:85], v[220:223], v[182:185], v[82:85]
	v_mfma_f32_16x16x32_f16 v[70:73], v[198:201], v[190:193], v[70:73]
	v_mfma_f32_16x16x32_f16 v[66:69], v[220:223], v[190:193], v[66:69]
	s_setprio 0
	s_mov_b32 m0, s74
	v_lshl_add_u64 v[144:145], v[212:213], 0, s[92:93]
	s_barrier
	ds_read_b128 v[162:165], v149 offset:49152
	ds_read_b128 v[166:169], v149 offset:50176
	ds_read_b128 v[170:173], v149 offset:51200
	ds_read_b128 v[174:177], v149 offset:52224
	ds_read_b128 v[178:181], v149 offset:53248
	ds_read_b128 v[182:185], v149 offset:54272
	ds_read_b128 v[186:189], v149 offset:55296
	ds_read_b128 v[190:193], v149 offset:56320
	global_load_lds_dwordx4 v[144:145], off
	v_lshl_add_u64 v[144:145], v[214:215], 0, s[92:93]
	s_mov_b32 m0, s75
	s_nop 0
	global_load_lds_dwordx4 v[144:145], off
	s_barrier
; #define PG8_STAGE(bufoff, gbase, voff) do { _Pragma("unroll") for (int _i = 0; _i < 2; ++_i) \
;         __builtin_amdgcn_global_load_lds((const unsigned*)((const char*)(gbase) + (voff)[_i]), (LAS unsigned*)(lds + (bufoff) + ldsw + _i * 8192), 16, 0, 0); } while (0)
; #define PG8_MMA(ai, bj, At, Bt_) do { __builtin_amdgcn_s_setprio(1); _Pragma("unroll") for (int m = 0; m < 4; ++m) _Pragma("unroll") for (int n = 0; n < 2; ++n) _Pragma("unroll") for (int k = 0; k < 2; ++k) \
;         acc[ai][bj][m][n] = __builtin_amdgcn_mfma_f32_16x16x32_f16(Bt_[n][k], At[m][k], acc[ai][bj][m][n], 0, 0, 0); __builtin_amdgcn_s_setprio(0); } while (0)
; #define PG8_WAIT_V(n) asm volatile("s_waitcnt vmcnt(" #n ")" ::: "memory")
; #define PG8_WAIT_L(n) asm volatile("s_waitcnt lgkmcnt(" #n ")" ::: "memory")
; #define PG8_BAR __builtin_amdgcn_s_barrier()
; #define PG8_SCHED __builtin_amdgcn_sched_barrier(0)
; template <class Epi, class AMap>
; __device__ __forceinline__ void gemm_phase(LAS unsigned char* lds, const AMap am, const int lda, const h16* Bt, const int ldb, const int M, const int N, const int K, const Epi& E) {
;     ...
;             PG8_BAR; PG8_WAIT_L(0); PG8_MMA(1, 0, At, B0); PG8_BAR; PG8_SCHED;
;             PG8_STAGE(PG8_SB(1, 1), b3 + hstepB, voffB);
;             PG8_WAIT_V(6); PG8_BAR; PG8_MMA(1, 1, At, B1); PG8_BAR;
;     __device__ __forceinline__ void operator()(const f32x4 (&acc)[2][2][4][2], const Unit& u, int wr, int wc, int fr, int fq) const {
;         EPI_ROWS_PERM
; #pragma unroll
;         for (int ai = 0; ai < 2; ++ai)
; #pragma unroll
;             for (int m = 0; m < 4; ++m) { const size_t off = (size_t)(row0 + ai * 128 + m * 16) * DM + colt;
; #pragma unroll
;                 for (int bj = 0; bj < 2; ++bj) {
;                     const h16x8 x = *(const h16x8*)(X + off + bj * 128);
;                     f32x4 o0, o1;
; #pragma unroll
;                     for (int e = 0; e < 4; ++e) { o0[e] = (float)x[e] * ALPHA + acc[ai][bj][m][0][e]; o1[e] = (float)x[4 + e] * ALPHA + acc[ai][bj][m][1][e]; }
;                     *(u32x4*)(PRE + off + bj * 128) = pack8(o0, o1); } }
	s_waitcnt lgkmcnt(0)
	s_setprio 1
	s_waitcnt lgkmcnt(0)
	v_mfma_f32_16x16x32_f16 v[62:65], v[140:143], v[162:165], v[62:65]
	v_mfma_f32_16x16x32_f16 v[58:61], v[154:157], v[162:165], v[58:61]
	v_mfma_f32_16x16x32_f16 v[46:49], v[140:143], v[170:173], v[46:49]
	v_mfma_f32_16x16x32_f16 v[42:45], v[154:157], v[170:173], v[42:45]
	v_mfma_f32_16x16x32_f16 v[30:33], v[140:143], v[178:181], v[30:33]
	v_mfma_f32_16x16x32_f16 v[26:29], v[154:157], v[178:181], v[26:29]
	v_mfma_f32_16x16x32_f16 v[14:17], v[140:143], v[186:189], v[14:17]
	v_mfma_f32_16x16x32_f16 v[10:13], v[154:157], v[186:189], v[10:13]
	v_mfma_f32_16x16x32_f16 v[62:65], v[150:153], v[166:169], v[62:65]
	v_mfma_f32_16x16x32_f16 v[58:61], v[158:161], v[166:169], v[58:61]
	v_mfma_f32_16x16x32_f16 v[46:49], v[150:153], v[174:177], v[46:49]
	v_mfma_f32_16x16x32_f16 v[42:45], v[158:161], v[174:177], v[42:45]
	v_mfma_f32_16x16x32_f16 v[30:33], v[150:153], v[182:185], v[30:33]
	v_mfma_f32_16x16x32_f16 v[26:29], v[158:161], v[182:185], v[26:29]
	v_mfma_f32_16x16x32_f16 v[14:17], v[150:153], v[190:193], v[14:17]
	v_mfma_f32_16x16x32_f16 v[10:13], v[158:161], v[190:193], v[10:13]
	s_setprio 0
	s_barrier
	s_add_u32 s46, s46, 0x80080
	s_addc_u32 s47, s47, 0
	s_add_i32 s48, s48, s64
	v_lshl_add_u64 v[140:141], s[46:47], 0, v[0:1]
	s_mov_b32 m0, s48
	s_nop 0
	global_load_lds_dwordx4 v[140:141], off
	v_lshl_add_u64 v[140:141], s[46:47], 0, v[134:135]
	s_add_i32 m0, s48, 0x2000
	s_nop 0
	global_load_lds_dwordx4 v[140:141], off
	s_waitcnt vmcnt(6)
	s_barrier
	s_setprio 1
	v_mfma_f32_16x16x32_f16 v[54:57], v[194:197], v[162:165], v[54:57]
	v_mfma_f32_16x16x32_f16 v[50:53], v[202:205], v[162:165], v[50:53]
	v_mfma_f32_16x16x32_f16 v[38:41], v[194:197], v[170:173], v[38:41]
	v_mfma_f32_16x16x32_f16 v[34:37], v[202:205], v[170:173], v[34:37]
	v_mfma_f32_16x16x32_f16 v[22:25], v[194:197], v[178:181], v[22:25]
	v_mfma_f32_16x16x32_f16 v[18:21], v[202:205], v[178:181], v[18:21]
	v_mfma_f32_16x16x32_f16 v[6:9], v[194:197], v[186:189], v[6:9]
	v_mfma_f32_16x16x32_f16 v[2:5], v[202:205], v[186:189], v[2:5]
	v_mfma_f32_16x16x32_f16 v[54:57], v[198:201], v[166:169], v[54:57]
	v_mfma_f32_16x16x32_f16 v[50:53], v[220:223], v[166:169], v[50:53]
	v_mfma_f32_16x16x32_f16 v[38:41], v[198:201], v[174:177], v[38:41]
	v_mfma_f32_16x16x32_f16 v[34:37], v[220:223], v[174:177], v[34:37]
	v_mfma_f32_16x16x32_f16 v[22:25], v[198:201], v[182:185], v[22:25]
	v_mfma_f32_16x16x32_f16 v[18:21], v[220:223], v[182:185], v[18:21]
	v_mfma_f32_16x16x32_f16 v[6:9], v[198:201], v[190:193], v[6:9]
	v_mfma_f32_16x16x32_f16 v[2:5], v[220:223], v[190:193], v[2:5]
	s_setprio 0
	s_add_i32 s51, s51, 2
	s_add_u32 s26, s26, 0x100
	s_addc_u32 s27, s27, 0
	s_add_u32 s21, s21, 0x100
	s_addc_u32 s50, s50, 0
	s_cmp_gt_u32 s51, 29
	s_barrier
	s_cbranch_scc0 .LBB0_147
	v_lshl_add_u32 v144, s22, 8, v146
	v_lshl_or_b32 v142, s35, 8, v148
	v_ashrrev_i32_e32 v145, 31, v144
	v_ashrrev_i32_e32 v143, 31, v142
	v_lshlrev_b64 v[140:141], 11, v[144:145]
	v_lshl_add_u64 v[140:141], v[140:141], 0, v[142:143]
	v_lshlrev_b64 v[140:141], 1, v[140:141]
	v_lshl_add_u64 v[154:155], s[94:95], 0, v[140:141]
	s_mov_b32 s101, 0
	global_load_dwordx4 v[158:161], v[154:155], off
	global_load_dwordx4 v[162:165], v[154:155], off offset:256
	s_mov_b32 s100, 0x10000
	v_lshl_add_u64 v[232:233], v[154:155], 0, s[100:101]
	global_load_dwordx4 v[166:169], v[232:233], off
	global_load_dwordx4 v[170:173], v[232:233], off offset:256
	s_mov_b32 s100, 0x20000
	v_lshl_add_u64 v[232:233], v[154:155], 0, s[100:101]
	global_load_dwordx4 v[174:177], v[232:233], off
	global_load_dwordx4 v[178:181], v[232:233], off offset:256
	s_mov_b32 s100, 0x30000
	v_lshl_add_u64 v[232:233], v[154:155], 0, s[100:101]
	global_load_dwordx4 v[182:185], v[232:233], off
	global_load_dwordx4 v[186:189], v[232:233], off offset:256
	s_mov_b32 s100, 0x80000
	v_lshl_add_u64 v[232:233], v[154:155], 0, s[100:101]
	global_load_dwordx4 v[190:193], v[232:233], off
	global_load_dwordx4 v[194:197], v[232:233], off offset:256
	s_mov_b32 s100, 0x90000
	v_lshl_add_u64 v[232:233], v[154:155], 0, s[100:101]
	global_load_dwordx4 v[198:201], v[232:233], off
	global_load_dwordx4 v[202:205], v[232:233], off offset:256
	s_mov_b32 s100, 0xa0000
	v_lshl_add_u64 v[232:233], v[154:155], 0, s[100:101]
	global_load_dwordx4 v[212:215], v[232:233], off
	global_load_dwordx4 v[220:223], v[232:233], off offset:256
	s_mov_b32 s100, 0xb0000
	v_lshl_add_u64 v[232:233], v[154:155], 0, s[100:101]
	global_load_dwordx4 v[224:227], v[232:233], off
	global_load_dwordx4 v[228:231], v[232:233], off offset:256
	s_mov_b64 s[2:3], 0xb0000
	s_and_b64 vcc, exec, s[38:39]
	s_mov_b32 s22, s40
	s_mov_b64 s[46:47], s[44:45]
	s_mov_b64 s[26:27], s[42:43]
	s_movk_i32 s66, 0x80
	s_waitcnt vmcnt(15)
	v_mov_b64_e32 v[150:151], v[158:159]
	v_mov_b64_e32 v[152:153], v[160:161]
	v_cvt_f32_f16_e32 v156, v150
	v_cvt_f32_f16_sdwa v157, v150 dst_sel:DWORD dst_unused:UNUSED_PAD src0_sel:WORD_1
	v_cvt_f32_f16_e32 v150, v151
	v_cvt_f32_f16_sdwa v151, v151 dst_sel:DWORD dst_unused:UNUSED_PAD src0_sel:WORD_1
	v_pk_fma_f32 v[126:127], v[156:157], s[34:35], v[126:127] op_sel_hi:[1,0,1]
	s_nop 0
	v_cvt_pk_f16_f32 v126, v126, v127
	v_pk_fma_f32 v[128:129], v[150:151], s[34:35], v[128:129] op_sel_hi:[1,0,1]
	v_lshl_add_u64 v[150:151], s[4:5], 0, v[140:141]
	v_cvt_pk_f16_f32 v127, v128, v129
	v_cvt_f32_f16_e32 v128, v152
	v_cvt_f32_f16_sdwa v129, v152 dst_sel:DWORD dst_unused:UNUSED_PAD src0_sel:WORD_1
	v_pk_fma_f32 v[122:123], v[128:129], s[34:35], v[122:123] op_sel_hi:[1,0,1]
	s_nop 0
	v_cvt_pk_f16_f32 v128, v122, v123
	v_cvt_f32_f16_e32 v122, v153
	v_cvt_f32_f16_sdwa v123, v153 dst_sel:DWORD dst_unused:UNUSED_PAD src0_sel:WORD_1
	v_pk_fma_f32 v[122:123], v[122:123], s[34:35], v[124:125] op_sel_hi:[1,0,1]
	s_nop 0
	v_cvt_pk_f16_f32 v129, v122, v123
	s_nop 0
	global_store_dwordx4 v[150:151], v[126:129], off
	s_waitcnt vmcnt(15)
;     __device__ __forceinline__ void operator()(const f32x4 (&acc)[2][2][4][2], const Unit& u, int wr, int wc, int fr, int fq) const {
;     ...
;             for (int m = 0; m < 4; ++m) { const size_t off = (size_t)(row0 + ai * 128 + m * 16) * DM + colt;
; #pragma unroll
;                 for (int bj = 0; bj < 2; ++bj) {
;                     const h16x8 x = *(const h16x8*)(X + off + bj * 128);
;                     f32x4 o0, o1;
; #pragma unroll
;                     for (int e = 0; e < 4; ++e) { o0[e] = (float)x[e] * ALPHA + acc[ai][bj][m][0][e]; o1[e] = (float)x[4 + e] * ALPHA + acc[ai][bj][m][1][e]; }
;                     *(u32x4*)(PRE + off + bj * 128) = pack8(o0, o1); } }
	v_mov_b64_e32 v[122:123], v[162:163]
	v_mov_b64_e32 v[124:125], v[164:165]
	s_nop 0
	v_cvt_f32_f16_e32 v126, v122
	v_cvt_f32_f16_sdwa v127, v122 dst_sel:DWORD dst_unused:UNUSED_PAD src0_sel:WORD_1
	v_cvt_f32_f16_e32 v122, v123
	v_cvt_f32_f16_sdwa v123, v123 dst_sel:DWORD dst_unused:UNUSED_PAD src0_sel:WORD_1
	v_pk_fma_f32 v[118:119], v[126:127], s[34:35], v[118:119] op_sel_hi:[1,0,1]
	s_nop 0
	v_cvt_pk_f16_f32 v118, v118, v119
	v_pk_fma_f32 v[120:121], v[122:123], s[34:35], v[120:121] op_sel_hi:[1,0,1]
	s_nop 0
	v_cvt_pk_f16_f32 v119, v120, v121
	v_cvt_f32_f16_e32 v120, v124
	v_cvt_f32_f16_sdwa v121, v124 dst_sel:DWORD dst_unused:UNUSED_PAD src0_sel:WORD_1
	v_pk_fma_f32 v[114:115], v[120:121], s[34:35], v[114:115] op_sel_hi:[1,0,1]
	s_nop 0
	v_cvt_pk_f16_f32 v120, v114, v115
	v_cvt_f32_f16_e32 v114, v125
	v_cvt_f32_f16_sdwa v115, v125 dst_sel:DWORD dst_unused:UNUSED_PAD src0_sel:WORD_1
	v_pk_fma_f32 v[114:115], v[114:115], s[34:35], v[116:117] op_sel_hi:[1,0,1]
	s_nop 0
	v_cvt_pk_f16_f32 v121, v114, v115
	v_or_b32_e32 v114, 16, v144
	v_ashrrev_i32_e32 v115, 31, v114
	v_lshlrev_b64 v[114:115], 11, v[114:115]
	v_lshl_add_u64 v[114:115], v[114:115], 0, v[142:143]
	global_store_dwordx4 v[150:151], v[118:121], off offset:256
	s_nop 1
	v_lshlrev_b64 v[118:119], 1, v[114:115]
	v_lshl_add_u64 v[120:121], s[94:95], 0, v[118:119]
	s_waitcnt vmcnt(15)
	v_mov_b64_e32 v[114:115], v[166:167]
	v_mov_b64_e32 v[116:117], v[168:169]
	v_cvt_f32_f16_e32 v122, v114
	v_cvt_f32_f16_sdwa v123, v114 dst_sel:DWORD dst_unused:UNUSED_PAD src0_sel:WORD_1
	v_cvt_f32_f16_e32 v114, v115
	v_cvt_f32_f16_sdwa v115, v115 dst_sel:DWORD dst_unused:UNUSED_PAD src0_sel:WORD_1
	v_pk_fma_f32 v[110:111], v[122:123], s[34:35], v[110:111] op_sel_hi:[1,0,1]
	s_nop 0
	v_cvt_pk_f16_f32 v110, v110, v111
	v_pk_fma_f32 v[112:113], v[114:115], s[34:35], v[112:113] op_sel_hi:[1,0,1]
	v_lshl_add_u64 v[114:115], s[4:5], 0, v[118:119]
	v_cvt_pk_f16_f32 v111, v112, v113
	v_cvt_f32_f16_e32 v112, v116
	v_cvt_f32_f16_sdwa v113, v116 dst_sel:DWORD dst_unused:UNUSED_PAD src0_sel:WORD_1
	v_pk_fma_f32 v[106:107], v[112:113], s[34:35], v[106:107] op_sel_hi:[1,0,1]
	s_nop 0
	v_cvt_pk_f16_f32 v112, v106, v107
	v_cvt_f32_f16_e32 v106, v117
	v_cvt_f32_f16_sdwa v107, v117 dst_sel:DWORD dst_unused:UNUSED_PAD src0_sel:WORD_1
	v_pk_fma_f32 v[106:107], v[106:107], s[34:35], v[108:109] op_sel_hi:[1,0,1]
	s_nop 0
	v_cvt_pk_f16_f32 v113, v106, v107
	s_nop 0
	global_store_dwordx4 v[114:115], v[110:113], off
	s_waitcnt vmcnt(15)
	v_mov_b64_e32 v[106:107], v[170:171]
	v_mov_b64_e32 v[108:109], v[172:173]
	s_nop 0
	v_cvt_f32_f16_e32 v110, v106
	v_cvt_f32_f16_sdwa v111, v106 dst_sel:DWORD dst_unused:UNUSED_PAD src0_sel:WORD_1
	v_cvt_f32_f16_e32 v106, v107
	v_cvt_f32_f16_sdwa v107, v107 dst_sel:DWORD dst_unused:UNUSED_PAD src0_sel:WORD_1
	v_pk_fma_f32 v[102:103], v[110:111], s[34:35], v[102:103] op_sel_hi:[1,0,1]
	s_nop 0
	v_cvt_pk_f16_f32 v102, v102, v103
	v_pk_fma_f32 v[104:105], v[106:107], s[34:35], v[104:105] op_sel_hi:[1,0,1]
	s_nop 0
	v_cvt_pk_f16_f32 v103, v104, v105
	v_cvt_f32_f16_e32 v104, v108
	v_cvt_f32_f16_sdwa v105, v108 dst_sel:DWORD dst_unused:UNUSED_PAD src0_sel:WORD_1
	v_pk_fma_f32 v[98:99], v[104:105], s[34:35], v[98:99] op_sel_hi:[1,0,1]
	s_nop 0
	v_cvt_pk_f16_f32 v104, v98, v99
	v_cvt_f32_f16_e32 v98, v109
	v_cvt_f32_f16_sdwa v99, v109 dst_sel:DWORD dst_unused:UNUSED_PAD src0_sel:WORD_1
	v_pk_fma_f32 v[98:99], v[98:99], s[34:35], v[100:101] op_sel_hi:[1,0,1]
	s_nop 0
	v_cvt_pk_f16_f32 v105, v98, v99
	v_or_b32_e32 v98, 32, v144
	v_ashrrev_i32_e32 v99, 31, v98
	v_lshlrev_b64 v[98:99], 11, v[98:99]
	v_lshl_add_u64 v[98:99], v[98:99], 0, v[142:143]
	global_store_dwordx4 v[114:115], v[102:105], off offset:256
	s_nop 1
	v_lshlrev_b64 v[102:103], 1, v[98:99]
	v_lshl_add_u64 v[104:105], s[94:95], 0, v[102:103]
	s_waitcnt vmcnt(15)
	v_mov_b64_e32 v[98:99], v[174:175]
	v_mov_b64_e32 v[100:101], v[176:177]
	v_cvt_f32_f16_e32 v106, v98
	v_cvt_f32_f16_sdwa v107, v98 dst_sel:DWORD dst_unused:UNUSED_PAD src0_sel:WORD_1
	v_cvt_f32_f16_e32 v98, v99
	v_cvt_f32_f16_sdwa v99, v99 dst_sel:DWORD dst_unused:UNUSED_PAD src0_sel:WORD_1
	v_pk_fma_f32 v[94:95], v[106:107], s[34:35], v[94:95] op_sel_hi:[1,0,1]
	s_nop 0
	v_cvt_pk_f16_f32 v94, v94, v95
	v_pk_fma_f32 v[96:97], v[98:99], s[34:35], v[96:97] op_sel_hi:[1,0,1]
	v_lshl_add_u64 v[98:99], s[4:5], 0, v[102:103]
	v_cvt_pk_f16_f32 v95, v96, v97
	v_cvt_f32_f16_e32 v96, v100
	v_cvt_f32_f16_sdwa v97, v100 dst_sel:DWORD dst_unused:UNUSED_PAD src0_sel:WORD_1
	v_pk_fma_f32 v[90:91], v[96:97], s[34:35], v[90:91] op_sel_hi:[1,0,1]
	s_nop 0
	v_cvt_pk_f16_f32 v96, v90, v91
	v_cvt_f32_f16_e32 v90, v101
	v_cvt_f32_f16_sdwa v91, v101 dst_sel:DWORD dst_unused:UNUSED_PAD src0_sel:WORD_1
	v_pk_fma_f32 v[90:91], v[90:91], s[34:35], v[92:93] op_sel_hi:[1,0,1]
	s_nop 0
	v_cvt_pk_f16_f32 v97, v90, v91
	s_nop 0
	global_store_dwordx4 v[98:99], v[94:97], off
	s_waitcnt vmcnt(15)
	v_mov_b64_e32 v[90:91], v[178:179]
	v_mov_b64_e32 v[92:93], v[180:181]
	s_nop 0
	v_cvt_f32_f16_e32 v94, v90
	v_cvt_f32_f16_sdwa v95, v90 dst_sel:DWORD dst_unused:UNUSED_PAD src0_sel:WORD_1
	v_cvt_f32_f16_e32 v90, v91
	v_cvt_f32_f16_sdwa v91, v91 dst_sel:DWORD dst_unused:UNUSED_PAD src0_sel:WORD_1
	v_pk_fma_f32 v[86:87], v[94:95], s[34:35], v[86:87] op_sel_hi:[1,0,1]
	s_nop 0
	v_cvt_pk_f16_f32 v86, v86, v87
	v_pk_fma_f32 v[88:89], v[90:91], s[34:35], v[88:89] op_sel_hi:[1,0,1]
	s_nop 0
	v_cvt_pk_f16_f32 v87, v88, v89
	v_cvt_f32_f16_e32 v88, v92
	v_cvt_f32_f16_sdwa v89, v92 dst_sel:DWORD dst_unused:UNUSED_PAD src0_sel:WORD_1
	v_pk_fma_f32 v[82:83], v[88:89], s[34:35], v[82:83] op_sel_hi:[1,0,1]
	s_nop 0
	v_cvt_pk_f16_f32 v88, v82, v83
	v_cvt_f32_f16_e32 v82, v93
	v_cvt_f32_f16_sdwa v83, v93 dst_sel:DWORD dst_unused:UNUSED_PAD src0_sel:WORD_1
	v_pk_fma_f32 v[82:83], v[82:83], s[34:35], v[84:85] op_sel_hi:[1,0,1]
	s_nop 0
	v_cvt_pk_f16_f32 v89, v82, v83
	v_or_b32_e32 v82, 48, v144
	v_ashrrev_i32_e32 v83, 31, v82
	v_lshlrev_b64 v[82:83], 11, v[82:83]
	v_lshl_add_u64 v[82:83], v[82:83], 0, v[142:143]
	global_store_dwordx4 v[98:99], v[86:89], off offset:256
	s_nop 1
	v_lshlrev_b64 v[86:87], 1, v[82:83]
	v_lshl_add_u64 v[88:89], s[94:95], 0, v[86:87]
	s_waitcnt vmcnt(15)
;     __device__ __forceinline__ void operator()(const f32x4 (&acc)[2][2][4][2], const Unit& u, int wr, int wc, int fr, int fq) const {
;     ...
;             for (int m = 0; m < 4; ++m) { const size_t off = (size_t)(row0 + ai * 128 + m * 16) * DM + colt;
; #pragma unroll
;                 for (int bj = 0; bj < 2; ++bj) {
;                     const h16x8 x = *(const h16x8*)(X + off + bj * 128);
;                     f32x4 o0, o1;
; #pragma unroll
;                     for (int e = 0; e < 4; ++e) { o0[e] = (float)x[e] * ALPHA + acc[ai][bj][m][0][e]; o1[e] = (float)x[4 + e] * ALPHA + acc[ai][bj][m][1][e]; }
;                     *(u32x4*)(PRE + off + bj * 128) = pack8(o0, o1); } }
	v_mov_b64_e32 v[82:83], v[182:183]
	v_mov_b64_e32 v[84:85], v[184:185]
	v_cvt_f32_f16_e32 v90, v82
	v_cvt_f32_f16_sdwa v91, v82 dst_sel:DWORD dst_unused:UNUSED_PAD src0_sel:WORD_1
	v_cvt_f32_f16_e32 v82, v83
	v_cvt_f32_f16_sdwa v83, v83 dst_sel:DWORD dst_unused:UNUSED_PAD src0_sel:WORD_1
	v_pk_fma_f32 v[78:79], v[90:91], s[34:35], v[78:79] op_sel_hi:[1,0,1]
	s_nop 0
	v_cvt_pk_f16_f32 v78, v78, v79
	v_pk_fma_f32 v[80:81], v[82:83], s[34:35], v[80:81] op_sel_hi:[1,0,1]
	v_lshl_add_u64 v[82:83], s[4:5], 0, v[86:87]
	v_cvt_pk_f16_f32 v79, v80, v81
	v_cvt_f32_f16_e32 v80, v84
	v_cvt_f32_f16_sdwa v81, v84 dst_sel:DWORD dst_unused:UNUSED_PAD src0_sel:WORD_1
	v_pk_fma_f32 v[74:75], v[80:81], s[34:35], v[74:75] op_sel_hi:[1,0,1]
	s_nop 0
	v_cvt_pk_f16_f32 v80, v74, v75
	v_cvt_f32_f16_e32 v74, v85
	v_cvt_f32_f16_sdwa v75, v85 dst_sel:DWORD dst_unused:UNUSED_PAD src0_sel:WORD_1
	v_pk_fma_f32 v[74:75], v[74:75], s[34:35], v[76:77] op_sel_hi:[1,0,1]
	s_nop 0
	v_cvt_pk_f16_f32 v81, v74, v75
	s_nop 0
	global_store_dwordx4 v[82:83], v[78:81], off
	s_waitcnt vmcnt(15)
	v_mov_b64_e32 v[74:75], v[186:187]
	v_mov_b64_e32 v[76:77], v[188:189]
	s_nop 0
	v_cvt_f32_f16_e32 v78, v74
	v_cvt_f32_f16_sdwa v79, v74 dst_sel:DWORD dst_unused:UNUSED_PAD src0_sel:WORD_1
	v_cvt_f32_f16_e32 v74, v75
	v_cvt_f32_f16_sdwa v75, v75 dst_sel:DWORD dst_unused:UNUSED_PAD src0_sel:WORD_1
	v_pk_fma_f32 v[70:71], v[78:79], s[34:35], v[70:71] op_sel_hi:[1,0,1]
	s_nop 0
	v_cvt_pk_f16_f32 v70, v70, v71
	v_pk_fma_f32 v[72:73], v[74:75], s[34:35], v[72:73] op_sel_hi:[1,0,1]
	s_nop 0
	v_cvt_pk_f16_f32 v71, v72, v73
	v_cvt_f32_f16_e32 v72, v76
	v_cvt_f32_f16_sdwa v73, v76 dst_sel:DWORD dst_unused:UNUSED_PAD src0_sel:WORD_1
	v_pk_fma_f32 v[66:67], v[72:73], s[34:35], v[66:67] op_sel_hi:[1,0,1]
	s_nop 0
	v_cvt_pk_f16_f32 v72, v66, v67
	v_cvt_f32_f16_e32 v66, v77
	v_cvt_f32_f16_sdwa v67, v77 dst_sel:DWORD dst_unused:UNUSED_PAD src0_sel:WORD_1
	v_pk_fma_f32 v[66:67], v[66:67], s[34:35], v[68:69] op_sel_hi:[1,0,1]
	s_nop 0
	v_cvt_pk_f16_f32 v73, v66, v67
	global_store_dwordx4 v[82:83], v[70:73], off offset:256
	s_nop 1
	v_lshl_add_u64 v[70:71], v[140:141], 0, s[16:17]
	v_lshl_add_u64 v[72:73], s[94:95], 0, v[70:71]
	s_waitcnt vmcnt(15)
	v_mov_b64_e32 v[66:67], v[190:191]
	v_mov_b64_e32 v[68:69], v[192:193]
	v_cvt_f32_f16_e32 v74, v66
	v_cvt_f32_f16_sdwa v75, v66 dst_sel:DWORD dst_unused:UNUSED_PAD src0_sel:WORD_1
	v_cvt_f32_f16_e32 v66, v67
	v_cvt_f32_f16_sdwa v67, v67 dst_sel:DWORD dst_unused:UNUSED_PAD src0_sel:WORD_1
	v_pk_fma_f32 v[62:63], v[74:75], s[34:35], v[62:63] op_sel_hi:[1,0,1]
	s_nop 0
	v_cvt_pk_f16_f32 v62, v62, v63
	v_pk_fma_f32 v[64:65], v[66:67], s[34:35], v[64:65] op_sel_hi:[1,0,1]
	v_lshl_add_u64 v[66:67], s[4:5], 0, v[70:71]
	v_cvt_pk_f16_f32 v63, v64, v65
	v_cvt_f32_f16_e32 v64, v68
	v_cvt_f32_f16_sdwa v65, v68 dst_sel:DWORD dst_unused:UNUSED_PAD src0_sel:WORD_1
	v_pk_fma_f32 v[58:59], v[64:65], s[34:35], v[58:59] op_sel_hi:[1,0,1]
	s_nop 0
	v_cvt_pk_f16_f32 v64, v58, v59
	v_cvt_f32_f16_e32 v58, v69
	v_cvt_f32_f16_sdwa v59, v69 dst_sel:DWORD dst_unused:UNUSED_PAD src0_sel:WORD_1
	v_pk_fma_f32 v[58:59], v[58:59], s[34:35], v[60:61] op_sel_hi:[1,0,1]
	s_nop 0
	v_cvt_pk_f16_f32 v65, v58, v59
	s_nop 0
	global_store_dwordx4 v[66:67], v[62:65], off
	s_waitcnt vmcnt(15)
	v_mov_b64_e32 v[58:59], v[194:195]
	v_mov_b64_e32 v[60:61], v[196:197]
	s_nop 0
	v_cvt_f32_f16_e32 v62, v58
	v_cvt_f32_f16_sdwa v63, v58 dst_sel:DWORD dst_unused:UNUSED_PAD src0_sel:WORD_1
	v_cvt_f32_f16_e32 v58, v59
	v_cvt_f32_f16_sdwa v59, v59 dst_sel:DWORD dst_unused:UNUSED_PAD src0_sel:WORD_1
	v_pk_fma_f32 v[54:55], v[62:63], s[34:35], v[54:55] op_sel_hi:[1,0,1]
	s_nop 0
	v_cvt_pk_f16_f32 v54, v54, v55
	v_pk_fma_f32 v[56:57], v[58:59], s[34:35], v[56:57] op_sel_hi:[1,0,1]
	s_nop 0
	v_cvt_pk_f16_f32 v55, v56, v57
	v_cvt_f32_f16_e32 v56, v60
	v_cvt_f32_f16_sdwa v57, v60 dst_sel:DWORD dst_unused:UNUSED_PAD src0_sel:WORD_1
	v_pk_fma_f32 v[50:51], v[56:57], s[34:35], v[50:51] op_sel_hi:[1,0,1]
	s_nop 0
	v_cvt_pk_f16_f32 v56, v50, v51
	v_cvt_f32_f16_e32 v50, v61
	v_cvt_f32_f16_sdwa v51, v61 dst_sel:DWORD dst_unused:UNUSED_PAD src0_sel:WORD_1
	v_pk_fma_f32 v[50:51], v[50:51], s[34:35], v[52:53] op_sel_hi:[1,0,1]
	s_nop 0
	v_cvt_pk_f16_f32 v57, v50, v51
	global_store_dwordx4 v[66:67], v[54:57], off offset:256
	s_nop 1
	v_lshl_add_u64 v[54:55], v[140:141], 0, s[18:19]
	v_lshl_add_u64 v[56:57], s[94:95], 0, v[54:55]
	s_waitcnt vmcnt(15)
	v_mov_b64_e32 v[50:51], v[198:199]
	v_mov_b64_e32 v[52:53], v[200:201]
	v_cvt_f32_f16_e32 v58, v50
	v_cvt_f32_f16_sdwa v59, v50 dst_sel:DWORD dst_unused:UNUSED_PAD src0_sel:WORD_1
	v_cvt_f32_f16_e32 v50, v51
	v_cvt_f32_f16_sdwa v51, v51 dst_sel:DWORD dst_unused:UNUSED_PAD src0_sel:WORD_1
	v_pk_fma_f32 v[46:47], v[58:59], s[34:35], v[46:47] op_sel_hi:[1,0,1]
	s_nop 0
	v_cvt_pk_f16_f32 v46, v46, v47
	v_pk_fma_f32 v[48:49], v[50:51], s[34:35], v[48:49] op_sel_hi:[1,0,1]
	v_lshl_add_u64 v[50:51], s[4:5], 0, v[54:55]
	v_cvt_pk_f16_f32 v47, v48, v49
	v_cvt_f32_f16_e32 v48, v52
	v_cvt_f32_f16_sdwa v49, v52 dst_sel:DWORD dst_unused:UNUSED_PAD src0_sel:WORD_1
	v_pk_fma_f32 v[42:43], v[48:49], s[34:35], v[42:43] op_sel_hi:[1,0,1]
	s_nop 0
	v_cvt_pk_f16_f32 v48, v42, v43
	v_cvt_f32_f16_e32 v42, v53
	v_cvt_f32_f16_sdwa v43, v53 dst_sel:DWORD dst_unused:UNUSED_PAD src0_sel:WORD_1
	v_pk_fma_f32 v[42:43], v[42:43], s[34:35], v[44:45] op_sel_hi:[1,0,1]
	s_nop 0
	v_cvt_pk_f16_f32 v49, v42, v43
	s_nop 0
	global_store_dwordx4 v[50:51], v[46:49], off
	s_waitcnt vmcnt(15)
; #define PG8_WAIT_V(n) asm volatile("s_waitcnt vmcnt(" #n ")" ::: "memory")
; #define PG8_BAR __builtin_amdgcn_s_barrier()
; template <class Epi, class AMap>
; __device__ __forceinline__ void gemm_phase(LAS unsigned char* lds, const AMap am, const int lda, const h16* Bt, const int ldb, const int M, const int N, const int K, const Epi& E) {
;     ...
;         cur = nxt; cA = nA; cB = nB; ++ui;
;     }
;     PG8_WAIT_V(0);
;     if (wr == 0) PG8_BAR;
;     PG8_BAR;
;     __device__ __forceinline__ void operator()(const f32x4 (&acc)[2][2][4][2], const Unit& u, int wr, int wc, int fr, int fq) const {
;     ...
;             for (int m = 0; m < 4; ++m) { const size_t off = (size_t)(row0 + ai * 128 + m * 16) * DM + colt;
; #pragma unroll
;                 for (int bj = 0; bj < 2; ++bj) {
;                     const h16x8 x = *(const h16x8*)(X + off + bj * 128);
;                     f32x4 o0, o1;
; #pragma unroll
;                     for (int e = 0; e < 4; ++e) { o0[e] = (float)x[e] * ALPHA + acc[ai][bj][m][0][e]; o1[e] = (float)x[4 + e] * ALPHA + acc[ai][bj][m][1][e]; }
;                     *(u32x4*)(PRE + off + bj * 128) = pack8(o0, o1); } }
	v_mov_b64_e32 v[42:43], v[202:203]
	v_mov_b64_e32 v[44:45], v[204:205]
	s_nop 0
	v_cvt_f32_f16_e32 v46, v42
	v_cvt_f32_f16_sdwa v47, v42 dst_sel:DWORD dst_unused:UNUSED_PAD src0_sel:WORD_1
	v_cvt_f32_f16_e32 v42, v43
	v_cvt_f32_f16_sdwa v43, v43 dst_sel:DWORD dst_unused:UNUSED_PAD src0_sel:WORD_1
	v_pk_fma_f32 v[38:39], v[46:47], s[34:35], v[38:39] op_sel_hi:[1,0,1]
	s_nop 0
	v_cvt_pk_f16_f32 v38, v38, v39
	v_pk_fma_f32 v[40:41], v[42:43], s[34:35], v[40:41] op_sel_hi:[1,0,1]
	s_nop 0
	v_cvt_pk_f16_f32 v39, v40, v41
	v_cvt_f32_f16_e32 v40, v44
	v_cvt_f32_f16_sdwa v41, v44 dst_sel:DWORD dst_unused:UNUSED_PAD src0_sel:WORD_1
	v_pk_fma_f32 v[34:35], v[40:41], s[34:35], v[34:35] op_sel_hi:[1,0,1]
	s_nop 0
	v_cvt_pk_f16_f32 v40, v34, v35
	v_cvt_f32_f16_e32 v34, v45
	v_cvt_f32_f16_sdwa v35, v45 dst_sel:DWORD dst_unused:UNUSED_PAD src0_sel:WORD_1
	v_pk_fma_f32 v[34:35], v[34:35], s[34:35], v[36:37] op_sel_hi:[1,0,1]
	s_nop 0
	v_cvt_pk_f16_f32 v41, v34, v35
	global_store_dwordx4 v[50:51], v[38:41], off offset:256
	s_nop 1
	v_lshl_add_u64 v[38:39], v[140:141], 0, s[8:9]
	v_lshl_add_u64 v[40:41], s[94:95], 0, v[38:39]
	s_waitcnt vmcnt(15)
	v_mov_b64_e32 v[34:35], v[212:213]
	v_mov_b64_e32 v[36:37], v[214:215]
	v_cvt_f32_f16_e32 v42, v34
	v_cvt_f32_f16_sdwa v43, v34 dst_sel:DWORD dst_unused:UNUSED_PAD src0_sel:WORD_1
	v_cvt_f32_f16_e32 v34, v35
	v_cvt_f32_f16_sdwa v35, v35 dst_sel:DWORD dst_unused:UNUSED_PAD src0_sel:WORD_1
	v_pk_fma_f32 v[30:31], v[42:43], s[34:35], v[30:31] op_sel_hi:[1,0,1]
	s_nop 0
	v_cvt_pk_f16_f32 v30, v30, v31
	v_pk_fma_f32 v[32:33], v[34:35], s[34:35], v[32:33] op_sel_hi:[1,0,1]
	v_lshl_add_u64 v[34:35], s[4:5], 0, v[38:39]
	v_cvt_pk_f16_f32 v31, v32, v33
	v_cvt_f32_f16_e32 v32, v36
	v_cvt_f32_f16_sdwa v33, v36 dst_sel:DWORD dst_unused:UNUSED_PAD src0_sel:WORD_1
	v_pk_fma_f32 v[26:27], v[32:33], s[34:35], v[26:27] op_sel_hi:[1,0,1]
	s_nop 0
	v_cvt_pk_f16_f32 v32, v26, v27
	v_cvt_f32_f16_e32 v26, v37
	v_cvt_f32_f16_sdwa v27, v37 dst_sel:DWORD dst_unused:UNUSED_PAD src0_sel:WORD_1
	v_pk_fma_f32 v[26:27], v[26:27], s[34:35], v[28:29] op_sel_hi:[1,0,1]
	s_nop 0
	v_cvt_pk_f16_f32 v33, v26, v27
	s_nop 0
	global_store_dwordx4 v[34:35], v[30:33], off
	s_waitcnt vmcnt(15)
	v_mov_b64_e32 v[26:27], v[220:221]
	v_mov_b64_e32 v[28:29], v[222:223]
	s_nop 0
	v_cvt_f32_f16_e32 v30, v26
	v_cvt_f32_f16_sdwa v31, v26 dst_sel:DWORD dst_unused:UNUSED_PAD src0_sel:WORD_1
	v_cvt_f32_f16_e32 v26, v27
	v_cvt_f32_f16_sdwa v27, v27 dst_sel:DWORD dst_unused:UNUSED_PAD src0_sel:WORD_1
	v_pk_fma_f32 v[22:23], v[30:31], s[34:35], v[22:23] op_sel_hi:[1,0,1]
	s_nop 0
	v_cvt_pk_f16_f32 v22, v22, v23
	v_pk_fma_f32 v[24:25], v[26:27], s[34:35], v[24:25] op_sel_hi:[1,0,1]
	s_nop 0
	v_cvt_pk_f16_f32 v23, v24, v25
	v_cvt_f32_f16_e32 v24, v28
	v_cvt_f32_f16_sdwa v25, v28 dst_sel:DWORD dst_unused:UNUSED_PAD src0_sel:WORD_1
	v_pk_fma_f32 v[18:19], v[24:25], s[34:35], v[18:19] op_sel_hi:[1,0,1]
	s_nop 0
	v_cvt_pk_f16_f32 v24, v18, v19
	v_cvt_f32_f16_e32 v18, v29
	v_cvt_f32_f16_sdwa v19, v29 dst_sel:DWORD dst_unused:UNUSED_PAD src0_sel:WORD_1
	v_pk_fma_f32 v[18:19], v[18:19], s[34:35], v[20:21] op_sel_hi:[1,0,1]
	s_nop 0
	v_cvt_pk_f16_f32 v25, v18, v19
	global_store_dwordx4 v[34:35], v[22:25], off offset:256
	s_nop 1
	v_lshl_add_u64 v[22:23], v[140:141], 0, s[2:3]
	v_lshl_add_u64 v[24:25], s[94:95], 0, v[22:23]
	s_waitcnt vmcnt(15)
	v_mov_b64_e32 v[18:19], v[224:225]
	v_mov_b64_e32 v[20:21], v[226:227]
	v_cvt_f32_f16_e32 v26, v18
	v_cvt_f32_f16_sdwa v27, v18 dst_sel:DWORD dst_unused:UNUSED_PAD src0_sel:WORD_1
	v_cvt_f32_f16_e32 v18, v19
	v_cvt_f32_f16_sdwa v19, v19 dst_sel:DWORD dst_unused:UNUSED_PAD src0_sel:WORD_1
	v_pk_fma_f32 v[14:15], v[26:27], s[34:35], v[14:15] op_sel_hi:[1,0,1]
	s_nop 0
	v_cvt_pk_f16_f32 v14, v14, v15
	v_pk_fma_f32 v[16:17], v[18:19], s[34:35], v[16:17] op_sel_hi:[1,0,1]
	v_lshl_add_u64 v[18:19], s[4:5], 0, v[22:23]
	v_cvt_pk_f16_f32 v15, v16, v17
	v_cvt_f32_f16_e32 v16, v20
	v_cvt_f32_f16_sdwa v17, v20 dst_sel:DWORD dst_unused:UNUSED_PAD src0_sel:WORD_1
	v_pk_fma_f32 v[10:11], v[16:17], s[34:35], v[10:11] op_sel_hi:[1,0,1]
	s_nop 0
	v_cvt_pk_f16_f32 v16, v10, v11
	v_cvt_f32_f16_e32 v10, v21
	v_cvt_f32_f16_sdwa v11, v21 dst_sel:DWORD dst_unused:UNUSED_PAD src0_sel:WORD_1
	v_pk_fma_f32 v[10:11], v[10:11], s[34:35], v[12:13] op_sel_hi:[1,0,1]
	s_nop 0
	v_cvt_pk_f16_f32 v17, v10, v11
	s_nop 0
	global_store_dwordx4 v[18:19], v[14:17], off
	s_waitcnt vmcnt(15)
	v_mov_b64_e32 v[10:11], v[228:229]
	v_mov_b64_e32 v[12:13], v[230:231]
	s_nop 0
	v_cvt_f32_f16_e32 v14, v10
	v_cvt_f32_f16_sdwa v15, v10 dst_sel:DWORD dst_unused:UNUSED_PAD src0_sel:WORD_1
	v_cvt_f32_f16_e32 v10, v11
	v_cvt_f32_f16_sdwa v11, v11 dst_sel:DWORD dst_unused:UNUSED_PAD src0_sel:WORD_1
	v_pk_fma_f32 v[6:7], v[14:15], s[34:35], v[6:7] op_sel_hi:[1,0,1]
	s_nop 0
	v_cvt_pk_f16_f32 v6, v6, v7
	v_pk_fma_f32 v[8:9], v[10:11], s[34:35], v[8:9] op_sel_hi:[1,0,1]
	s_nop 0
	v_cvt_pk_f16_f32 v7, v8, v9
	v_cvt_f32_f16_e32 v8, v12
	v_cvt_f32_f16_sdwa v9, v12 dst_sel:DWORD dst_unused:UNUSED_PAD src0_sel:WORD_1
	v_pk_fma_f32 v[2:3], v[8:9], s[34:35], v[2:3] op_sel_hi:[1,0,1]
	s_nop 0
	v_cvt_pk_f16_f32 v8, v2, v3
	v_cvt_f32_f16_e32 v2, v13
	v_cvt_f32_f16_sdwa v3, v13 dst_sel:DWORD dst_unused:UNUSED_PAD src0_sel:WORD_1
	v_pk_fma_f32 v[2:3], v[2:3], s[34:35], v[4:5] op_sel_hi:[1,0,1]
	s_nop 0
	v_cvt_pk_f16_f32 v9, v2, v3
	s_mov_b32 s35, s0
	global_store_dwordx4 v[18:19], v[6:9], off offset:256
	s_cbranch_vccz .LBB0_140
	s_waitcnt vmcnt(0)
	s_cmpk_gt_u32 s62, 0xff
	s_cbranch_scc1 .LBB0_151
	s_barrier

; __device__ __forceinline__ int otid() { int t = (int)threadIdx.x; asm volatile("" : "+v"(t)); return t; }
; __device__ __forceinline__ int obid() { int t = (int)blockIdx.x; asm volatile("" : "+s"(t)); return t; }
; template <bool LN>
; __device__ __forceinline__ void ln_phase(const void* src, const float* g, const float* bt, float* xout, h16* xh, const float* mu, h16* mix) {
;     const int lane = otid() & 63, gw = obid() * 8 + (otid() >> 6), GW = gridDim.x * 8;
;     for (int ch = gw; ch < MTOK / 8; ch += GW) {
;         const size_t t0 = (size_t)ch * 8;
;         f32x4 prev[8], cur[8];
;         if (mix) {
;             if ((t0 & (SEQ - 1)) == 0) {
; #pragma unroll
;                 for (int i = 0; i < 8; ++i) prev[i] = (f32x4){0.f, 0.f, 0.f, 0.f};
;             } else ln_row<LN>(src, t0 - 1, lane, g, bt, prev);
;         }
;     ...
;                         const f32x4 m4 = ((const f32x4*)(mu + (size_t)k * DM))[i * 64 + lane];
;                         const f32x4 o4 = cur[i] + xx * m4;
;                         h16x4 o = {(h16)o4[0], (h16)o4[1], (h16)o4[2], (h16)o4[3]};
;                         ((h16x4*)(mix + ((size_t)k * MTOK + row) * DM))[i * 64 + lane] = o;
.LBB0_1008:
	v_mov_b32_e32 v0, v240
	s_mov_b32 s0, s29
	s_waitcnt vmcnt(0)
	v_mov_b32_e32 v2, v240
	s_lshl_b32 s22, s0, 3
	v_ashrrev_i32_e32 v2, 6, v2
	v_add_u32_e32 v68, s22, v2
	v_cmp_gt_i32_e32 vcc, s2, v68
	s_and_saveexec_b64 s[0:1], vcc
	s_movk_i32 s2, 0x7ff
	s_cbranch_execz .LBB0_1015
	v_and_b32_e32 v4, 63, v0
	v_lshlrev_b32_e32 v0, 4, v4
	v_lshl_add_u64 v[70:71], s[74:75], 0, v[0:1]
	s_mov_b64 s[4:5], 0x2400
	v_lshl_add_u64 v[82:83], v[70:71], 0, s[4:5]
	s_mov_b64 s[4:5], 0x4400
	v_lshl_add_u64 v[84:85], v[70:71], 0, s[4:5]
	s_mov_b64 s[4:5], 0x6400
	v_lshl_add_u64 v[86:87], v[70:71], 0, s[4:5]
	s_mov_b64 s[4:5], 0x8400
	v_lshl_add_u64 v[88:89], v[70:71], 0, s[4:5]
	s_mov_b64 s[4:5], 0xa400
	v_lshl_add_u64 v[90:91], v[70:71], 0, s[4:5]
	s_mov_b64 s[4:5], 0x2800
	v_lshl_add_u64 v[92:93], v[70:71], 0, s[4:5]
	s_mov_b64 s[4:5], 0x4800
	v_lshl_add_u64 v[94:95], v[70:71], 0, s[4:5]
	s_mov_b64 s[4:5], 0x6800
	v_lshl_add_u64 v[96:97], v[70:71], 0, s[4:5]
	s_mov_b64 s[4:5], 0x8800
	v_or_b32_e32 v6, 0x1000, v0
	v_mov_b32_e32 v7, v1
	v_lshl_add_u64 v[98:99], v[70:71], 0, s[4:5]
	s_mov_b64 s[4:5], 0xa800
	v_lshl_add_u64 v[108:109], s[74:75], 0, v[6:7]
	v_or_b32_e32 v6, 0x1400, v0
	v_lshl_add_u64 v[100:101], v[70:71], 0, s[4:5]
	s_mov_b64 s[4:5], 0x2c00
	v_lshl_add_u64 v[110:111], s[74:75], 0, v[6:7]
	v_or_b32_e32 v6, 0x1800, v0
	v_lshl_add_u64 v[102:103], v[70:71], 0, s[4:5]
	s_mov_b64 s[4:5], 0x4c00
	v_lshl_add_u64 v[112:113], s[74:75], 0, v[6:7]
	v_or_b32_e32 v6, 0x1c00, v0
	v_ashrrev_i32_e32 v3, 31, v2
	s_ashr_i32 s23, s22, 31
	v_lshl_add_u64 v[104:105], v[70:71], 0, s[4:5]
	s_mov_b64 s[4:5], 0x6c00
	v_lshl_add_u64 v[114:115], s[74:75], 0, v[6:7]
	v_lshlrev_b64 v[6:7], 15, v[2:3]
	v_lshl_add_u64 v[2:3], v[2:3], 0, s[22:23]
	v_lshl_add_u64 v[106:107], v[70:71], 0, s[4:5]
	v_lshlrev_b64 v[2:3], 16, v[2:3]
	v_readlane_b32 s4, v254, 9
	s_lshl_b64 s[20:21], s[22:23], 15
	v_or_b32_e32 v2, v2, v0
	v_readlane_b32 s5, v254, 10
	v_lshl_add_u64 v[6:7], v[6:7], 0, s[20:21]
	s_mov_b64 s[6:7], 0x4000
	v_lshl_add_u64 v[118:119], s[4:5], 0, v[2:3]
	s_mov_b64 s[4:5], 0x8c00
	s_mov_b64 s[18:19], 0x6000
	s_mov_b64 s[26:27], 0x8000
	s_mov_b64 s[38:39], 0xa000
	v_lshl_or_b32 v6, v4, 3, v6
	v_lshl_add_u64 v[122:123], v[70:71], 0, s[4:5]
	s_mov_b64 s[4:5], 0xac00
	v_lshl_add_u64 v[72:73], v[70:71], 0, s[90:91]
	v_lshl_add_u64 v[74:75], v[70:71], 0, s[6:7]
	v_lshl_add_u64 v[76:77], v[70:71], 0, s[18:19]
	v_lshl_add_u64 v[78:79], v[70:71], 0, s[26:27]
	v_lshl_add_u64 v[80:81], v[70:71], 0, s[38:39]
	v_lshl_add_u64 v[116:117], s[84:85], 0, v[6:7]
	s_mov_b64 s[22:23], 0
	v_lshlrev_b32_e32 v120, 4, v4
	v_lshl_add_u64 v[124:125], v[70:71], 0, s[4:5]
	v_lshl_add_u64 v[126:127], v[108:109], 0, s[90:91]
	v_lshl_add_u64 v[128:129], v[108:109], 0, s[6:7]
	v_lshl_add_u64 v[130:131], v[108:109], 0, s[18:19]
	v_lshl_add_u64 v[132:133], v[108:109], 0, s[26:27]
	v_lshl_add_u64 v[134:135], v[108:109], 0, s[38:39]
	v_lshl_add_u64 v[136:137], v[110:111], 0, s[90:91]
	v_lshl_add_u64 v[138:139], v[110:111], 0, s[6:7]
	v_lshl_add_u64 v[140:141], v[110:111], 0, s[18:19]
	v_lshl_add_u64 v[142:143], v[110:111], 0, s[26:27]
	v_lshl_add_u64 v[144:145], v[110:111], 0, s[38:39]
	v_lshl_add_u64 v[146:147], v[112:113], 0, s[90:91]
	v_lshl_add_u64 v[148:149], v[112:113], 0, s[6:7]
	v_lshl_add_u64 v[150:151], v[112:113], 0, s[18:19]
	v_lshl_add_u64 v[152:153], v[112:113], 0, s[26:27]
	v_lshl_add_u64 v[154:155], v[112:113], 0, s[38:39]
	v_lshl_add_u64 v[156:157], v[114:115], 0, s[90:91]
	v_lshl_add_u64 v[158:159], v[114:115], 0, s[6:7]
	v_lshl_add_u64 v[160:161], v[114:115], 0, s[18:19]
	s_mov_b64 s[18:19], 0x90000
	s_mov_b64 s[16:17], 0x80000
	v_lshl_add_u64 v[162:163], v[114:115], 0, s[26:27]
	v_lshl_add_u64 v[164:165], v[114:115], 0, s[38:39]
	v_and_b32_e32 v230, 63, v240
	v_lshrrev_b32_e32 v232, 6, v240
	v_lshlrev_b32_e32 v230, 4, v230
	v_readfirstlane_b32 s100, v232
	s_mov_b32 s101, 0
	s_nop 3
	s_lshl_b32 s100, s100, 10
	v_or_b32_e32 v232, v70, v71
	s_nop 0
	v_readfirstlane_b32 s101, v232
	s_nop 3
	s_cmp_eq_u32 s101, 0
	s_mov_b32 s101, 0
	s_cbranch_scc1 .Lmix_nostage_b
	s_mul_i32 s100, s100, 6
	v_lshl_add_u64 v[232:233], v[70:71], 0, s[100:101]
	s_mov_b32 m0, s100
	s_nop 0
	global_load_lds_dwordx4 v[232:233], off
	global_load_lds_dwordx4 v[232:233], off offset:1024
	global_load_lds_dwordx4 v[232:233], off offset:2048
	global_load_lds_dwordx4 v[232:233], off offset:3072
	s_add_i32 s100, s100, 0x1000
	v_lshl_add_u64 v[232:233], v[70:71], 0, s[100:101]
	s_mov_b32 m0, s100
	s_nop 0
	global_load_lds_dwordx4 v[232:233], off
	global_load_lds_dwordx4 v[232:233], off offset:1024
.Lmix_nostage_b:
	s_waitcnt vmcnt(0)
	s_barrier
